# attention epilogue: the 7 vmcnt(1) waits that guarded the per-iteration gate loads are no longer needed (loads hoisted): replaced by same-size s_nop; on top of v35
# speedup vs baseline: 1.0093x; 1.0093x over previous
; __device__ __forceinline__ int crow(int r, int hi) { return (r & 3) + 8 * (r >> 2) + 4 * hi; }
; __device__ __forceinline__ unsigned short f2bf(float f) { unsigned u = __float_as_uint(f); return (unsigned short)((u + 0x7fffu + ((u >> 16) & 1u)) >> 16); }
; __device__ __forceinline__ unsigned f2bf(float f) { return pk2(f, 0.f) & 0xffffu; }
; __device__ __forceinline__ void attn_unit(const bf16* __restrict__ P, unsigned short* __restrict__ Ob, int b, int h, int kvh, int qb, bool meta, int jt0, int ntl, float* part, unsigned* cnt, const float* __restrict__ qnw, const float2* __restrict__ rtab, char* lds) {
;     ...
;     if (hi == 0) li_l[r32] = l_reg; asm volatile("s_waitcnt lgkmcnt(0)" ::: "memory");
;     float rli[16];
; #pragma unroll
;     for (int r = 0; r < 16; ++r) rli[r] = __builtin_amdgcn_rcpf(li_l[crow(r, hi)]);
;     char* stg = lds + 2 * SHM_V + 2 * SHM_K + NW * 64 * 4 + wid * (32 * 272);
; #pragma unroll
;     for (int r = 0; r < 16; ++r) { const int orow = crow(r, hi);
; #pragma unroll
;       for (int d0 = 0; d0 < 4; ++d0) *(unsigned short*)(stg + orow * 272 + (d0 * 32 + r32) * 2) = f2bf(o[d0][r] * rli[r]); }
.LBB0_270:
	s_or_b64 exec, exec, s[0:1]
	s_waitcnt lgkmcnt(0)
	v_add_u32_e32 v72, v195, v180
	ds_read_b128 v[64:67], v72
	ds_read_b128 v[68:71], v72 offset:32
	s_movk_i32 s0, 0x2200
	v_lshlrev_b32_e32 v81, 1, v193
	v_mul_u32_u24_e32 v82, 0x440, v194
	s_waitcnt lgkmcnt(1)
	v_rcp_f32_e32 v73, v64
	v_rcp_f32_e32 v74, v65
	v_rcp_f32_e32 v75, v66
	v_rcp_f32_e32 v76, v67
	s_waitcnt lgkmcnt(0)
	v_rcp_f32_e32 v77, v68
	ds_read_b128 v[64:67], v72 offset:64
	v_rcp_f32_e32 v78, v69
	v_rcp_f32_e32 v79, v70
	v_rcp_f32_e32 v80, v71
	ds_read_b128 v[68:71], v72 offset:96
	v_mul_lo_u32 v72, v192, s0
	v_add_u32_e32 v72, s82, v72
	v_mul_f32_e32 v0, v0, v73
	v_add3_u32 v81, v72, v81, v82
	v_bfe_u32 v82, v0, 16, 1
	v_add3_u32 v0, v0, v82, s80
	ds_write_b16_d16_hi v81, v0
	v_mul_f32_e32 v0, v48, v73
	v_bfe_u32 v48, v0, 16, 1
	v_add3_u32 v0, v0, v48, s80
	ds_write_b16_d16_hi v81, v0 offset:64
	v_mul_f32_e32 v0, v32, v73
	v_bfe_u32 v32, v0, 16, 1
	v_add3_u32 v0, v0, v32, s80
	ds_write_b16_d16_hi v81, v0 offset:128
	v_mul_f32_e32 v0, v16, v73
	v_bfe_u32 v16, v0, 16, 1
	v_add3_u32 v0, v0, v16, s80
	ds_write_b16_d16_hi v81, v0 offset:192
	v_mul_f32_e32 v0, v1, v74
	v_bfe_u32 v1, v0, 16, 1
	v_add3_u32 v0, v0, v1, s80
	ds_write_b16_d16_hi v81, v0 offset:272
	v_mul_f32_e32 v0, v49, v74
	v_bfe_u32 v1, v0, 16, 1
	v_add3_u32 v0, v0, v1, s80
	ds_write_b16_d16_hi v81, v0 offset:336
	v_mul_f32_e32 v0, v33, v74
	v_bfe_u32 v1, v0, 16, 1
	v_add3_u32 v0, v0, v1, s80
	ds_write_b16_d16_hi v81, v0 offset:400
	v_mul_f32_e32 v0, v17, v74
	v_bfe_u32 v1, v0, 16, 1
	v_add3_u32 v0, v0, v1, s80
	ds_write_b16_d16_hi v81, v0 offset:464
	v_mul_f32_e32 v0, v2, v75
	v_bfe_u32 v1, v0, 16, 1
	v_add3_u32 v0, v0, v1, s80
	ds_write_b16_d16_hi v81, v0 offset:544
	v_mul_f32_e32 v0, v50, v75
	v_bfe_u32 v1, v0, 16, 1
	v_add3_u32 v0, v0, v1, s80
	ds_write_b16_d16_hi v81, v0 offset:608
	v_mul_f32_e32 v0, v34, v75
	v_bfe_u32 v1, v0, 16, 1
	v_add3_u32 v0, v0, v1, s80
	ds_write_b16_d16_hi v81, v0 offset:672
	v_mul_f32_e32 v0, v18, v75
	v_bfe_u32 v1, v0, 16, 1
	v_add3_u32 v0, v0, v1, s80
	ds_write_b16_d16_hi v81, v0 offset:736
	v_mul_f32_e32 v0, v3, v76
	v_bfe_u32 v1, v0, 16, 1
	v_add3_u32 v0, v0, v1, s80
	ds_write_b16_d16_hi v81, v0 offset:816
	v_mul_f32_e32 v0, v51, v76
	v_bfe_u32 v1, v0, 16, 1
	v_add3_u32 v0, v0, v1, s80
	ds_write_b16_d16_hi v81, v0 offset:880
	v_mul_f32_e32 v0, v35, v76
	v_bfe_u32 v1, v0, 16, 1
	v_add3_u32 v0, v0, v1, s80
	ds_write_b16_d16_hi v81, v0 offset:944
	v_mul_f32_e32 v0, v19, v76
	v_bfe_u32 v1, v0, 16, 1
	v_add3_u32 v0, v0, v1, s80
	ds_write_b16_d16_hi v81, v0 offset:1008
	v_mul_f32_e32 v0, v4, v77
	v_bfe_u32 v1, v0, 16, 1
	v_add3_u32 v0, v0, v1, s80
	ds_write_b16_d16_hi v81, v0 offset:2176
	v_mul_f32_e32 v0, v52, v77
	v_bfe_u32 v1, v0, 16, 1
	v_add3_u32 v0, v0, v1, s80
	ds_write_b16_d16_hi v81, v0 offset:2240
	v_mul_f32_e32 v0, v36, v77
	v_bfe_u32 v1, v0, 16, 1
	v_add3_u32 v0, v0, v1, s80
	ds_write_b16_d16_hi v81, v0 offset:2304
	v_mul_f32_e32 v0, v20, v77
	v_bfe_u32 v1, v0, 16, 1
	v_add3_u32 v0, v0, v1, s80
	ds_write_b16_d16_hi v81, v0 offset:2368
	v_mul_f32_e32 v0, v5, v78
	v_bfe_u32 v1, v0, 16, 1
	v_add3_u32 v0, v0, v1, s80
	ds_write_b16_d16_hi v81, v0 offset:2448
	v_mul_f32_e32 v0, v53, v78
	v_bfe_u32 v1, v0, 16, 1
	v_add3_u32 v0, v0, v1, s80
	ds_write_b16_d16_hi v81, v0 offset:2512
	v_mul_f32_e32 v0, v37, v78
	v_bfe_u32 v1, v0, 16, 1
	v_add3_u32 v0, v0, v1, s80
	ds_write_b16_d16_hi v81, v0 offset:2576
	v_mul_f32_e32 v0, v21, v78
	v_bfe_u32 v1, v0, 16, 1
	v_add3_u32 v0, v0, v1, s80
	ds_write_b16_d16_hi v81, v0 offset:2640
	v_mul_f32_e32 v0, v6, v79
	v_bfe_u32 v1, v0, 16, 1
	v_add3_u32 v0, v0, v1, s80
	ds_write_b16_d16_hi v81, v0 offset:2720
	v_mul_f32_e32 v0, v54, v79
	v_bfe_u32 v1, v0, 16, 1
	v_add3_u32 v0, v0, v1, s80
	ds_write_b16_d16_hi v81, v0 offset:2784
	v_mul_f32_e32 v0, v38, v79
	v_bfe_u32 v1, v0, 16, 1
	v_add3_u32 v0, v0, v1, s80
	ds_write_b16_d16_hi v81, v0 offset:2848
	v_mul_f32_e32 v0, v22, v79
	v_bfe_u32 v1, v0, 16, 1
	v_add3_u32 v0, v0, v1, s80
	ds_write_b16_d16_hi v81, v0 offset:2912
	v_mul_f32_e32 v0, v7, v80
	v_bfe_u32 v1, v0, 16, 1
	v_add3_u32 v0, v0, v1, s80
	ds_write_b16_d16_hi v81, v0 offset:2992
	v_mul_f32_e32 v0, v55, v80
	v_bfe_u32 v1, v0, 16, 1
	v_add3_u32 v0, v0, v1, s80
	ds_write_b16_d16_hi v81, v0 offset:3056
	v_mul_f32_e32 v0, v39, v80
	v_bfe_u32 v1, v0, 16, 1
	s_waitcnt lgkmcnt(14)
; __device__ __forceinline__ int crow(int r, int hi) { return (r & 3) + 8 * (r >> 2) + 4 * hi; }
; __device__ __forceinline__ unsigned short f2bf(float f) { unsigned u = __float_as_uint(f); return (unsigned short)((u + 0x7fffu + ((u >> 16) & 1u)) >> 16); }
; __device__ __forceinline__ unsigned f2bf(float f) { return pk2(f, 0.f) & 0xffffu; }
; __device__ __forceinline__ void attn_unit(const bf16* __restrict__ P, unsigned short* __restrict__ Ob, int b, int h, int kvh, int qb, bool meta, int jt0, int ntl, float* part, unsigned* cnt, const float* __restrict__ qnw, const float2* __restrict__ rtab, char* lds) {
;     ...
;     for (int r = 0; r < 16; ++r) { const int orow = crow(r, hi);
; #pragma unroll
;       for (int d0 = 0; d0 < 4; ++d0) *(unsigned short*)(stg + orow * 272 + (d0 * 32 + r32) * 2) = f2bf(o[d0][r] * rli[r]); }
;     asm volatile("s_waitcnt lgkmcnt(0)" ::: "memory");
;     const long grow0 = (long)b * 4096 + qb * 256 + wid * QBLK;
; #pragma unroll
;     for (int i = 0; i < 8; ++i) { const int cidx = lane + 64 * i, orow = cidx >> 4, c8 = (cidx & 15) * 8;
;       const u32x4 ov = *(const u32x4*)(stg + orow * 272 + c8 * 2);
;       const u32x4 gv = *(const u32x4*)(Pg + (grow0 + orow) * LD + 4096 + h * D + c8);
	v_rcp_f32_e32 v64, v64
	v_add3_u32 v0, v0, v1, s80
	ds_write_b16_d16_hi v81, v0 offset:3120
	v_mul_f32_e32 v0, v23, v80
	v_bfe_u32 v1, v0, 16, 1
	v_add3_u32 v0, v0, v1, s80
	ds_write_b16_d16_hi v81, v0 offset:3184
	v_mul_f32_e32 v0, v8, v64
	v_bfe_u32 v1, v0, 16, 1
	v_add3_u32 v0, v0, v1, s80
	ds_write_b16_d16_hi v81, v0 offset:4352
	v_mul_f32_e32 v0, v56, v64
	v_bfe_u32 v1, v0, 16, 1
	v_add3_u32 v0, v0, v1, s80
	ds_write_b16_d16_hi v81, v0 offset:4416
	v_mul_f32_e32 v0, v40, v64
	v_bfe_u32 v1, v0, 16, 1
	v_rcp_f32_e32 v65, v65
	v_add3_u32 v0, v0, v1, s80
	ds_write_b16_d16_hi v81, v0 offset:4480
	v_mul_f32_e32 v0, v24, v64
	v_bfe_u32 v1, v0, 16, 1
	v_add3_u32 v0, v0, v1, s80
	ds_write_b16_d16_hi v81, v0 offset:4544
	v_mul_f32_e32 v0, v9, v65
	v_bfe_u32 v1, v0, 16, 1
	v_add3_u32 v0, v0, v1, s80
	ds_write_b16_d16_hi v81, v0 offset:4624
	v_mul_f32_e32 v0, v57, v65
	v_bfe_u32 v1, v0, 16, 1
	v_add3_u32 v0, v0, v1, s80
	ds_write_b16_d16_hi v81, v0 offset:4688
	v_mul_f32_e32 v0, v41, v65
	v_bfe_u32 v1, v0, 16, 1
	v_rcp_f32_e32 v66, v66
	v_add3_u32 v0, v0, v1, s80
	ds_write_b16_d16_hi v81, v0 offset:4752
	v_mul_f32_e32 v0, v25, v65
	v_bfe_u32 v1, v0, 16, 1
	v_add3_u32 v0, v0, v1, s80
	ds_write_b16_d16_hi v81, v0 offset:4816
	v_mul_f32_e32 v0, v10, v66
	v_bfe_u32 v1, v0, 16, 1
	v_add3_u32 v0, v0, v1, s80
	ds_write_b16_d16_hi v81, v0 offset:4896
	v_mul_f32_e32 v0, v58, v66
	v_bfe_u32 v1, v0, 16, 1
	v_add3_u32 v0, v0, v1, s80
	ds_write_b16_d16_hi v81, v0 offset:4960
	v_mul_f32_e32 v0, v42, v66
	v_bfe_u32 v1, v0, 16, 1
	v_rcp_f32_e32 v67, v67
	v_add3_u32 v0, v0, v1, s80
	ds_write_b16_d16_hi v81, v0 offset:5024
	v_mul_f32_e32 v0, v26, v66
	v_bfe_u32 v1, v0, 16, 1
	v_add3_u32 v0, v0, v1, s80
	ds_write_b16_d16_hi v81, v0 offset:5088
	v_mul_f32_e32 v0, v11, v67
	v_bfe_u32 v1, v0, 16, 1
	v_add3_u32 v0, v0, v1, s80
	ds_write_b16_d16_hi v81, v0 offset:5168
	v_mul_f32_e32 v0, v59, v67
	v_bfe_u32 v1, v0, 16, 1
	v_add3_u32 v0, v0, v1, s80
	ds_write_b16_d16_hi v81, v0 offset:5232
	v_mul_f32_e32 v0, v43, v67
	v_bfe_u32 v1, v0, 16, 1
	v_rcp_f32_e32 v68, v68
	v_add3_u32 v0, v0, v1, s80
	ds_write_b16_d16_hi v81, v0 offset:5296
	v_mul_f32_e32 v0, v27, v67
	v_bfe_u32 v1, v0, 16, 1
	v_add3_u32 v0, v0, v1, s80
	ds_write_b16_d16_hi v81, v0 offset:5360
	v_mul_f32_e32 v0, v12, v68
	v_bfe_u32 v1, v0, 16, 1
	v_add3_u32 v0, v0, v1, s80
	ds_write_b16_d16_hi v81, v0 offset:6528
	v_mul_f32_e32 v0, v60, v68
	v_bfe_u32 v1, v0, 16, 1
	v_add3_u32 v0, v0, v1, s80
	ds_write_b16_d16_hi v81, v0 offset:6592
	v_mul_f32_e32 v0, v44, v68
	v_bfe_u32 v1, v0, 16, 1
	v_rcp_f32_e32 v69, v69
	v_add3_u32 v0, v0, v1, s80
	ds_write_b16_d16_hi v81, v0 offset:6656
	v_mul_f32_e32 v0, v28, v68
	v_bfe_u32 v1, v0, 16, 1
	v_add3_u32 v0, v0, v1, s80
	ds_write_b16_d16_hi v81, v0 offset:6720
	v_mul_f32_e32 v0, v13, v69
	v_bfe_u32 v1, v0, 16, 1
	v_add3_u32 v0, v0, v1, s80
	ds_write_b16_d16_hi v81, v0 offset:6800
	v_mul_f32_e32 v0, v61, v69
	v_bfe_u32 v1, v0, 16, 1
	v_add3_u32 v0, v0, v1, s80
	ds_write_b16_d16_hi v81, v0 offset:6864
	v_mul_f32_e32 v0, v45, v69
	v_bfe_u32 v1, v0, 16, 1
	v_rcp_f32_e32 v70, v70
	v_add3_u32 v0, v0, v1, s80
	ds_write_b16_d16_hi v81, v0 offset:6928
	v_mul_f32_e32 v0, v29, v69
	v_bfe_u32 v1, v0, 16, 1
	v_add3_u32 v0, v0, v1, s80
	ds_write_b16_d16_hi v81, v0 offset:6992
	v_mul_f32_e32 v0, v14, v70
	v_bfe_u32 v1, v0, 16, 1
	v_add3_u32 v0, v0, v1, s80
	ds_write_b16_d16_hi v81, v0 offset:7072
	v_mul_f32_e32 v0, v62, v70
	v_bfe_u32 v1, v0, 16, 1
	v_add3_u32 v0, v0, v1, s80
	ds_write_b16_d16_hi v81, v0 offset:7136
	v_mul_f32_e32 v0, v46, v70
	v_bfe_u32 v1, v0, 16, 1
	v_rcp_f32_e32 v71, v71
	v_add3_u32 v0, v0, v1, s80
	ds_write_b16_d16_hi v81, v0 offset:7200
	v_mul_f32_e32 v0, v30, v70
	v_bfe_u32 v1, v0, 16, 1
	v_add3_u32 v0, v0, v1, s80
	ds_write_b16_d16_hi v81, v0 offset:7264
	v_mul_f32_e32 v0, v15, v71
	v_bfe_u32 v1, v0, 16, 1
	v_add3_u32 v0, v0, v1, s80
	ds_write_b16_d16_hi v81, v0 offset:7344
	v_mul_f32_e32 v0, v63, v71
	v_bfe_u32 v1, v0, 16, 1
	v_add3_u32 v0, v0, v1, s80
	ds_write_b16_d16_hi v81, v0 offset:7408
	v_mul_f32_e32 v0, v47, v71
	v_bfe_u32 v1, v0, 16, 1
	v_add3_u32 v0, v0, v1, s80
	ds_write_b16_d16_hi v81, v0 offset:7472
	v_mul_f32_e32 v0, v31, v71
	v_bfe_u32 v1, v0, 16, 1
	v_add3_u32 v0, v0, v1, s80
	ds_write_b16_d16_hi v81, v0 offset:7536
	v_lshl_add_u64 v[0:1], s[34:35], 0, v[178:179]
	v_lshrrev_b32_e32 v8, 4, v181
	v_or_b32_e32 v0, v8, v0
	v_mov_b64_e32 v[2:3], s[6:7]
	v_mad_u64_u32 v[4:5], s[0:1], v0, s44, v[2:3]
	v_mul_lo_u32 v13, v1, s44
	s_lshl_b32 s8, s36, 1
	v_add_u32_e32 v5, v13, v5
	v_lshl_add_u64 v[4:5], v[4:5], 0, s[8:9]
	v_lshl_add_u64 v[4:5], v[4:5], 0, v[176:177]
	v_add_co_u32_e32 v4, vcc, s50, v4
	s_waitcnt lgkmcnt(0)
	v_mul_u32_u24_e32 v8, 0x110, v8
	s_nop 0
	v_addc_co_u32_e32 v5, vcc, 0, v5, vcc
	s_mov_b32 s99, 0
	s_mov_b32 s98, 0xc000
	v_lshl_add_u64 v[128:129], v[4:5], 0, s[98:99]
	global_load_dwordx4 v[100:103], v[128:129], off
	s_mov_b32 s98, 0x18000
	v_lshl_add_u64 v[128:129], v[4:5], 0, s[98:99]
	global_load_dwordx4 v[104:107], v[128:129], off
	s_mov_b32 s98, 0x24000
	v_lshl_add_u64 v[128:129], v[4:5], 0, s[98:99]
	global_load_dwordx4 v[108:111], v[128:129], off
	s_mov_b32 s98, 0x30000
	v_lshl_add_u64 v[128:129], v[4:5], 0, s[98:99]
	global_load_dwordx4 v[112:115], v[128:129], off
	s_mov_b32 s98, 0x3c000
	v_lshl_add_u64 v[128:129], v[4:5], 0, s[98:99]
	global_load_dwordx4 v[116:119], v[128:129], off
	s_mov_b32 s98, 0x48000
	v_lshl_add_u64 v[128:129], v[4:5], 0, s[98:99]
	global_load_dwordx4 v[120:123], v[128:129], off
	s_mov_b32 s98, 0x54000
	v_lshl_add_u64 v[128:129], v[4:5], 0, s[98:99]
	global_load_dwordx4 v[124:127], v[128:129], off
	global_load_dwordx4 v[4:7], v[4:5], off
	v_add3_u32 v12, v72, v176, v8
	s_waitcnt vmcnt(0)
; __device__ __forceinline__ void attn_unit(const bf16* __restrict__ P, unsigned short* __restrict__ Ob, int b, int h, int kvh, int qb, bool meta, int jt0, int ntl, float* part, unsigned* cnt, const float* __restrict__ qnw, const float2* __restrict__ rtab, char* lds) {
;     ...
;     for (int i = 0; i < 8; ++i) { const int cidx = lane + 64 * i, orow = cidx >> 4, c8 = (cidx & 15) * 8;
;       const u32x4 ov = *(const u32x4*)(stg + orow * 272 + c8 * 2);
;       const u32x4 gv = *(const u32x4*)(Pg + (grow0 + orow) * LD + 4096 + h * D + c8);
;       const unsigned ow[4] = {ov.x, ov.y, ov.z, ov.w}, gw[4] = {gv.x, gv.y, gv.z, gv.w}; unsigned res[4];
; #pragma unroll
;       for (int e = 0; e < 4; ++e) { const float o0 = __uint_as_float(ow[e] << 16), o1 = __uint_as_float(ow[e] & 0xffff0000u), g0 = __uint_as_float(gw[e] << 16), g1 = __uint_as_float(gw[e] & 0xffff0000u);
;         res[e] = cvtpk(o0 * (g0 / (1.f + __expf(-g0))), o1 * (g1 / (1.f + __expf(-g1)))); }
;       *(u32x4*)(Ob + (grow0 + orow) * 2048 + h * D + c8) = (u32x4){res[0], res[1], res[2], res[3]}; }
	v_lshlrev_b32_e32 v14, 16, v4
	v_mul_f32_e32 v9, 0xbfb8aa3b, v14
	v_exp_f32_e32 v15, v9
	v_and_b32_e32 v4, 0xffff0000, v4
	v_mul_f32_e32 v21, 0xbfb8aa3b, v4
	v_exp_f32_e32 v21, v21
	v_add_f32_e32 v15, 1.0, v15
	v_div_scale_f32 v16, s[0:1], v15, v15, v14
	v_rcp_f32_e32 v17, v16
	ds_read_b128 v[8:11], v12
	v_fma_f32 v19, -v16, v17, 1.0
	v_fmac_f32_e32 v17, v19, v17
	v_div_scale_f32 v19, vcc, v14, v15, v14
	v_mul_f32_e32 v20, v19, v17
	v_fma_f32 v22, -v16, v20, v19
	v_fmac_f32_e32 v20, v22, v17
	v_fma_f32 v16, -v16, v20, v19
	v_add_f32_e32 v19, 1.0, v21
	v_div_scale_f32 v21, s[0:1], v19, v19, v4
	v_rcp_f32_e32 v22, v21
	v_div_fmas_f32 v16, v16, v17, v20
	v_div_fixup_f32 v14, v16, v15, v14
	s_waitcnt lgkmcnt(0)
	v_lshlrev_b32_e32 v18, 16, v8
	v_fma_f32 v15, -v21, v22, 1.0
	v_fmac_f32_e32 v22, v15, v22
	v_div_scale_f32 v15, vcc, v4, v19, v4
	v_mul_f32_e32 v16, v15, v22
	v_fma_f32 v17, -v21, v16, v15
	v_fmac_f32_e32 v16, v17, v22
	v_fma_f32 v15, -v21, v16, v15
	v_div_fmas_f32 v15, v15, v22, v16
	v_lshlrev_b32_e32 v16, 16, v5
	v_mul_f32_e32 v17, 0xbfb8aa3b, v16
	v_exp_f32_e32 v17, v17
	v_and_b32_e32 v8, 0xffff0000, v8
	v_div_fixup_f32 v4, v15, v19, v4
	v_mul_f32_e32 v4, v4, v8
	v_mul_f32_e32 v14, v14, v18
	v_cvt_pk_bf16_f32 v8, v14, v4
	v_add_f32_e32 v4, 1.0, v17
	v_div_scale_f32 v14, s[0:1], v4, v4, v16
	v_rcp_f32_e32 v15, v14
	v_and_b32_e32 v5, 0xffff0000, v5
	v_mul_f32_e32 v20, 0xbfb8aa3b, v5
	v_exp_f32_e32 v20, v20
	v_fma_f32 v18, -v14, v15, 1.0
	v_fmac_f32_e32 v15, v18, v15
	v_div_scale_f32 v18, vcc, v16, v4, v16
	v_mul_f32_e32 v19, v18, v15
	v_fma_f32 v21, -v14, v19, v18
	v_fmac_f32_e32 v19, v21, v15
	v_fma_f32 v14, -v14, v19, v18
	v_add_f32_e32 v18, 1.0, v20
	v_div_scale_f32 v20, s[0:1], v18, v18, v5
	v_rcp_f32_e32 v21, v20
	v_div_fmas_f32 v14, v14, v15, v19
	v_div_fixup_f32 v4, v14, v4, v16
	v_lshlrev_b32_e32 v17, 16, v9
	v_fma_f32 v14, -v20, v21, 1.0
	v_fmac_f32_e32 v21, v14, v21
	v_div_scale_f32 v14, vcc, v5, v18, v5
	v_mul_f32_e32 v15, v14, v21
	v_fma_f32 v16, -v20, v15, v14
	v_fmac_f32_e32 v15, v16, v21
	v_fma_f32 v14, -v20, v15, v14
	v_div_fmas_f32 v14, v14, v21, v15
	v_lshlrev_b32_e32 v15, 16, v6
	v_mul_f32_e32 v16, 0xbfb8aa3b, v15
	v_exp_f32_e32 v16, v16
	v_and_b32_e32 v9, 0xffff0000, v9
	v_mul_f32_e32 v4, v4, v17
	v_div_fixup_f32 v5, v14, v18, v5
	v_mul_f32_e32 v5, v5, v9
	v_cvt_pk_bf16_f32 v9, v4, v5
	v_add_f32_e32 v4, 1.0, v16
	v_div_scale_f32 v5, s[0:1], v4, v4, v15
	v_rcp_f32_e32 v14, v5
	v_and_b32_e32 v6, 0xffff0000, v6
	v_mul_f32_e32 v19, 0xbfb8aa3b, v6
	v_exp_f32_e32 v19, v19
	v_fma_f32 v17, -v5, v14, 1.0
	v_fmac_f32_e32 v14, v17, v14
	v_div_scale_f32 v17, vcc, v15, v4, v15
	v_mul_f32_e32 v18, v17, v14
	v_fma_f32 v20, -v5, v18, v17
	v_fmac_f32_e32 v18, v20, v14
	v_fma_f32 v5, -v5, v18, v17
	v_add_f32_e32 v17, 1.0, v19
	v_div_scale_f32 v19, s[0:1], v17, v17, v6
	v_rcp_f32_e32 v20, v19
	v_div_fmas_f32 v5, v5, v14, v18
	v_div_fixup_f32 v4, v5, v4, v15
	v_lshlrev_b32_e32 v16, 16, v10
	v_fma_f32 v5, -v19, v20, 1.0
	v_fmac_f32_e32 v20, v5, v20
	v_div_scale_f32 v5, vcc, v6, v17, v6
	v_mul_f32_e32 v14, v5, v20
	v_fma_f32 v15, -v19, v14, v5
	v_fmac_f32_e32 v14, v15, v20
	v_fma_f32 v5, -v19, v14, v5
	v_div_fmas_f32 v5, v5, v20, v14
	v_lshlrev_b32_e32 v14, 16, v7
	v_mul_f32_e32 v15, 0xbfb8aa3b, v14
	v_exp_f32_e32 v15, v15
	v_and_b32_e32 v10, 0xffff0000, v10
	v_mul_f32_e32 v4, v4, v16
	v_div_fixup_f32 v5, v5, v17, v6
	v_mul_f32_e32 v5, v5, v10
	v_cvt_pk_bf16_f32 v10, v4, v5
	v_add_f32_e32 v4, 1.0, v15
	v_div_scale_f32 v5, s[0:1], v4, v4, v14
	v_rcp_f32_e32 v6, v5
	v_and_b32_e32 v7, 0xffff0000, v7
	v_mul_f32_e32 v18, 0xbfb8aa3b, v7
	v_exp_f32_e32 v18, v18
	v_fma_f32 v16, -v5, v6, 1.0
	v_fmac_f32_e32 v6, v16, v6
	v_div_scale_f32 v16, vcc, v14, v4, v14
	v_mul_f32_e32 v17, v16, v6
	v_fma_f32 v19, -v5, v17, v16
	v_fmac_f32_e32 v17, v19, v6
	v_fma_f32 v5, -v5, v17, v16
	v_add_f32_e32 v16, 1.0, v18
	v_div_scale_f32 v18, s[0:1], v16, v16, v7
	v_rcp_f32_e32 v19, v18
	v_div_fmas_f32 v5, v5, v6, v17
	v_div_fixup_f32 v4, v5, v4, v14
	v_lshlrev_b32_e32 v15, 16, v11
	v_fma_f32 v5, -v18, v19, 1.0
	v_fmac_f32_e32 v19, v5, v19
	v_div_scale_f32 v5, vcc, v7, v16, v7
	v_mul_f32_e32 v6, v5, v19
	v_fma_f32 v14, -v18, v6, v5
	v_fmac_f32_e32 v6, v14, v19
	v_fma_f32 v5, -v18, v6, v5
	v_div_fmas_f32 v5, v5, v19, v6
	v_and_b32_e32 v11, 0xffff0000, v11
	v_div_fixup_f32 v5, v5, v16, v7
	v_mul_f32_e32 v4, v4, v15
	v_mul_f32_e32 v5, v5, v11
	v_or_b32_e32 v6, 4, v0
	v_cvt_pk_bf16_f32 v11, v4, v5
	v_mad_u64_u32 v[4:5], s[0:1], v6, s44, v[2:3]
	v_add_u32_e32 v5, v13, v5
	v_lshl_add_u64 v[4:5], v[4:5], 0, s[8:9]
	v_lshl_add_u64 v[4:5], v[4:5], 0, v[176:177]
	v_add_co_u32_e32 v4, vcc, s50, v4
	s_add_u32 s0, s24, s8
	s_nop 0
	v_addc_co_u32_e32 v5, vcc, 0, v5, vcc
	s_nop 1
	v_mov_b64_e32 v[14:15], v[100:101]
	v_mov_b64_e32 v[16:17], v[102:103]
	s_addc_u32 s1, s25, 0
	v_lshl_add_u64 v[4:5], s[0:1], 0, v[176:177]
	v_lshlrev_b64 v[18:19], 12, v[0:1]
	v_lshl_add_u64 v[18:19], v[4:5], 0, v[18:19]
	global_store_dwordx4 v[18:19], v[8:11], off
	ds_read_b128 v[8:11], v12 offset:1088
	s_waitcnt lgkmcnt(0)
; __device__ __forceinline__ void attn_unit(const bf16* __restrict__ P, unsigned short* __restrict__ Ob, int b, int h, int kvh, int qb, bool meta, int jt0, int ntl, float* part, unsigned* cnt, const float* __restrict__ qnw, const float2* __restrict__ rtab, char* lds) {
;     ...
;     for (int i = 0; i < 8; ++i) { const int cidx = lane + 64 * i, orow = cidx >> 4, c8 = (cidx & 15) * 8;
;       const u32x4 ov = *(const u32x4*)(stg + orow * 272 + c8 * 2);
;       const u32x4 gv = *(const u32x4*)(Pg + (grow0 + orow) * LD + 4096 + h * D + c8);
;       const unsigned ow[4] = {ov.x, ov.y, ov.z, ov.w}, gw[4] = {gv.x, gv.y, gv.z, gv.w}; unsigned res[4];
; #pragma unroll
;       for (int e = 0; e < 4; ++e) { const float o0 = __uint_as_float(ow[e] << 16), o1 = __uint_as_float(ow[e] & 0xffff0000u), g0 = __uint_as_float(gw[e] << 16), g1 = __uint_as_float(gw[e] & 0xffff0000u);
;         res[e] = cvtpk(o0 * (g0 / (1.f + __expf(-g0))), o1 * (g1 / (1.f + __expf(-g1)))); }
;       *(u32x4*)(Ob + (grow0 + orow) * 2048 + h * D + c8) = (u32x4){res[0], res[1], res[2], res[3]}; }
	v_lshlrev_b32_e32 v21, 16, v8
	v_and_b32_e32 v8, 0xffff0000, v8
	s_nop 0
	v_lshlrev_b32_e32 v7, 16, v14
	v_mul_f32_e32 v20, 0xbfb8aa3b, v7
	v_exp_f32_e32 v20, v20
	v_and_b32_e32 v14, 0xffff0000, v14
	v_mul_f32_e32 v24, 0xbfb8aa3b, v14
	v_exp_f32_e32 v24, v24
	v_add_f32_e32 v18, 1.0, v20
	v_div_scale_f32 v19, s[0:1], v18, v18, v7
	v_rcp_f32_e32 v20, v19
	s_nop 0
	v_fma_f32 v22, -v19, v20, 1.0
	v_fmac_f32_e32 v20, v22, v20
	v_div_scale_f32 v22, vcc, v7, v18, v7
	v_mul_f32_e32 v23, v22, v20
	v_fma_f32 v25, -v19, v23, v22
	v_fmac_f32_e32 v23, v25, v20
	v_fma_f32 v19, -v19, v23, v22
	v_add_f32_e32 v22, 1.0, v24
	v_div_scale_f32 v24, s[0:1], v22, v22, v14
	v_rcp_f32_e32 v25, v24
	v_div_fmas_f32 v19, v19, v20, v23
	v_div_fixup_f32 v7, v19, v18, v7
	v_mul_f32_e32 v7, v7, v21
	v_fma_f32 v18, -v24, v25, 1.0
	v_fmac_f32_e32 v25, v18, v25
	v_div_scale_f32 v18, vcc, v14, v22, v14
	v_mul_f32_e32 v19, v18, v25
	v_fma_f32 v20, -v24, v19, v18
	v_fmac_f32_e32 v19, v20, v25
	v_fma_f32 v18, -v24, v19, v18
	v_div_fmas_f32 v18, v18, v25, v19
	v_lshlrev_b32_e32 v19, 16, v15
	v_mul_f32_e32 v20, 0xbfb8aa3b, v19
	v_exp_f32_e32 v20, v20
	v_div_fixup_f32 v14, v18, v22, v14
	v_mul_f32_e32 v8, v14, v8
	v_cvt_pk_bf16_f32 v14, v7, v8
	v_add_f32_e32 v7, 1.0, v20
	v_div_scale_f32 v8, s[0:1], v7, v7, v19
	v_rcp_f32_e32 v18, v8
	v_and_b32_e32 v15, 0xffff0000, v15
	v_mul_f32_e32 v23, 0xbfb8aa3b, v15
	v_exp_f32_e32 v23, v23
	v_fma_f32 v21, -v8, v18, 1.0
	v_fmac_f32_e32 v18, v21, v18
	v_div_scale_f32 v21, vcc, v19, v7, v19
	v_mul_f32_e32 v22, v21, v18
	v_fma_f32 v24, -v8, v22, v21
	v_fmac_f32_e32 v22, v24, v18
	v_fma_f32 v8, -v8, v22, v21
	v_add_f32_e32 v21, 1.0, v23
	v_div_scale_f32 v23, s[0:1], v21, v21, v15
	v_rcp_f32_e32 v24, v23
	v_div_fmas_f32 v8, v8, v18, v22
	v_div_fixup_f32 v7, v8, v7, v19
	v_lshlrev_b32_e32 v20, 16, v9
	v_fma_f32 v8, -v23, v24, 1.0
	v_fmac_f32_e32 v24, v8, v24
	v_div_scale_f32 v8, vcc, v15, v21, v15
	v_mul_f32_e32 v18, v8, v24
	v_fma_f32 v19, -v23, v18, v8
	v_fmac_f32_e32 v18, v19, v24
	v_fma_f32 v8, -v23, v18, v8
	v_div_fmas_f32 v8, v8, v24, v18
	v_lshlrev_b32_e32 v18, 16, v16
	v_mul_f32_e32 v19, 0xbfb8aa3b, v18
	v_exp_f32_e32 v19, v19
	v_and_b32_e32 v9, 0xffff0000, v9
	v_mul_f32_e32 v7, v7, v20
	v_div_fixup_f32 v8, v8, v21, v15
	v_mul_f32_e32 v8, v8, v9
	v_cvt_pk_bf16_f32 v15, v7, v8
	v_add_f32_e32 v7, 1.0, v19
	v_div_scale_f32 v8, s[0:1], v7, v7, v18
	v_rcp_f32_e32 v9, v8
	v_and_b32_e32 v16, 0xffff0000, v16
	v_mul_f32_e32 v22, 0xbfb8aa3b, v16
	v_exp_f32_e32 v22, v22
	v_fma_f32 v20, -v8, v9, 1.0
	v_fmac_f32_e32 v9, v20, v9
	v_div_scale_f32 v20, vcc, v18, v7, v18
	v_mul_f32_e32 v21, v20, v9
	v_fma_f32 v23, -v8, v21, v20
	v_fmac_f32_e32 v21, v23, v9
	v_fma_f32 v8, -v8, v21, v20
	v_add_f32_e32 v20, 1.0, v22
	v_div_scale_f32 v22, s[0:1], v20, v20, v16
	v_rcp_f32_e32 v23, v22
	v_div_fmas_f32 v8, v8, v9, v21
	v_div_fixup_f32 v7, v8, v7, v18
	v_lshlrev_b32_e32 v19, 16, v10
	v_fma_f32 v8, -v22, v23, 1.0
	v_fmac_f32_e32 v23, v8, v23
	v_div_scale_f32 v8, vcc, v16, v20, v16
	v_mul_f32_e32 v9, v8, v23
	v_fma_f32 v18, -v22, v9, v8
	v_fmac_f32_e32 v9, v18, v23
	v_fma_f32 v8, -v22, v9, v8
	v_div_fmas_f32 v8, v8, v23, v9
	v_lshlrev_b32_e32 v9, 16, v17
	v_mul_f32_e32 v18, 0xbfb8aa3b, v9
	v_exp_f32_e32 v18, v18
	v_and_b32_e32 v10, 0xffff0000, v10
	v_mul_f32_e32 v7, v7, v19
	v_div_fixup_f32 v8, v8, v20, v16
	v_mul_f32_e32 v8, v8, v10
	v_cvt_pk_bf16_f32 v16, v7, v8
	v_add_f32_e32 v7, 1.0, v18
	v_div_scale_f32 v8, s[0:1], v7, v7, v9
	v_rcp_f32_e32 v10, v8
	v_and_b32_e32 v17, 0xffff0000, v17
	v_mul_f32_e32 v21, 0xbfb8aa3b, v17
	v_exp_f32_e32 v21, v21
	v_fma_f32 v19, -v8, v10, 1.0
	v_fmac_f32_e32 v10, v19, v10
	v_div_scale_f32 v19, vcc, v9, v7, v9
	v_mul_f32_e32 v20, v19, v10
	v_fma_f32 v22, -v8, v20, v19
	v_fmac_f32_e32 v20, v22, v10
	v_fma_f32 v8, -v8, v20, v19
	v_add_f32_e32 v19, 1.0, v21
	v_div_scale_f32 v21, s[0:1], v19, v19, v17
	v_rcp_f32_e32 v22, v21
	v_div_fmas_f32 v8, v8, v10, v20
	v_div_fixup_f32 v7, v8, v7, v9
	v_lshlrev_b32_e32 v18, 16, v11
	v_fma_f32 v8, -v21, v22, 1.0
	v_fmac_f32_e32 v22, v8, v22
	v_div_scale_f32 v8, vcc, v17, v19, v17
	v_mul_f32_e32 v9, v8, v22
	v_fma_f32 v10, -v21, v9, v8
	v_fmac_f32_e32 v9, v10, v22
	v_fma_f32 v8, -v21, v9, v8
	v_div_fmas_f32 v8, v8, v22, v9
	v_and_b32_e32 v11, 0xffff0000, v11
	v_div_fixup_f32 v8, v8, v19, v17
	v_mul_f32_e32 v8, v8, v11
	v_or_b32_e32 v10, 8, v0
	v_mul_f32_e32 v7, v7, v18
	v_cvt_pk_bf16_f32 v17, v7, v8
	v_mad_u64_u32 v[8:9], s[0:1], v10, s44, v[2:3]
	v_add_u32_e32 v9, v13, v9
	v_lshl_add_u64 v[8:9], v[8:9], 0, s[8:9]
	v_lshl_add_u64 v[8:9], v[8:9], 0, v[176:177]
	v_add_co_u32_e32 v8, vcc, s50, v8
	v_mov_b32_e32 v7, v1
	s_nop 0
	v_addc_co_u32_e32 v9, vcc, 0, v9, vcc
	s_nop 1
	v_mov_b64_e32 v[18:19], v[104:105]
	v_mov_b64_e32 v[20:21], v[106:107]
	v_lshlrev_b64 v[6:7], 12, v[6:7]
	v_lshl_add_u64 v[6:7], v[4:5], 0, v[6:7]
	global_store_dwordx4 v[6:7], v[14:17], off
	s_nop 0
	v_lshlrev_b32_e32 v11, 16, v18
	v_mul_f32_e32 v8, 0xbfb8aa3b, v11
	v_exp_f32_e32 v22, v8
	v_and_b32_e32 v18, 0xffff0000, v18
	v_mul_f32_e32 v24, 0xbfb8aa3b, v18
	v_exp_f32_e32 v24, v24
	v_add_f32_e32 v14, 1.0, v22
	v_div_scale_f32 v15, s[0:1], v14, v14, v11
	v_rcp_f32_e32 v16, v15
	ds_read_b128 v[6:9], v12 offset:2176
	v_fma_f32 v22, -v15, v16, 1.0
	v_fmac_f32_e32 v16, v22, v16
	v_div_scale_f32 v22, vcc, v11, v14, v11
	v_mul_f32_e32 v23, v22, v16
	v_fma_f32 v25, -v15, v23, v22
	v_fmac_f32_e32 v23, v25, v16
	v_fma_f32 v15, -v15, v23, v22
	v_add_f32_e32 v22, 1.0, v24
	v_div_scale_f32 v24, s[0:1], v22, v22, v18
	v_rcp_f32_e32 v25, v24
	v_div_fmas_f32 v15, v15, v16, v23
	v_div_fixup_f32 v11, v15, v14, v11
	s_waitcnt lgkmcnt(0)
; __device__ __forceinline__ void attn_unit(const bf16* __restrict__ P, unsigned short* __restrict__ Ob, int b, int h, int kvh, int qb, bool meta, int jt0, int ntl, float* part, unsigned* cnt, const float* __restrict__ qnw, const float2* __restrict__ rtab, char* lds) {
;     ...
;     for (int i = 0; i < 8; ++i) { const int cidx = lane + 64 * i, orow = cidx >> 4, c8 = (cidx & 15) * 8;
;       const u32x4 ov = *(const u32x4*)(stg + orow * 272 + c8 * 2);
;       const u32x4 gv = *(const u32x4*)(Pg + (grow0 + orow) * LD + 4096 + h * D + c8);
;       const unsigned ow[4] = {ov.x, ov.y, ov.z, ov.w}, gw[4] = {gv.x, gv.y, gv.z, gv.w}; unsigned res[4];
; #pragma unroll
;       for (int e = 0; e < 4; ++e) { const float o0 = __uint_as_float(ow[e] << 16), o1 = __uint_as_float(ow[e] & 0xffff0000u), g0 = __uint_as_float(gw[e] << 16), g1 = __uint_as_float(gw[e] & 0xffff0000u);
;         res[e] = cvtpk(o0 * (g0 / (1.f + __expf(-g0))), o1 * (g1 / (1.f + __expf(-g1)))); }
;       *(u32x4*)(Ob + (grow0 + orow) * 2048 + h * D + c8) = (u32x4){res[0], res[1], res[2], res[3]}; }
	v_lshlrev_b32_e32 v17, 16, v6
	v_fma_f32 v14, -v24, v25, 1.0
	v_fmac_f32_e32 v25, v14, v25
	v_div_scale_f32 v14, vcc, v18, v22, v18
	v_mul_f32_e32 v15, v14, v25
	v_fma_f32 v16, -v24, v15, v14
	v_fmac_f32_e32 v15, v16, v25
	v_fma_f32 v14, -v24, v15, v14
	v_div_fmas_f32 v14, v14, v25, v15
	v_lshlrev_b32_e32 v15, 16, v19
	v_mul_f32_e32 v16, 0xbfb8aa3b, v15
	v_exp_f32_e32 v16, v16
	v_and_b32_e32 v6, 0xffff0000, v6
	v_div_fixup_f32 v14, v14, v22, v18
	v_mul_f32_e32 v6, v14, v6
	v_mul_f32_e32 v11, v11, v17
	v_cvt_pk_bf16_f32 v14, v11, v6
	v_add_f32_e32 v6, 1.0, v16
	v_div_scale_f32 v11, s[0:1], v6, v6, v15
	v_rcp_f32_e32 v16, v11
	v_and_b32_e32 v18, 0xffff0000, v19
	v_mul_f32_e32 v23, 0xbfb8aa3b, v18
	v_exp_f32_e32 v23, v23
	v_fma_f32 v19, -v11, v16, 1.0
	v_fmac_f32_e32 v16, v19, v16
	v_div_scale_f32 v19, vcc, v15, v6, v15
	v_mul_f32_e32 v22, v19, v16
	v_fma_f32 v24, -v11, v22, v19
	v_fmac_f32_e32 v22, v24, v16
	v_fma_f32 v11, -v11, v22, v19
	v_add_f32_e32 v19, 1.0, v23
	v_div_scale_f32 v23, s[0:1], v19, v19, v18
	v_rcp_f32_e32 v24, v23
	v_div_fmas_f32 v11, v11, v16, v22
	v_div_fixup_f32 v6, v11, v6, v15
	v_lshlrev_b32_e32 v17, 16, v7
	v_fma_f32 v11, -v23, v24, 1.0
	v_fmac_f32_e32 v24, v11, v24
	v_div_scale_f32 v11, vcc, v18, v19, v18
	v_mul_f32_e32 v15, v11, v24
	v_fma_f32 v16, -v23, v15, v11
	v_fmac_f32_e32 v15, v16, v24
	v_fma_f32 v11, -v23, v15, v11
	v_lshlrev_b32_e32 v16, 16, v20
	v_div_fmas_f32 v11, v11, v24, v15
	v_mul_f32_e32 v15, 0xbfb8aa3b, v16
	v_mul_f32_e32 v6, v6, v17
	v_exp_f32_e32 v17, v15
	v_and_b32_e32 v7, 0xffff0000, v7
	v_div_fixup_f32 v11, v11, v19, v18
	v_mul_f32_e32 v7, v11, v7
	v_cvt_pk_bf16_f32 v15, v6, v7
	v_add_f32_e32 v6, 1.0, v17
	v_div_scale_f32 v7, s[0:1], v6, v6, v16
	v_rcp_f32_e32 v11, v7
	v_and_b32_e32 v18, 0xffff0000, v20
	v_mul_f32_e32 v22, 0xbfb8aa3b, v18
	v_exp_f32_e32 v22, v22
	v_fma_f32 v19, -v7, v11, 1.0
	v_fmac_f32_e32 v11, v19, v11
	v_div_scale_f32 v19, vcc, v16, v6, v16
	v_mul_f32_e32 v20, v19, v11
	v_fma_f32 v23, -v7, v20, v19
	v_fmac_f32_e32 v20, v23, v11
	v_fma_f32 v7, -v7, v20, v19
	v_add_f32_e32 v19, 1.0, v22
	v_div_scale_f32 v22, s[0:1], v19, v19, v18
	v_rcp_f32_e32 v23, v22
	v_div_fmas_f32 v7, v7, v11, v20
	v_div_fixup_f32 v6, v7, v6, v16
	v_lshlrev_b32_e32 v17, 16, v8
	v_fma_f32 v7, -v22, v23, 1.0
	v_fmac_f32_e32 v23, v7, v23
	v_div_scale_f32 v7, vcc, v18, v19, v18
	v_mul_f32_e32 v11, v7, v23
	v_fma_f32 v16, -v22, v11, v7
	v_fmac_f32_e32 v11, v16, v23
	v_fma_f32 v7, -v22, v11, v7
	v_div_fmas_f32 v7, v7, v23, v11
	v_lshlrev_b32_e32 v11, 16, v21
	v_mul_f32_e32 v16, 0xbfb8aa3b, v11
	v_mul_f32_e32 v6, v6, v17
	v_exp_f32_e32 v17, v16
	v_and_b32_e32 v8, 0xffff0000, v8
	v_div_fixup_f32 v7, v7, v19, v18
	v_mul_f32_e32 v7, v7, v8
	v_cvt_pk_bf16_f32 v16, v6, v7
	v_add_f32_e32 v6, 1.0, v17
	v_div_scale_f32 v7, s[0:1], v6, v6, v11
	v_rcp_f32_e32 v8, v7
	v_and_b32_e32 v18, 0xffff0000, v21
	v_mul_f32_e32 v21, 0xbfb8aa3b, v18
	v_exp_f32_e32 v21, v21
	v_fma_f32 v19, -v7, v8, 1.0
	v_fmac_f32_e32 v8, v19, v8
	v_div_scale_f32 v19, vcc, v11, v6, v11
	v_mul_f32_e32 v20, v19, v8
	v_fma_f32 v22, -v7, v20, v19
	v_fmac_f32_e32 v20, v22, v8
	v_fma_f32 v7, -v7, v20, v19
	v_add_f32_e32 v19, 1.0, v21
	v_div_scale_f32 v21, s[0:1], v19, v19, v18
	v_rcp_f32_e32 v22, v21
	v_div_fmas_f32 v7, v7, v8, v20
	v_div_fixup_f32 v6, v7, v6, v11
	v_lshlrev_b32_e32 v17, 16, v9
	v_fma_f32 v7, -v21, v22, 1.0
	v_fmac_f32_e32 v22, v7, v22
	v_div_scale_f32 v7, vcc, v18, v19, v18
	v_mul_f32_e32 v8, v7, v22
	v_fma_f32 v11, -v21, v8, v7
	v_fmac_f32_e32 v8, v11, v22
	v_fma_f32 v7, -v21, v8, v7
	v_div_fmas_f32 v7, v7, v22, v8
	v_and_b32_e32 v9, 0xffff0000, v9
	v_div_fixup_f32 v7, v7, v19, v18
	v_mul_f32_e32 v6, v6, v17
	v_mul_f32_e32 v7, v7, v9
	v_or_b32_e32 v8, 12, v0
	v_cvt_pk_bf16_f32 v17, v6, v7
	v_mad_u64_u32 v[6:7], s[0:1], v8, s44, v[2:3]
	v_add_u32_e32 v7, v13, v7
	v_lshl_add_u64 v[6:7], v[6:7], 0, s[8:9]
	v_lshl_add_u64 v[6:7], v[6:7], 0, v[176:177]
	v_add_co_u32_e32 v6, vcc, s50, v6
	v_mov_b32_e32 v11, v1
	s_nop 0
	v_addc_co_u32_e32 v7, vcc, 0, v7, vcc
	s_nop 1
	v_mov_b64_e32 v[18:19], v[108:109]
	v_mov_b64_e32 v[20:21], v[110:111]
	v_lshlrev_b64 v[6:7], 12, v[10:11]
	v_lshl_add_u64 v[6:7], v[4:5], 0, v[6:7]
	global_store_dwordx4 v[6:7], v[14:17], off
	ds_read_b128 v[14:17], v12 offset:3264
	s_waitcnt lgkmcnt(0)
; __device__ __forceinline__ void attn_unit(const bf16* __restrict__ P, unsigned short* __restrict__ Ob, int b, int h, int kvh, int qb, bool meta, int jt0, int ntl, float* part, unsigned* cnt, const float* __restrict__ qnw, const float2* __restrict__ rtab, char* lds) {
;     ...
;     for (int i = 0; i < 8; ++i) { const int cidx = lane + 64 * i, orow = cidx >> 4, c8 = (cidx & 15) * 8;
;       const u32x4 ov = *(const u32x4*)(stg + orow * 272 + c8 * 2);
;       const u32x4 gv = *(const u32x4*)(Pg + (grow0 + orow) * LD + 4096 + h * D + c8);
;       const unsigned ow[4] = {ov.x, ov.y, ov.z, ov.w}, gw[4] = {gv.x, gv.y, gv.z, gv.w}; unsigned res[4];
; #pragma unroll
;       for (int e = 0; e < 4; ++e) { const float o0 = __uint_as_float(ow[e] << 16), o1 = __uint_as_float(ow[e] & 0xffff0000u), g0 = __uint_as_float(gw[e] << 16), g1 = __uint_as_float(gw[e] & 0xffff0000u);
;         res[e] = cvtpk(o0 * (g0 / (1.f + __expf(-g0))), o1 * (g1 / (1.f + __expf(-g1)))); }
;       *(u32x4*)(Ob + (grow0 + orow) * 2048 + h * D + c8) = (u32x4){res[0], res[1], res[2], res[3]}; }
	v_lshlrev_b32_e32 v11, 16, v14
	v_and_b32_e32 v14, 0xffff0000, v14
	s_nop 0
	v_lshlrev_b32_e32 v9, 16, v18
	v_mul_f32_e32 v10, 0xbfb8aa3b, v9
	v_exp_f32_e32 v10, v10
	v_and_b32_e32 v18, 0xffff0000, v18
	v_mul_f32_e32 v24, 0xbfb8aa3b, v18
	v_exp_f32_e32 v24, v24
	v_add_f32_e32 v6, 1.0, v10
	v_div_scale_f32 v7, s[0:1], v6, v6, v9
	v_rcp_f32_e32 v10, v7
	s_nop 0
	v_fma_f32 v22, -v7, v10, 1.0
	v_fmac_f32_e32 v10, v22, v10
	v_div_scale_f32 v22, vcc, v9, v6, v9
	v_mul_f32_e32 v23, v22, v10
	v_fma_f32 v25, -v7, v23, v22
	v_fmac_f32_e32 v23, v25, v10
	v_fma_f32 v7, -v7, v23, v22
	v_add_f32_e32 v22, 1.0, v24
	v_div_scale_f32 v24, s[0:1], v22, v22, v18
	v_rcp_f32_e32 v25, v24
	v_div_fmas_f32 v7, v7, v10, v23
	v_div_fixup_f32 v6, v7, v6, v9
	v_mul_f32_e32 v6, v6, v11
	v_fma_f32 v7, -v24, v25, 1.0
	v_fmac_f32_e32 v25, v7, v25
	v_div_scale_f32 v7, vcc, v18, v22, v18
	v_mul_f32_e32 v9, v7, v25
	v_fma_f32 v10, -v24, v9, v7
	v_fmac_f32_e32 v9, v10, v25
	v_fma_f32 v7, -v24, v9, v7
	v_div_fmas_f32 v7, v7, v25, v9
	v_lshlrev_b32_e32 v9, 16, v19
	v_mul_f32_e32 v10, 0xbfb8aa3b, v9
	v_exp_f32_e32 v10, v10
	v_div_fixup_f32 v7, v7, v22, v18
	v_mul_f32_e32 v7, v7, v14
	v_cvt_pk_bf16_f32 v14, v6, v7
	v_add_f32_e32 v6, 1.0, v10
	v_div_scale_f32 v7, s[0:1], v6, v6, v9
	v_rcp_f32_e32 v10, v7
	v_and_b32_e32 v18, 0xffff0000, v19
	v_mul_f32_e32 v23, 0xbfb8aa3b, v18
	v_exp_f32_e32 v23, v23
	v_fma_f32 v19, -v7, v10, 1.0
	v_fmac_f32_e32 v10, v19, v10
	v_div_scale_f32 v19, vcc, v9, v6, v9
	v_mul_f32_e32 v22, v19, v10
	v_fma_f32 v24, -v7, v22, v19
	v_fmac_f32_e32 v22, v24, v10
	v_fma_f32 v7, -v7, v22, v19
	v_add_f32_e32 v19, 1.0, v23
	v_div_scale_f32 v23, s[0:1], v19, v19, v18
	v_rcp_f32_e32 v24, v23
	v_div_fmas_f32 v7, v7, v10, v22
	v_div_fixup_f32 v6, v7, v6, v9
	v_lshlrev_b32_e32 v11, 16, v15
	v_fma_f32 v7, -v23, v24, 1.0
	v_fmac_f32_e32 v24, v7, v24
	v_div_scale_f32 v7, vcc, v18, v19, v18
	v_mul_f32_e32 v9, v7, v24
	v_fma_f32 v10, -v23, v9, v7
	v_fmac_f32_e32 v9, v10, v24
	v_fma_f32 v7, -v23, v9, v7
	v_div_fmas_f32 v7, v7, v24, v9
	v_lshlrev_b32_e32 v9, 16, v20
	v_mul_f32_e32 v10, 0xbfb8aa3b, v9
	v_exp_f32_e32 v10, v10
	v_and_b32_e32 v15, 0xffff0000, v15
	v_mul_f32_e32 v6, v6, v11
	v_div_fixup_f32 v7, v7, v19, v18
	v_mul_f32_e32 v7, v7, v15
	v_cvt_pk_bf16_f32 v15, v6, v7
	v_add_f32_e32 v6, 1.0, v10
	v_div_scale_f32 v7, s[0:1], v6, v6, v9
	v_rcp_f32_e32 v10, v7
	v_and_b32_e32 v18, 0xffff0000, v20
	v_mul_f32_e32 v22, 0xbfb8aa3b, v18
	v_exp_f32_e32 v22, v22
	v_fma_f32 v19, -v7, v10, 1.0
	v_fmac_f32_e32 v10, v19, v10
	v_div_scale_f32 v19, vcc, v9, v6, v9
	v_mul_f32_e32 v20, v19, v10
	v_fma_f32 v23, -v7, v20, v19
	v_fmac_f32_e32 v20, v23, v10
	v_fma_f32 v7, -v7, v20, v19
	v_add_f32_e32 v19, 1.0, v22
	v_div_scale_f32 v22, s[0:1], v19, v19, v18
	v_rcp_f32_e32 v23, v22
	v_div_fmas_f32 v7, v7, v10, v20
	v_div_fixup_f32 v6, v7, v6, v9
	v_lshlrev_b32_e32 v11, 16, v16
	v_fma_f32 v7, -v22, v23, 1.0
	v_fmac_f32_e32 v23, v7, v23
	v_div_scale_f32 v7, vcc, v18, v19, v18
	v_mul_f32_e32 v9, v7, v23
	v_fma_f32 v10, -v22, v9, v7
	v_fmac_f32_e32 v9, v10, v23
	v_fma_f32 v7, -v22, v9, v7
	v_div_fmas_f32 v7, v7, v23, v9
	v_lshlrev_b32_e32 v9, 16, v21
	v_mul_f32_e32 v10, 0xbfb8aa3b, v9
	v_exp_f32_e32 v10, v10
	v_and_b32_e32 v16, 0xffff0000, v16
	v_mul_f32_e32 v6, v6, v11
	v_div_fixup_f32 v7, v7, v19, v18
	v_mul_f32_e32 v7, v7, v16
	v_cvt_pk_bf16_f32 v16, v6, v7
	v_add_f32_e32 v6, 1.0, v10
	v_div_scale_f32 v7, s[0:1], v6, v6, v9
	v_rcp_f32_e32 v10, v7
	v_and_b32_e32 v18, 0xffff0000, v21
	v_mul_f32_e32 v21, 0xbfb8aa3b, v18
	v_exp_f32_e32 v21, v21
	v_fma_f32 v19, -v7, v10, 1.0
	v_fmac_f32_e32 v10, v19, v10
	v_div_scale_f32 v19, vcc, v9, v6, v9
	v_mul_f32_e32 v20, v19, v10
	v_fma_f32 v22, -v7, v20, v19
	v_fmac_f32_e32 v20, v22, v10
	v_fma_f32 v7, -v7, v20, v19
	v_add_f32_e32 v19, 1.0, v21
	v_div_scale_f32 v21, s[0:1], v19, v19, v18
	v_rcp_f32_e32 v22, v21
	v_div_fmas_f32 v7, v7, v10, v20
	v_div_fixup_f32 v6, v7, v6, v9
	v_lshlrev_b32_e32 v11, 16, v17
	v_fma_f32 v7, -v21, v22, 1.0
	v_fmac_f32_e32 v22, v7, v22
	v_div_scale_f32 v7, vcc, v18, v19, v18
	v_mul_f32_e32 v9, v7, v22
	v_fma_f32 v10, -v21, v9, v7
	v_fmac_f32_e32 v9, v10, v22
	v_fma_f32 v7, -v21, v9, v7
	v_div_fmas_f32 v7, v7, v22, v9
	v_and_b32_e32 v17, 0xffff0000, v17
	v_mul_f32_e32 v6, v6, v11
	v_div_fixup_f32 v7, v7, v19, v18
	v_mul_f32_e32 v7, v7, v17
	v_cvt_pk_bf16_f32 v17, v6, v7
	v_or_b32_e32 v6, 16, v0
	v_mad_u64_u32 v[10:11], s[0:1], v6, s44, v[2:3]
	v_add_u32_e32 v11, v13, v11
	v_lshl_add_u64 v[10:11], v[10:11], 0, s[8:9]
	v_lshl_add_u64 v[10:11], v[10:11], 0, v[176:177]
	v_add_co_u32_e32 v10, vcc, s50, v10
	v_mov_b32_e32 v9, v1
	s_nop 0
	v_addc_co_u32_e32 v11, vcc, 0, v11, vcc
	s_nop 1
	v_mov_b64_e32 v[18:19], v[112:113]
	v_mov_b64_e32 v[20:21], v[114:115]
	v_lshlrev_b64 v[8:9], 12, v[8:9]
	v_lshl_add_u64 v[8:9], v[4:5], 0, v[8:9]
	global_store_dwordx4 v[8:9], v[14:17], off
	s_nop 0
	v_lshlrev_b32_e32 v7, 16, v18
	v_mul_f32_e32 v10, 0xbfb8aa3b, v7
	v_exp_f32_e32 v22, v10
	v_and_b32_e32 v18, 0xffff0000, v18
	v_mul_f32_e32 v24, 0xbfb8aa3b, v18
	v_exp_f32_e32 v24, v24
	v_add_f32_e32 v14, 1.0, v22
	v_div_scale_f32 v15, s[0:1], v14, v14, v7
	v_rcp_f32_e32 v16, v15
	ds_read_b128 v[8:11], v12 offset:4352
	v_fma_f32 v22, -v15, v16, 1.0
	v_fmac_f32_e32 v16, v22, v16
	v_div_scale_f32 v22, vcc, v7, v14, v7
	v_mul_f32_e32 v23, v22, v16
	v_fma_f32 v25, -v15, v23, v22
	v_fmac_f32_e32 v23, v25, v16
	v_fma_f32 v15, -v15, v23, v22
	v_add_f32_e32 v22, 1.0, v24
	v_div_scale_f32 v24, s[0:1], v22, v22, v18
	v_rcp_f32_e32 v25, v24
	v_div_fmas_f32 v15, v15, v16, v23
	v_div_fixup_f32 v7, v15, v14, v7
	s_waitcnt lgkmcnt(0)
; __device__ __forceinline__ void attn_unit(const bf16* __restrict__ P, unsigned short* __restrict__ Ob, int b, int h, int kvh, int qb, bool meta, int jt0, int ntl, float* part, unsigned* cnt, const float* __restrict__ qnw, const float2* __restrict__ rtab, char* lds) {
;     ...
;     for (int i = 0; i < 8; ++i) { const int cidx = lane + 64 * i, orow = cidx >> 4, c8 = (cidx & 15) * 8;
;       const u32x4 ov = *(const u32x4*)(stg + orow * 272 + c8 * 2);
;       const u32x4 gv = *(const u32x4*)(Pg + (grow0 + orow) * LD + 4096 + h * D + c8);
;       const unsigned ow[4] = {ov.x, ov.y, ov.z, ov.w}, gw[4] = {gv.x, gv.y, gv.z, gv.w}; unsigned res[4];
; #pragma unroll
;       for (int e = 0; e < 4; ++e) { const float o0 = __uint_as_float(ow[e] << 16), o1 = __uint_as_float(ow[e] & 0xffff0000u), g0 = __uint_as_float(gw[e] << 16), g1 = __uint_as_float(gw[e] & 0xffff0000u);
;         res[e] = cvtpk(o0 * (g0 / (1.f + __expf(-g0))), o1 * (g1 / (1.f + __expf(-g1)))); }
;       *(u32x4*)(Ob + (grow0 + orow) * 2048 + h * D + c8) = (u32x4){res[0], res[1], res[2], res[3]}; }
	v_lshlrev_b32_e32 v17, 16, v8
	v_fma_f32 v14, -v24, v25, 1.0
	v_fmac_f32_e32 v25, v14, v25
	v_div_scale_f32 v14, vcc, v18, v22, v18
	v_mul_f32_e32 v15, v14, v25
	v_fma_f32 v16, -v24, v15, v14
	v_fmac_f32_e32 v15, v16, v25
	v_fma_f32 v14, -v24, v15, v14
	v_div_fmas_f32 v14, v14, v25, v15
	v_lshlrev_b32_e32 v15, 16, v19
	v_mul_f32_e32 v16, 0xbfb8aa3b, v15
	v_exp_f32_e32 v16, v16
	v_and_b32_e32 v8, 0xffff0000, v8
	v_mul_f32_e32 v7, v7, v17
	v_div_fixup_f32 v14, v14, v22, v18
	v_mul_f32_e32 v8, v14, v8
	v_cvt_pk_bf16_f32 v14, v7, v8
	v_add_f32_e32 v7, 1.0, v16
	v_div_scale_f32 v8, s[0:1], v7, v7, v15
	v_rcp_f32_e32 v16, v8
	v_and_b32_e32 v18, 0xffff0000, v19
	v_mul_f32_e32 v23, 0xbfb8aa3b, v18
	v_exp_f32_e32 v23, v23
	v_fma_f32 v19, -v8, v16, 1.0
	v_fmac_f32_e32 v16, v19, v16
	v_div_scale_f32 v19, vcc, v15, v7, v15
	v_mul_f32_e32 v22, v19, v16
	v_fma_f32 v24, -v8, v22, v19
	v_fmac_f32_e32 v22, v24, v16
	v_fma_f32 v8, -v8, v22, v19
	v_add_f32_e32 v19, 1.0, v23
	v_div_scale_f32 v23, s[0:1], v19, v19, v18
	v_rcp_f32_e32 v24, v23
	v_div_fmas_f32 v8, v8, v16, v22
	v_div_fixup_f32 v7, v8, v7, v15
	v_lshlrev_b32_e32 v17, 16, v9
	v_fma_f32 v8, -v23, v24, 1.0
	v_fmac_f32_e32 v24, v8, v24
	v_div_scale_f32 v8, vcc, v18, v19, v18
	v_mul_f32_e32 v15, v8, v24
	v_fma_f32 v16, -v23, v15, v8
	v_fmac_f32_e32 v15, v16, v24
	v_fma_f32 v8, -v23, v15, v8
	v_lshlrev_b32_e32 v16, 16, v20
	v_div_fmas_f32 v8, v8, v24, v15
	v_mul_f32_e32 v15, 0xbfb8aa3b, v16
	v_mul_f32_e32 v7, v7, v17
	v_exp_f32_e32 v17, v15
	v_and_b32_e32 v9, 0xffff0000, v9
	v_div_fixup_f32 v8, v8, v19, v18
	v_mul_f32_e32 v8, v8, v9
	v_cvt_pk_bf16_f32 v15, v7, v8
	v_add_f32_e32 v7, 1.0, v17
	v_div_scale_f32 v8, s[0:1], v7, v7, v16
	v_rcp_f32_e32 v9, v8
	v_and_b32_e32 v18, 0xffff0000, v20
	v_mul_f32_e32 v22, 0xbfb8aa3b, v18
	v_exp_f32_e32 v22, v22
	v_fma_f32 v19, -v8, v9, 1.0
	v_fmac_f32_e32 v9, v19, v9
	v_div_scale_f32 v19, vcc, v16, v7, v16
	v_mul_f32_e32 v20, v19, v9
	v_fma_f32 v23, -v8, v20, v19
	v_fmac_f32_e32 v20, v23, v9
	v_fma_f32 v8, -v8, v20, v19
	v_add_f32_e32 v19, 1.0, v22
	v_div_scale_f32 v22, s[0:1], v19, v19, v18
	v_rcp_f32_e32 v23, v22
	v_div_fmas_f32 v8, v8, v9, v20
	v_div_fixup_f32 v7, v8, v7, v16
	v_lshlrev_b32_e32 v17, 16, v10
	v_fma_f32 v8, -v22, v23, 1.0
	v_fmac_f32_e32 v23, v8, v23
	v_div_scale_f32 v8, vcc, v18, v19, v18
	v_mul_f32_e32 v9, v8, v23
	v_fma_f32 v16, -v22, v9, v8
	v_fmac_f32_e32 v9, v16, v23
	v_fma_f32 v8, -v22, v9, v8
	v_div_fmas_f32 v8, v8, v23, v9
	v_lshlrev_b32_e32 v9, 16, v21
	v_mul_f32_e32 v16, 0xbfb8aa3b, v9
	v_mul_f32_e32 v7, v7, v17
	v_exp_f32_e32 v17, v16
	v_and_b32_e32 v10, 0xffff0000, v10
	v_div_fixup_f32 v8, v8, v19, v18
	v_mul_f32_e32 v8, v8, v10
	v_cvt_pk_bf16_f32 v16, v7, v8
	v_add_f32_e32 v7, 1.0, v17
	v_div_scale_f32 v8, s[0:1], v7, v7, v9
	v_rcp_f32_e32 v10, v8
	v_and_b32_e32 v18, 0xffff0000, v21
	v_mul_f32_e32 v21, 0xbfb8aa3b, v18
	v_exp_f32_e32 v21, v21
	v_fma_f32 v19, -v8, v10, 1.0
	v_fmac_f32_e32 v10, v19, v10
	v_div_scale_f32 v19, vcc, v9, v7, v9
	v_mul_f32_e32 v20, v19, v10
	v_fma_f32 v22, -v8, v20, v19
	v_fmac_f32_e32 v20, v22, v10
	v_fma_f32 v8, -v8, v20, v19
	v_add_f32_e32 v19, 1.0, v21
	v_div_scale_f32 v21, s[0:1], v19, v19, v18
	v_rcp_f32_e32 v22, v21
	v_div_fmas_f32 v8, v8, v10, v20
	v_div_fixup_f32 v7, v8, v7, v9
	v_lshlrev_b32_e32 v17, 16, v11
	v_fma_f32 v8, -v21, v22, 1.0
	v_fmac_f32_e32 v22, v8, v22
	v_div_scale_f32 v8, vcc, v18, v19, v18
	v_mul_f32_e32 v9, v8, v22
	v_fma_f32 v10, -v21, v9, v8
	v_fmac_f32_e32 v9, v10, v22
	v_fma_f32 v8, -v21, v9, v8
	v_div_fmas_f32 v8, v8, v22, v9
	v_and_b32_e32 v11, 0xffff0000, v11
	v_div_fixup_f32 v8, v8, v19, v18
	v_mul_f32_e32 v8, v8, v11
	v_mul_f32_e32 v7, v7, v17
	v_cvt_pk_bf16_f32 v17, v7, v8
	v_or_b32_e32 v8, 20, v0
	v_mad_u64_u32 v[10:11], s[0:1], v8, s44, v[2:3]
	v_add_u32_e32 v11, v13, v11
	v_lshl_add_u64 v[10:11], v[10:11], 0, s[8:9]
	v_lshl_add_u64 v[10:11], v[10:11], 0, v[176:177]
	v_add_co_u32_e32 v10, vcc, s50, v10
	v_mov_b32_e32 v7, v1
	s_nop 0
	v_addc_co_u32_e32 v11, vcc, 0, v11, vcc
	s_nop 1
	v_mov_b64_e32 v[18:19], v[116:117]
	v_mov_b64_e32 v[20:21], v[118:119]
	v_lshlrev_b64 v[6:7], 12, v[6:7]
	v_lshl_add_u64 v[6:7], v[4:5], 0, v[6:7]
	global_store_dwordx4 v[6:7], v[14:17], off
	ds_read_b128 v[14:17], v12 offset:5440
	s_waitcnt lgkmcnt(0)
; __device__ __forceinline__ void attn_unit(const bf16* __restrict__ P, unsigned short* __restrict__ Ob, int b, int h, int kvh, int qb, bool meta, int jt0, int ntl, float* part, unsigned* cnt, const float* __restrict__ qnw, const float2* __restrict__ rtab, char* lds) {
;     ...
;     for (int i = 0; i < 8; ++i) { const int cidx = lane + 64 * i, orow = cidx >> 4, c8 = (cidx & 15) * 8;
;       const u32x4 ov = *(const u32x4*)(stg + orow * 272 + c8 * 2);
;       const u32x4 gv = *(const u32x4*)(Pg + (grow0 + orow) * LD + 4096 + h * D + c8);
;       const unsigned ow[4] = {ov.x, ov.y, ov.z, ov.w}, gw[4] = {gv.x, gv.y, gv.z, gv.w}; unsigned res[4];
; #pragma unroll
;       for (int e = 0; e < 4; ++e) { const float o0 = __uint_as_float(ow[e] << 16), o1 = __uint_as_float(ow[e] & 0xffff0000u), g0 = __uint_as_float(gw[e] << 16), g1 = __uint_as_float(gw[e] & 0xffff0000u);
;         res[e] = cvtpk(o0 * (g0 / (1.f + __expf(-g0))), o1 * (g1 / (1.f + __expf(-g1)))); }
;       *(u32x4*)(Ob + (grow0 + orow) * 2048 + h * D + c8) = (u32x4){res[0], res[1], res[2], res[3]}; }
	v_lshlrev_b32_e32 v11, 16, v14
	v_and_b32_e32 v14, 0xffff0000, v14
	s_nop 0
	v_lshlrev_b32_e32 v9, 16, v18
	v_mul_f32_e32 v10, 0xbfb8aa3b, v9
	v_exp_f32_e32 v10, v10
	v_and_b32_e32 v18, 0xffff0000, v18
	v_mul_f32_e32 v24, 0xbfb8aa3b, v18
	v_exp_f32_e32 v24, v24
	v_add_f32_e32 v6, 1.0, v10
	v_div_scale_f32 v7, s[0:1], v6, v6, v9
	v_rcp_f32_e32 v10, v7
	s_nop 0
	v_fma_f32 v22, -v7, v10, 1.0
	v_fmac_f32_e32 v10, v22, v10
	v_div_scale_f32 v22, vcc, v9, v6, v9
	v_mul_f32_e32 v23, v22, v10
	v_fma_f32 v25, -v7, v23, v22
	v_fmac_f32_e32 v23, v25, v10
	v_fma_f32 v7, -v7, v23, v22
	v_add_f32_e32 v22, 1.0, v24
	v_div_scale_f32 v24, s[0:1], v22, v22, v18
	v_rcp_f32_e32 v25, v24
	v_div_fmas_f32 v7, v7, v10, v23
	v_div_fixup_f32 v6, v7, v6, v9
	v_mul_f32_e32 v6, v6, v11
	v_fma_f32 v7, -v24, v25, 1.0
	v_fmac_f32_e32 v25, v7, v25
	v_div_scale_f32 v7, vcc, v18, v22, v18
	v_mul_f32_e32 v9, v7, v25
	v_fma_f32 v10, -v24, v9, v7
	v_fmac_f32_e32 v9, v10, v25
	v_fma_f32 v7, -v24, v9, v7
	v_div_fmas_f32 v7, v7, v25, v9
	v_lshlrev_b32_e32 v9, 16, v19
	v_mul_f32_e32 v10, 0xbfb8aa3b, v9
	v_exp_f32_e32 v10, v10
	v_div_fixup_f32 v7, v7, v22, v18
	v_mul_f32_e32 v7, v7, v14
	v_cvt_pk_bf16_f32 v14, v6, v7
	v_add_f32_e32 v6, 1.0, v10
	v_div_scale_f32 v7, s[0:1], v6, v6, v9
	v_rcp_f32_e32 v10, v7
	v_and_b32_e32 v18, 0xffff0000, v19
	v_mul_f32_e32 v23, 0xbfb8aa3b, v18
	v_exp_f32_e32 v23, v23
	v_fma_f32 v19, -v7, v10, 1.0
	v_fmac_f32_e32 v10, v19, v10
	v_div_scale_f32 v19, vcc, v9, v6, v9
	v_mul_f32_e32 v22, v19, v10
	v_fma_f32 v24, -v7, v22, v19
	v_fmac_f32_e32 v22, v24, v10
	v_fma_f32 v7, -v7, v22, v19
	v_add_f32_e32 v19, 1.0, v23
	v_div_scale_f32 v23, s[0:1], v19, v19, v18
	v_rcp_f32_e32 v24, v23
	v_div_fmas_f32 v7, v7, v10, v22
	v_div_fixup_f32 v6, v7, v6, v9
	v_lshlrev_b32_e32 v11, 16, v15
	v_fma_f32 v7, -v23, v24, 1.0
	v_fmac_f32_e32 v24, v7, v24
	v_div_scale_f32 v7, vcc, v18, v19, v18
	v_mul_f32_e32 v9, v7, v24
	v_fma_f32 v10, -v23, v9, v7
	v_fmac_f32_e32 v9, v10, v24
	v_fma_f32 v7, -v23, v9, v7
	v_div_fmas_f32 v7, v7, v24, v9
	v_lshlrev_b32_e32 v9, 16, v20
	v_mul_f32_e32 v10, 0xbfb8aa3b, v9
	v_exp_f32_e32 v10, v10
	v_and_b32_e32 v15, 0xffff0000, v15
	v_mul_f32_e32 v6, v6, v11
	v_div_fixup_f32 v7, v7, v19, v18
	v_mul_f32_e32 v7, v7, v15
	v_cvt_pk_bf16_f32 v15, v6, v7
	v_add_f32_e32 v6, 1.0, v10
	v_div_scale_f32 v7, s[0:1], v6, v6, v9
	v_rcp_f32_e32 v10, v7
	v_and_b32_e32 v18, 0xffff0000, v20
	v_mul_f32_e32 v22, 0xbfb8aa3b, v18
	v_exp_f32_e32 v22, v22
	v_fma_f32 v19, -v7, v10, 1.0
	v_fmac_f32_e32 v10, v19, v10
	v_div_scale_f32 v19, vcc, v9, v6, v9
	v_mul_f32_e32 v20, v19, v10
	v_fma_f32 v23, -v7, v20, v19
	v_fmac_f32_e32 v20, v23, v10
	v_fma_f32 v7, -v7, v20, v19
	v_add_f32_e32 v19, 1.0, v22
	v_div_scale_f32 v22, s[0:1], v19, v19, v18
	v_rcp_f32_e32 v23, v22
	v_div_fmas_f32 v7, v7, v10, v20
	v_div_fixup_f32 v6, v7, v6, v9
	v_lshlrev_b32_e32 v11, 16, v16
	v_fma_f32 v7, -v22, v23, 1.0
	v_fmac_f32_e32 v23, v7, v23
	v_div_scale_f32 v7, vcc, v18, v19, v18
	v_mul_f32_e32 v9, v7, v23
	v_fma_f32 v10, -v22, v9, v7
	v_fmac_f32_e32 v9, v10, v23
	v_fma_f32 v7, -v22, v9, v7
	v_div_fmas_f32 v7, v7, v23, v9
	v_lshlrev_b32_e32 v9, 16, v21
	v_mul_f32_e32 v10, 0xbfb8aa3b, v9
	v_exp_f32_e32 v10, v10
	v_and_b32_e32 v16, 0xffff0000, v16
	v_mul_f32_e32 v6, v6, v11
	v_div_fixup_f32 v7, v7, v19, v18
	v_mul_f32_e32 v7, v7, v16
	v_cvt_pk_bf16_f32 v16, v6, v7
	v_add_f32_e32 v6, 1.0, v10
	v_div_scale_f32 v7, s[0:1], v6, v6, v9
	v_rcp_f32_e32 v10, v7
	v_and_b32_e32 v18, 0xffff0000, v21
	v_mul_f32_e32 v21, 0xbfb8aa3b, v18
	v_exp_f32_e32 v21, v21
	v_fma_f32 v19, -v7, v10, 1.0
	v_fmac_f32_e32 v10, v19, v10
	v_div_scale_f32 v19, vcc, v9, v6, v9
	v_mul_f32_e32 v20, v19, v10
	v_fma_f32 v22, -v7, v20, v19
	v_fmac_f32_e32 v20, v22, v10
	v_fma_f32 v7, -v7, v20, v19
	v_add_f32_e32 v19, 1.0, v21
	v_div_scale_f32 v21, s[0:1], v19, v19, v18
	v_rcp_f32_e32 v22, v21
	v_div_fmas_f32 v7, v7, v10, v20
	v_div_fixup_f32 v6, v7, v6, v9
	v_lshlrev_b32_e32 v11, 16, v17
	v_fma_f32 v7, -v21, v22, 1.0
	v_fmac_f32_e32 v22, v7, v22
	v_div_scale_f32 v7, vcc, v18, v19, v18
	v_mul_f32_e32 v9, v7, v22
	v_fma_f32 v10, -v21, v9, v7
	v_fmac_f32_e32 v9, v10, v22
	v_fma_f32 v7, -v21, v9, v7
	v_div_fmas_f32 v7, v7, v22, v9
	v_and_b32_e32 v17, 0xffff0000, v17
	v_mul_f32_e32 v6, v6, v11
	v_div_fixup_f32 v7, v7, v19, v18
	v_mul_f32_e32 v7, v7, v17
	v_cvt_pk_bf16_f32 v17, v6, v7
	v_or_b32_e32 v6, 24, v0
	v_mad_u64_u32 v[10:11], s[0:1], v6, s44, v[2:3]
	v_add_u32_e32 v11, v13, v11
	v_lshl_add_u64 v[10:11], v[10:11], 0, s[8:9]
	v_lshl_add_u64 v[10:11], v[10:11], 0, v[176:177]
	v_add_co_u32_e32 v10, vcc, s50, v10
	v_mov_b32_e32 v9, v1
	s_nop 0
	v_addc_co_u32_e32 v11, vcc, 0, v11, vcc
	s_nop 1
	v_mov_b64_e32 v[18:19], v[120:121]
	v_mov_b64_e32 v[20:21], v[122:123]
	v_lshlrev_b64 v[8:9], 12, v[8:9]
	v_lshl_add_u64 v[8:9], v[4:5], 0, v[8:9]
	global_store_dwordx4 v[8:9], v[14:17], off
	v_or_b32_e32 v0, 28, v0
	v_mad_u64_u32 v[2:3], s[0:1], v0, s44, v[2:3]
	v_add_u32_e32 v3, v13, v3
	v_lshl_add_u64 v[2:3], v[2:3], 0, s[8:9]
	v_lshl_add_u64 v[2:3], v[2:3], 0, v[176:177]
	s_nop 0
	v_lshlrev_b32_e32 v7, 16, v18
	v_mul_f32_e32 v10, 0xbfb8aa3b, v7
	v_exp_f32_e32 v22, v10
	v_and_b32_e32 v18, 0xffff0000, v18
	v_mul_f32_e32 v24, 0xbfb8aa3b, v18
	v_exp_f32_e32 v24, v24
	v_add_f32_e32 v14, 1.0, v22
	v_div_scale_f32 v15, s[0:1], v14, v14, v7
	v_rcp_f32_e32 v16, v15
	ds_read_b128 v[8:11], v12 offset:6528
	v_fma_f32 v22, -v15, v16, 1.0
	v_fmac_f32_e32 v16, v22, v16
	v_div_scale_f32 v22, vcc, v7, v14, v7
	v_mul_f32_e32 v23, v22, v16
	v_fma_f32 v25, -v15, v23, v22
	v_fmac_f32_e32 v23, v25, v16
	v_fma_f32 v15, -v15, v23, v22
	v_add_f32_e32 v22, 1.0, v24
	v_div_scale_f32 v24, s[0:1], v22, v22, v18
	v_rcp_f32_e32 v25, v24
	v_div_fmas_f32 v15, v15, v16, v23
	v_div_fixup_f32 v7, v15, v14, v7
	s_waitcnt lgkmcnt(0)
; __device__ __forceinline__ void attn_unit(const bf16* __restrict__ P, unsigned short* __restrict__ Ob, int b, int h, int kvh, int qb, bool meta, int jt0, int ntl, float* part, unsigned* cnt, const float* __restrict__ qnw, const float2* __restrict__ rtab, char* lds) {
;     ...
;     for (int i = 0; i < 8; ++i) { const int cidx = lane + 64 * i, orow = cidx >> 4, c8 = (cidx & 15) * 8;
;       const u32x4 ov = *(const u32x4*)(stg + orow * 272 + c8 * 2);
;       const u32x4 gv = *(const u32x4*)(Pg + (grow0 + orow) * LD + 4096 + h * D + c8);
;       const unsigned ow[4] = {ov.x, ov.y, ov.z, ov.w}, gw[4] = {gv.x, gv.y, gv.z, gv.w}; unsigned res[4];
; #pragma unroll
;       for (int e = 0; e < 4; ++e) { const float o0 = __uint_as_float(ow[e] << 16), o1 = __uint_as_float(ow[e] & 0xffff0000u), g0 = __uint_as_float(gw[e] << 16), g1 = __uint_as_float(gw[e] & 0xffff0000u);
;         res[e] = cvtpk(o0 * (g0 / (1.f + __expf(-g0))), o1 * (g1 / (1.f + __expf(-g1)))); }
;       *(u32x4*)(Ob + (grow0 + orow) * 2048 + h * D + c8) = (u32x4){res[0], res[1], res[2], res[3]}; }
	v_lshlrev_b32_e32 v17, 16, v8
	v_fma_f32 v14, -v24, v25, 1.0
	v_fmac_f32_e32 v25, v14, v25
	v_div_scale_f32 v14, vcc, v18, v22, v18
	v_mul_f32_e32 v15, v14, v25
	v_fma_f32 v16, -v24, v15, v14
	v_fmac_f32_e32 v15, v16, v25
	v_fma_f32 v14, -v24, v15, v14
	v_div_fmas_f32 v14, v14, v25, v15
	v_lshlrev_b32_e32 v15, 16, v19
	v_mul_f32_e32 v16, 0xbfb8aa3b, v15
	v_exp_f32_e32 v16, v16
	v_and_b32_e32 v8, 0xffff0000, v8
	v_div_fixup_f32 v14, v14, v22, v18
	v_mul_f32_e32 v7, v7, v17
	v_mul_f32_e32 v8, v14, v8
	v_cvt_pk_bf16_f32 v8, v7, v8
	v_add_f32_e32 v7, 1.0, v16
	v_div_scale_f32 v14, s[0:1], v7, v7, v15
	v_rcp_f32_e32 v16, v14
	v_and_b32_e32 v18, 0xffff0000, v19
	v_mul_f32_e32 v23, 0xbfb8aa3b, v18
	v_exp_f32_e32 v23, v23
	v_fma_f32 v19, -v14, v16, 1.0
	v_fmac_f32_e32 v16, v19, v16
	v_div_scale_f32 v19, vcc, v15, v7, v15
	v_mul_f32_e32 v22, v19, v16
	v_fma_f32 v24, -v14, v22, v19
	v_fmac_f32_e32 v22, v24, v16
	v_fma_f32 v14, -v14, v22, v19
	v_add_f32_e32 v19, 1.0, v23
	v_div_scale_f32 v23, s[0:1], v19, v19, v18
	v_rcp_f32_e32 v24, v23
	v_div_fmas_f32 v14, v14, v16, v22
	v_div_fixup_f32 v7, v14, v7, v15
	v_lshlrev_b32_e32 v17, 16, v9
	v_fma_f32 v14, -v23, v24, 1.0
	v_fmac_f32_e32 v24, v14, v24
	v_div_scale_f32 v14, vcc, v18, v19, v18
	v_mul_f32_e32 v15, v14, v24
	v_fma_f32 v16, -v23, v15, v14
	v_fmac_f32_e32 v15, v16, v24
	v_fma_f32 v14, -v23, v15, v14
	v_div_fmas_f32 v14, v14, v24, v15
	v_lshlrev_b32_e32 v15, 16, v20
	v_mul_f32_e32 v16, 0xbfb8aa3b, v15
	v_exp_f32_e32 v16, v16
	v_and_b32_e32 v9, 0xffff0000, v9
	v_div_fixup_f32 v14, v14, v19, v18
	v_mul_f32_e32 v7, v7, v17
	v_mul_f32_e32 v9, v14, v9
	v_cvt_pk_bf16_f32 v9, v7, v9
	v_add_f32_e32 v7, 1.0, v16
	v_div_scale_f32 v14, s[0:1], v7, v7, v15
	v_rcp_f32_e32 v16, v14
	v_and_b32_e32 v18, 0xffff0000, v20
	v_mul_f32_e32 v22, 0xbfb8aa3b, v18
	v_exp_f32_e32 v22, v22
	v_fma_f32 v19, -v14, v16, 1.0
	v_fmac_f32_e32 v16, v19, v16
	v_div_scale_f32 v19, vcc, v15, v7, v15
	v_mul_f32_e32 v20, v19, v16
	v_fma_f32 v23, -v14, v20, v19
	v_fmac_f32_e32 v20, v23, v16
	v_fma_f32 v14, -v14, v20, v19
	v_add_f32_e32 v19, 1.0, v22
	v_div_scale_f32 v22, s[0:1], v19, v19, v18
	v_rcp_f32_e32 v23, v22
	v_div_fmas_f32 v14, v14, v16, v20
	v_div_fixup_f32 v7, v14, v7, v15
	v_lshlrev_b32_e32 v17, 16, v10
	v_fma_f32 v14, -v22, v23, 1.0
	v_fmac_f32_e32 v23, v14, v23
	v_div_scale_f32 v14, vcc, v18, v19, v18
	v_mul_f32_e32 v15, v14, v23
	v_fma_f32 v16, -v22, v15, v14
	v_fmac_f32_e32 v15, v16, v23
	v_fma_f32 v14, -v22, v15, v14
	v_div_fmas_f32 v14, v14, v23, v15
	v_lshlrev_b32_e32 v15, 16, v21
	v_mul_f32_e32 v16, 0xbfb8aa3b, v15
	v_exp_f32_e32 v16, v16
	v_and_b32_e32 v10, 0xffff0000, v10
	v_div_fixup_f32 v14, v14, v19, v18
	v_mul_f32_e32 v7, v7, v17
	v_mul_f32_e32 v10, v14, v10
	v_cvt_pk_bf16_f32 v10, v7, v10
	v_add_f32_e32 v7, 1.0, v16
	v_div_scale_f32 v14, s[0:1], v7, v7, v15
	v_rcp_f32_e32 v16, v14
	v_and_b32_e32 v18, 0xffff0000, v21
	v_mul_f32_e32 v21, 0xbfb8aa3b, v18
	v_exp_f32_e32 v21, v21
	v_fma_f32 v19, -v14, v16, 1.0
	v_fmac_f32_e32 v16, v19, v16
	v_div_scale_f32 v19, vcc, v15, v7, v15
	v_mul_f32_e32 v20, v19, v16
	v_fma_f32 v22, -v14, v20, v19
	v_fmac_f32_e32 v20, v22, v16
	v_fma_f32 v14, -v14, v20, v19
	v_add_f32_e32 v19, 1.0, v21
	v_div_scale_f32 v21, s[0:1], v19, v19, v18
	v_rcp_f32_e32 v22, v21
	v_div_fmas_f32 v14, v14, v16, v20
	v_div_fixup_f32 v7, v14, v7, v15
	v_lshlrev_b32_e32 v17, 16, v11
	v_fma_f32 v14, -v21, v22, 1.0
	v_fmac_f32_e32 v22, v14, v22
	v_div_scale_f32 v14, vcc, v18, v19, v18
	v_mul_f32_e32 v15, v14, v22
	v_fma_f32 v16, -v21, v15, v14
	v_fmac_f32_e32 v15, v16, v22
	v_fma_f32 v14, -v21, v15, v14
	v_div_fmas_f32 v14, v14, v22, v15
	v_and_b32_e32 v11, 0xffff0000, v11
	v_div_fixup_f32 v14, v14, v19, v18
	v_add_co_u32_e32 v2, vcc, s50, v2
	v_mul_f32_e32 v11, v14, v11
	s_nop 0
	v_addc_co_u32_e32 v3, vcc, 0, v3, vcc
	v_mul_f32_e32 v7, v7, v17
	v_cvt_pk_bf16_f32 v11, v7, v11
	s_nop 1
	v_mov_b64_e32 v[14:15], v[124:125]
	v_mov_b64_e32 v[16:17], v[126:127]
	v_mov_b32_e32 v7, v1
	v_lshlrev_b64 v[2:3], 12, v[6:7]
	v_lshl_add_u64 v[2:3], v[4:5], 0, v[2:3]
	global_store_dwordx4 v[2:3], v[8:11], off
	v_lshlrev_b64 v[0:1], 12, v[0:1]
	v_lshl_add_u64 v[0:1], v[4:5], 0, v[0:1]
	s_nop 0
	v_lshlrev_b32_e32 v13, 16, v14
	v_mul_f32_e32 v6, 0xbfb8aa3b, v13
	v_exp_f32_e32 v18, v6
	ds_read_b128 v[6:9], v12 offset:7616
	v_and_b32_e32 v12, 0xffff0000, v14
	v_mul_f32_e32 v19, 0xbfb8aa3b, v12
	v_add_f32_e32 v2, 1.0, v18
	v_div_scale_f32 v3, s[0:1], v2, v2, v13
	v_rcp_f32_e32 v10, v3
	v_exp_f32_e32 v19, v19
	s_waitcnt lgkmcnt(0)
; __device__ __forceinline__ void attn_unit(const bf16* __restrict__ P, unsigned short* __restrict__ Ob, int b, int h, int kvh, int qb, bool meta, int jt0, int ntl, float* part, unsigned* cnt, const float* __restrict__ qnw, const float2* __restrict__ rtab, char* lds) {
;     ...
;     for (int i = 0; i < 8; ++i) { const int cidx = lane + 64 * i, orow = cidx >> 4, c8 = (cidx & 15) * 8;
;       const u32x4 ov = *(const u32x4*)(stg + orow * 272 + c8 * 2);
;       const u32x4 gv = *(const u32x4*)(Pg + (grow0 + orow) * LD + 4096 + h * D + c8);
;       const unsigned ow[4] = {ov.x, ov.y, ov.z, ov.w}, gw[4] = {gv.x, gv.y, gv.z, gv.w}; unsigned res[4];
; #pragma unroll
;       for (int e = 0; e < 4; ++e) { const float o0 = __uint_as_float(ow[e] << 16), o1 = __uint_as_float(ow[e] & 0xffff0000u), g0 = __uint_as_float(gw[e] << 16), g1 = __uint_as_float(gw[e] & 0xffff0000u);
;         res[e] = cvtpk(o0 * (g0 / (1.f + __expf(-g0))), o1 * (g1 / (1.f + __expf(-g1)))); }
;       *(u32x4*)(Ob + (grow0 + orow) * 2048 + h * D + c8) = (u32x4){res[0], res[1], res[2], res[3]}; }
;     ...
;   __syncthreads();
	v_lshlrev_b32_e32 v11, 16, v6
	v_and_b32_e32 v6, 0xffff0000, v6
	v_fma_f32 v14, -v3, v10, 1.0
	v_fmac_f32_e32 v10, v14, v10
	v_div_scale_f32 v14, vcc, v13, v2, v13
	v_mul_f32_e32 v18, v14, v10
	v_fma_f32 v20, -v3, v18, v14
	v_fmac_f32_e32 v18, v20, v10
	v_fma_f32 v3, -v3, v18, v14
	v_add_f32_e32 v14, 1.0, v19
	v_div_scale_f32 v19, s[0:1], v14, v14, v12
	v_rcp_f32_e32 v20, v19
	v_div_fmas_f32 v3, v3, v10, v18
	v_div_fixup_f32 v2, v3, v2, v13
	v_mul_f32_e32 v2, v2, v11
	v_fma_f32 v3, -v19, v20, 1.0
	v_fmac_f32_e32 v20, v3, v20
	v_div_scale_f32 v3, vcc, v12, v14, v12
	v_mul_f32_e32 v10, v3, v20
	v_fma_f32 v11, -v19, v10, v3
	v_fmac_f32_e32 v10, v11, v20
	v_fma_f32 v3, -v19, v10, v3
	v_div_fmas_f32 v3, v3, v20, v10
	v_lshlrev_b32_e32 v10, 16, v15
	v_mul_f32_e32 v11, 0xbfb8aa3b, v10
	v_exp_f32_e32 v11, v11
	v_div_fixup_f32 v3, v3, v14, v12
	v_mul_f32_e32 v3, v3, v6
	v_cvt_pk_bf16_f32 v6, v2, v3
	v_add_f32_e32 v2, 1.0, v11
	v_div_scale_f32 v3, s[0:1], v2, v2, v10
	v_rcp_f32_e32 v11, v3
	v_and_b32_e32 v13, 0xffff0000, v15
	v_mul_f32_e32 v18, 0xbfb8aa3b, v13
	v_exp_f32_e32 v18, v18
	v_fma_f32 v14, -v3, v11, 1.0
	v_fmac_f32_e32 v11, v14, v11
	v_div_scale_f32 v14, vcc, v10, v2, v10
	v_mul_f32_e32 v15, v14, v11
	v_fma_f32 v19, -v3, v15, v14
	v_fmac_f32_e32 v15, v19, v11
	v_fma_f32 v3, -v3, v15, v14
	v_add_f32_e32 v14, 1.0, v18
	v_div_scale_f32 v18, s[0:1], v14, v14, v13
	v_rcp_f32_e32 v19, v18
	v_div_fmas_f32 v3, v3, v11, v15
	v_div_fixup_f32 v2, v3, v2, v10
	v_lshlrev_b32_e32 v12, 16, v7
	v_fma_f32 v3, -v18, v19, 1.0
	v_fmac_f32_e32 v19, v3, v19
	v_div_scale_f32 v3, vcc, v13, v14, v13
	v_mul_f32_e32 v10, v3, v19
	v_fma_f32 v11, -v18, v10, v3
	v_fmac_f32_e32 v10, v11, v19
	v_fma_f32 v3, -v18, v10, v3
	v_div_fmas_f32 v3, v3, v19, v10
	v_lshlrev_b32_e32 v10, 16, v16
	v_mul_f32_e32 v11, 0xbfb8aa3b, v10
	v_exp_f32_e32 v11, v11
	v_and_b32_e32 v7, 0xffff0000, v7
	v_mul_f32_e32 v2, v2, v12
	v_div_fixup_f32 v3, v3, v14, v13
	v_mul_f32_e32 v3, v3, v7
	v_cvt_pk_bf16_f32 v7, v2, v3
	v_add_f32_e32 v2, 1.0, v11
	v_div_scale_f32 v3, s[0:1], v2, v2, v10
	v_rcp_f32_e32 v11, v3
	v_and_b32_e32 v13, 0xffff0000, v16
	v_mul_f32_e32 v16, 0xbfb8aa3b, v13
	v_exp_f32_e32 v16, v16
	v_fma_f32 v14, -v3, v11, 1.0
	v_fmac_f32_e32 v11, v14, v11
	v_div_scale_f32 v14, vcc, v10, v2, v10
	v_mul_f32_e32 v15, v14, v11
	v_fma_f32 v18, -v3, v15, v14
	v_fmac_f32_e32 v15, v18, v11
	v_fma_f32 v3, -v3, v15, v14
	v_add_f32_e32 v14, 1.0, v16
	v_div_scale_f32 v16, s[0:1], v14, v14, v13
	v_rcp_f32_e32 v18, v16
	v_div_fmas_f32 v3, v3, v11, v15
	v_div_fixup_f32 v2, v3, v2, v10
	v_lshlrev_b32_e32 v12, 16, v8
	v_fma_f32 v3, -v16, v18, 1.0
	v_fmac_f32_e32 v18, v3, v18
	v_div_scale_f32 v3, vcc, v13, v14, v13
	v_mul_f32_e32 v10, v3, v18
	v_fma_f32 v11, -v16, v10, v3
	v_fmac_f32_e32 v10, v11, v18
	v_fma_f32 v3, -v16, v10, v3
	v_div_fmas_f32 v3, v3, v18, v10
	v_lshlrev_b32_e32 v10, 16, v17
	v_mul_f32_e32 v11, 0xbfb8aa3b, v10
	v_exp_f32_e32 v11, v11
	v_and_b32_e32 v8, 0xffff0000, v8
	v_mul_f32_e32 v2, v2, v12
	v_div_fixup_f32 v3, v3, v14, v13
	v_mul_f32_e32 v3, v3, v8
	v_cvt_pk_bf16_f32 v8, v2, v3
	v_add_f32_e32 v2, 1.0, v11
	v_div_scale_f32 v3, s[0:1], v2, v2, v10
	v_rcp_f32_e32 v11, v3
	v_and_b32_e32 v13, 0xffff0000, v17
	v_mul_f32_e32 v16, 0xbfb8aa3b, v13
	v_exp_f32_e32 v16, v16
	v_fma_f32 v14, -v3, v11, 1.0
	v_fmac_f32_e32 v11, v14, v11
	v_div_scale_f32 v14, vcc, v10, v2, v10
	v_mul_f32_e32 v15, v14, v11
	v_fma_f32 v17, -v3, v15, v14
	v_fmac_f32_e32 v15, v17, v11
	v_fma_f32 v3, -v3, v15, v14
	v_add_f32_e32 v14, 1.0, v16
	v_div_scale_f32 v16, s[0:1], v14, v14, v13
	v_rcp_f32_e32 v17, v16
	v_div_fmas_f32 v3, v3, v11, v15
	v_div_fixup_f32 v2, v3, v2, v10
	v_lshlrev_b32_e32 v12, 16, v9
	v_fma_f32 v3, -v16, v17, 1.0
	v_fmac_f32_e32 v17, v3, v17
	v_div_scale_f32 v3, vcc, v13, v14, v13
	v_mul_f32_e32 v10, v3, v17
	v_fma_f32 v11, -v16, v10, v3
	v_fmac_f32_e32 v10, v11, v17
	v_fma_f32 v3, -v16, v10, v3
	v_div_fmas_f32 v3, v3, v17, v10
	v_and_b32_e32 v9, 0xffff0000, v9
	v_div_fixup_f32 v3, v3, v14, v13
	v_mul_f32_e32 v2, v2, v12
	v_mul_f32_e32 v3, v3, v9
	v_cvt_pk_bf16_f32 v9, v2, v3
	global_store_dwordx4 v[0:1], v[6:9], off
	s_barrier

; __device__ __forceinline__ int crow(int r, int hi) { return (r & 3) + 8 * (r >> 2) + 4 * hi; }
; __device__ __forceinline__ unsigned short f2bf(float f) { unsigned u = __float_as_uint(f); return (unsigned short)((u + 0x7fffu + ((u >> 16) & 1u)) >> 16); }
; __device__ __forceinline__ unsigned f2bf(float f) { return pk2(f, 0.f) & 0xffffu; }
; __device__ __forceinline__ void attn_unit(const bf16* __restrict__ P, unsigned short* __restrict__ Ob, int b, int h, int kvh, int qb, bool meta, int jt0, int ntl, float* part, unsigned* cnt, const float* __restrict__ qnw, const float2* __restrict__ rtab, char* lds) {
;     ...
;     if (hi == 0) li_l[r32] = l_reg; asm volatile("s_waitcnt lgkmcnt(0)" ::: "memory");
;     float rli[16];
; #pragma unroll
;     for (int r = 0; r < 16; ++r) rli[r] = __builtin_amdgcn_rcpf(li_l[crow(r, hi)]);
;     char* stg = lds + 2 * SHM_V + 2 * SHM_K + NW * 64 * 4 + wid * (32 * 272);
; #pragma unroll
;     for (int r = 0; r < 16; ++r) { const int orow = crow(r, hi);
; #pragma unroll
;       for (int d0 = 0; d0 < 4; ++d0) *(unsigned short*)(stg + orow * 272 + (d0 * 32 + r32) * 2) = f2bf(o[d0][r] * rli[r]); }
.LBB0_1234:
	s_or_b64 exec, exec, s[0:1]
	s_waitcnt lgkmcnt(0)
	v_add_u32_e32 v72, v195, v180
	ds_read_b128 v[64:67], v72
	ds_read_b128 v[68:71], v72 offset:32
	v_lshlrev_b32_e32 v81, 1, v193
	v_mul_u32_u24_e32 v82, 0x440, v194
	s_lshl_b32 s64, s38, 1
	s_waitcnt lgkmcnt(1)
	v_rcp_f32_e32 v73, v64
	v_rcp_f32_e32 v74, v65
	v_rcp_f32_e32 v75, v66
	v_rcp_f32_e32 v76, v67
	s_waitcnt lgkmcnt(0)
	v_rcp_f32_e32 v77, v68
	ds_read_b128 v[64:67], v72 offset:64
	v_rcp_f32_e32 v78, v69
	v_rcp_f32_e32 v79, v70
	v_rcp_f32_e32 v80, v71
	ds_read_b128 v[68:71], v72 offset:96
	v_mul_lo_u32 v72, v192, s96
	v_add_u32_e32 v72, s97, v72
	v_mul_f32_e32 v0, v0, v73
	v_add3_u32 v81, v72, v81, v82
	v_bfe_u32 v82, v0, 16, 1
	v_add3_u32 v0, v0, v82, s61
	ds_write_b16_d16_hi v81, v0
	v_mul_f32_e32 v0, v48, v73
	v_bfe_u32 v48, v0, 16, 1
	v_add3_u32 v0, v0, v48, s61
	ds_write_b16_d16_hi v81, v0 offset:64
	v_mul_f32_e32 v0, v32, v73
	v_bfe_u32 v32, v0, 16, 1
	v_add3_u32 v0, v0, v32, s61
	ds_write_b16_d16_hi v81, v0 offset:128
	v_mul_f32_e32 v0, v16, v73
	v_bfe_u32 v16, v0, 16, 1
	v_add3_u32 v0, v0, v16, s61
	ds_write_b16_d16_hi v81, v0 offset:192
	v_mul_f32_e32 v0, v1, v74
	v_bfe_u32 v1, v0, 16, 1
	v_add3_u32 v0, v0, v1, s61
	ds_write_b16_d16_hi v81, v0 offset:272
	v_mul_f32_e32 v0, v49, v74
	v_bfe_u32 v1, v0, 16, 1
	v_add3_u32 v0, v0, v1, s61
	ds_write_b16_d16_hi v81, v0 offset:336
	v_mul_f32_e32 v0, v33, v74
	v_bfe_u32 v1, v0, 16, 1
	v_add3_u32 v0, v0, v1, s61
	ds_write_b16_d16_hi v81, v0 offset:400
	v_mul_f32_e32 v0, v17, v74
	v_bfe_u32 v1, v0, 16, 1
	v_add3_u32 v0, v0, v1, s61
	ds_write_b16_d16_hi v81, v0 offset:464
	v_mul_f32_e32 v0, v2, v75
	v_bfe_u32 v1, v0, 16, 1
	v_add3_u32 v0, v0, v1, s61
	ds_write_b16_d16_hi v81, v0 offset:544
	v_mul_f32_e32 v0, v50, v75
	v_bfe_u32 v1, v0, 16, 1
	v_add3_u32 v0, v0, v1, s61
	ds_write_b16_d16_hi v81, v0 offset:608
	v_mul_f32_e32 v0, v34, v75
	v_bfe_u32 v1, v0, 16, 1
	v_add3_u32 v0, v0, v1, s61
	ds_write_b16_d16_hi v81, v0 offset:672
	v_mul_f32_e32 v0, v18, v75
	v_bfe_u32 v1, v0, 16, 1
	v_add3_u32 v0, v0, v1, s61
	ds_write_b16_d16_hi v81, v0 offset:736
	v_mul_f32_e32 v0, v3, v76
	v_bfe_u32 v1, v0, 16, 1
	v_add3_u32 v0, v0, v1, s61
	ds_write_b16_d16_hi v81, v0 offset:816
	v_mul_f32_e32 v0, v51, v76
	v_bfe_u32 v1, v0, 16, 1
	v_add3_u32 v0, v0, v1, s61
	ds_write_b16_d16_hi v81, v0 offset:880
	v_mul_f32_e32 v0, v35, v76
	v_bfe_u32 v1, v0, 16, 1
	v_add3_u32 v0, v0, v1, s61
	ds_write_b16_d16_hi v81, v0 offset:944
	v_mul_f32_e32 v0, v19, v76
	v_bfe_u32 v1, v0, 16, 1
	v_add3_u32 v0, v0, v1, s61
	ds_write_b16_d16_hi v81, v0 offset:1008
	v_mul_f32_e32 v0, v4, v77
	v_bfe_u32 v1, v0, 16, 1
	v_add3_u32 v0, v0, v1, s61
	ds_write_b16_d16_hi v81, v0 offset:2176
	v_mul_f32_e32 v0, v52, v77
	v_bfe_u32 v1, v0, 16, 1
	v_add3_u32 v0, v0, v1, s61
	ds_write_b16_d16_hi v81, v0 offset:2240
	v_mul_f32_e32 v0, v36, v77
	v_bfe_u32 v1, v0, 16, 1
	v_add3_u32 v0, v0, v1, s61
	ds_write_b16_d16_hi v81, v0 offset:2304
	v_mul_f32_e32 v0, v20, v77
	v_bfe_u32 v1, v0, 16, 1
	v_add3_u32 v0, v0, v1, s61
	ds_write_b16_d16_hi v81, v0 offset:2368
	v_mul_f32_e32 v0, v5, v78
	v_bfe_u32 v1, v0, 16, 1
	v_add3_u32 v0, v0, v1, s61
	ds_write_b16_d16_hi v81, v0 offset:2448
	v_mul_f32_e32 v0, v53, v78
	v_bfe_u32 v1, v0, 16, 1
	v_add3_u32 v0, v0, v1, s61
	ds_write_b16_d16_hi v81, v0 offset:2512
	v_mul_f32_e32 v0, v37, v78
	v_bfe_u32 v1, v0, 16, 1
	v_add3_u32 v0, v0, v1, s61
	ds_write_b16_d16_hi v81, v0 offset:2576
	v_mul_f32_e32 v0, v21, v78
	v_bfe_u32 v1, v0, 16, 1
	v_add3_u32 v0, v0, v1, s61
	ds_write_b16_d16_hi v81, v0 offset:2640
	v_mul_f32_e32 v0, v6, v79
	v_bfe_u32 v1, v0, 16, 1
	v_add3_u32 v0, v0, v1, s61
	ds_write_b16_d16_hi v81, v0 offset:2720
	v_mul_f32_e32 v0, v54, v79
	v_bfe_u32 v1, v0, 16, 1
	v_add3_u32 v0, v0, v1, s61
	ds_write_b16_d16_hi v81, v0 offset:2784
	v_mul_f32_e32 v0, v38, v79
	v_bfe_u32 v1, v0, 16, 1
	v_add3_u32 v0, v0, v1, s61
	ds_write_b16_d16_hi v81, v0 offset:2848
	v_mul_f32_e32 v0, v22, v79
	v_bfe_u32 v1, v0, 16, 1
	v_add3_u32 v0, v0, v1, s61
	ds_write_b16_d16_hi v81, v0 offset:2912
	v_mul_f32_e32 v0, v7, v80
	v_bfe_u32 v1, v0, 16, 1
	v_add3_u32 v0, v0, v1, s61
	ds_write_b16_d16_hi v81, v0 offset:2992
	v_mul_f32_e32 v0, v55, v80
	v_bfe_u32 v1, v0, 16, 1
	v_add3_u32 v0, v0, v1, s61
	ds_write_b16_d16_hi v81, v0 offset:3056
	v_mul_f32_e32 v0, v39, v80
	v_bfe_u32 v1, v0, 16, 1
	s_waitcnt lgkmcnt(14)
; __device__ __forceinline__ int crow(int r, int hi) { return (r & 3) + 8 * (r >> 2) + 4 * hi; }
; __device__ __forceinline__ unsigned short f2bf(float f) { unsigned u = __float_as_uint(f); return (unsigned short)((u + 0x7fffu + ((u >> 16) & 1u)) >> 16); }
; __device__ __forceinline__ unsigned f2bf(float f) { return pk2(f, 0.f) & 0xffffu; }
; __device__ __forceinline__ void attn_unit(const bf16* __restrict__ P, unsigned short* __restrict__ Ob, int b, int h, int kvh, int qb, bool meta, int jt0, int ntl, float* part, unsigned* cnt, const float* __restrict__ qnw, const float2* __restrict__ rtab, char* lds) {
;     ...
;     for (int r = 0; r < 16; ++r) rli[r] = __builtin_amdgcn_rcpf(li_l[crow(r, hi)]);
;     char* stg = lds + 2 * SHM_V + 2 * SHM_K + NW * 64 * 4 + wid * (32 * 272);
; #pragma unroll
;     for (int r = 0; r < 16; ++r) { const int orow = crow(r, hi);
; #pragma unroll
;       for (int d0 = 0; d0 < 4; ++d0) *(unsigned short*)(stg + orow * 272 + (d0 * 32 + r32) * 2) = f2bf(o[d0][r] * rli[r]); }
;     asm volatile("s_waitcnt lgkmcnt(0)" ::: "memory");
;     const long grow0 = (long)b * 4096 + qb * 256 + wid * QBLK;
; #pragma unroll
;     for (int i = 0; i < 8; ++i) { const int cidx = lane + 64 * i, orow = cidx >> 4, c8 = (cidx & 15) * 8;
;       const u32x4 ov = *(const u32x4*)(stg + orow * 272 + c8 * 2);
;       const u32x4 gv = *(const u32x4*)(Pg + (grow0 + orow) * LD + 4096 + h * D + c8);
	v_rcp_f32_e32 v64, v64
	v_add3_u32 v0, v0, v1, s61
	ds_write_b16_d16_hi v81, v0 offset:3120
	v_mul_f32_e32 v0, v23, v80
	v_bfe_u32 v1, v0, 16, 1
	v_add3_u32 v0, v0, v1, s61
	ds_write_b16_d16_hi v81, v0 offset:3184
	v_mul_f32_e32 v0, v8, v64
	v_bfe_u32 v1, v0, 16, 1
	v_add3_u32 v0, v0, v1, s61
	ds_write_b16_d16_hi v81, v0 offset:4352
	v_mul_f32_e32 v0, v56, v64
	v_bfe_u32 v1, v0, 16, 1
	v_add3_u32 v0, v0, v1, s61
	ds_write_b16_d16_hi v81, v0 offset:4416
	v_mul_f32_e32 v0, v40, v64
	v_bfe_u32 v1, v0, 16, 1
	v_rcp_f32_e32 v65, v65
	v_add3_u32 v0, v0, v1, s61
	ds_write_b16_d16_hi v81, v0 offset:4480
	v_mul_f32_e32 v0, v24, v64
	v_bfe_u32 v1, v0, 16, 1
	v_add3_u32 v0, v0, v1, s61
	ds_write_b16_d16_hi v81, v0 offset:4544
	v_mul_f32_e32 v0, v9, v65
	v_bfe_u32 v1, v0, 16, 1
	v_add3_u32 v0, v0, v1, s61
	ds_write_b16_d16_hi v81, v0 offset:4624
	v_mul_f32_e32 v0, v57, v65
	v_bfe_u32 v1, v0, 16, 1
	v_add3_u32 v0, v0, v1, s61
	ds_write_b16_d16_hi v81, v0 offset:4688
	v_mul_f32_e32 v0, v41, v65
	v_bfe_u32 v1, v0, 16, 1
	v_rcp_f32_e32 v66, v66
	v_add3_u32 v0, v0, v1, s61
	ds_write_b16_d16_hi v81, v0 offset:4752
	v_mul_f32_e32 v0, v25, v65
	v_bfe_u32 v1, v0, 16, 1
	v_add3_u32 v0, v0, v1, s61
	ds_write_b16_d16_hi v81, v0 offset:4816
	v_mul_f32_e32 v0, v10, v66
	v_bfe_u32 v1, v0, 16, 1
	v_add3_u32 v0, v0, v1, s61
	ds_write_b16_d16_hi v81, v0 offset:4896
	v_mul_f32_e32 v0, v58, v66
	v_bfe_u32 v1, v0, 16, 1
	v_add3_u32 v0, v0, v1, s61
	ds_write_b16_d16_hi v81, v0 offset:4960
	v_mul_f32_e32 v0, v42, v66
	v_bfe_u32 v1, v0, 16, 1
	v_rcp_f32_e32 v67, v67
	v_add3_u32 v0, v0, v1, s61
	ds_write_b16_d16_hi v81, v0 offset:5024
	v_mul_f32_e32 v0, v26, v66
	v_bfe_u32 v1, v0, 16, 1
	v_add3_u32 v0, v0, v1, s61
	ds_write_b16_d16_hi v81, v0 offset:5088
	v_mul_f32_e32 v0, v11, v67
	v_bfe_u32 v1, v0, 16, 1
	v_add3_u32 v0, v0, v1, s61
	ds_write_b16_d16_hi v81, v0 offset:5168
	v_mul_f32_e32 v0, v59, v67
	v_bfe_u32 v1, v0, 16, 1
	v_add3_u32 v0, v0, v1, s61
	ds_write_b16_d16_hi v81, v0 offset:5232
	v_mul_f32_e32 v0, v43, v67
	v_bfe_u32 v1, v0, 16, 1
	v_rcp_f32_e32 v68, v68
	v_add3_u32 v0, v0, v1, s61
	ds_write_b16_d16_hi v81, v0 offset:5296
	v_mul_f32_e32 v0, v27, v67
	v_bfe_u32 v1, v0, 16, 1
	v_add3_u32 v0, v0, v1, s61
	ds_write_b16_d16_hi v81, v0 offset:5360
	v_mul_f32_e32 v0, v12, v68
	v_bfe_u32 v1, v0, 16, 1
	v_add3_u32 v0, v0, v1, s61
	ds_write_b16_d16_hi v81, v0 offset:6528
	v_mul_f32_e32 v0, v60, v68
	v_bfe_u32 v1, v0, 16, 1
	v_add3_u32 v0, v0, v1, s61
	ds_write_b16_d16_hi v81, v0 offset:6592
	v_mul_f32_e32 v0, v44, v68
	v_bfe_u32 v1, v0, 16, 1
	v_rcp_f32_e32 v69, v69
	v_add3_u32 v0, v0, v1, s61
	ds_write_b16_d16_hi v81, v0 offset:6656
	v_mul_f32_e32 v0, v28, v68
	v_bfe_u32 v1, v0, 16, 1
	v_add3_u32 v0, v0, v1, s61
	ds_write_b16_d16_hi v81, v0 offset:6720
	v_mul_f32_e32 v0, v13, v69
	v_bfe_u32 v1, v0, 16, 1
	v_add3_u32 v0, v0, v1, s61
	ds_write_b16_d16_hi v81, v0 offset:6800
	v_mul_f32_e32 v0, v61, v69
	v_bfe_u32 v1, v0, 16, 1
	v_add3_u32 v0, v0, v1, s61
	ds_write_b16_d16_hi v81, v0 offset:6864
	v_mul_f32_e32 v0, v45, v69
	v_bfe_u32 v1, v0, 16, 1
	v_rcp_f32_e32 v70, v70
	v_add3_u32 v0, v0, v1, s61
	ds_write_b16_d16_hi v81, v0 offset:6928
	v_mul_f32_e32 v0, v29, v69
	v_bfe_u32 v1, v0, 16, 1
	v_add3_u32 v0, v0, v1, s61
	ds_write_b16_d16_hi v81, v0 offset:6992
	v_mul_f32_e32 v0, v14, v70
	v_bfe_u32 v1, v0, 16, 1
	v_add3_u32 v0, v0, v1, s61
	ds_write_b16_d16_hi v81, v0 offset:7072
	v_mul_f32_e32 v0, v62, v70
	v_bfe_u32 v1, v0, 16, 1
	v_add3_u32 v0, v0, v1, s61
	ds_write_b16_d16_hi v81, v0 offset:7136
	v_mul_f32_e32 v0, v46, v70
	v_bfe_u32 v1, v0, 16, 1
	v_rcp_f32_e32 v71, v71
	v_add3_u32 v0, v0, v1, s61
	ds_write_b16_d16_hi v81, v0 offset:7200
	v_mul_f32_e32 v0, v30, v70
	v_bfe_u32 v1, v0, 16, 1
	v_add3_u32 v0, v0, v1, s61
	ds_write_b16_d16_hi v81, v0 offset:7264
	v_mul_f32_e32 v0, v15, v71
	v_bfe_u32 v1, v0, 16, 1
	v_add3_u32 v0, v0, v1, s61
	ds_write_b16_d16_hi v81, v0 offset:7344
	v_mul_f32_e32 v0, v63, v71
	v_bfe_u32 v1, v0, 16, 1
	v_add3_u32 v0, v0, v1, s61
	ds_write_b16_d16_hi v81, v0 offset:7408
	v_mul_f32_e32 v0, v47, v71
	v_bfe_u32 v1, v0, 16, 1
	v_add3_u32 v0, v0, v1, s61
	ds_write_b16_d16_hi v81, v0 offset:7472
	v_mul_f32_e32 v0, v31, v71
	v_bfe_u32 v1, v0, 16, 1
	v_add3_u32 v0, v0, v1, s61
	ds_write_b16_d16_hi v81, v0 offset:7536
	v_lshl_add_u64 v[0:1], s[36:37], 0, v[178:179]
	v_lshrrev_b32_e32 v8, 4, v181
	v_or_b32_e32 v0, v8, v0
	v_mov_b64_e32 v[2:3], s[6:7]
	v_mad_u64_u32 v[4:5], s[0:1], v0, s46, v[2:3]
	v_mul_lo_u32 v13, v1, s46
	v_add_u32_e32 v5, v13, v5
	v_lshl_add_u64 v[4:5], v[4:5], 0, s[64:65]
	v_lshl_add_u64 v[4:5], v[4:5], 0, v[176:177]
	v_add_co_u32_e32 v4, vcc, s52, v4
	s_waitcnt lgkmcnt(0)
	v_mul_u32_u24_e32 v8, 0x110, v8
	s_nop 0
	v_addc_co_u32_e32 v5, vcc, 0, v5, vcc
	s_mov_b32 s99, 0
	s_mov_b32 s98, 0xc000
	v_lshl_add_u64 v[128:129], v[4:5], 0, s[98:99]
	global_load_dwordx4 v[100:103], v[128:129], off
	s_mov_b32 s98, 0x18000
	v_lshl_add_u64 v[128:129], v[4:5], 0, s[98:99]
	global_load_dwordx4 v[104:107], v[128:129], off
	s_mov_b32 s98, 0x24000
	v_lshl_add_u64 v[128:129], v[4:5], 0, s[98:99]
	global_load_dwordx4 v[108:111], v[128:129], off
	s_mov_b32 s98, 0x30000
	v_lshl_add_u64 v[128:129], v[4:5], 0, s[98:99]
	global_load_dwordx4 v[112:115], v[128:129], off
	s_mov_b32 s98, 0x3c000
	v_lshl_add_u64 v[128:129], v[4:5], 0, s[98:99]
	global_load_dwordx4 v[116:119], v[128:129], off
	s_mov_b32 s98, 0x48000
	v_lshl_add_u64 v[128:129], v[4:5], 0, s[98:99]
	global_load_dwordx4 v[120:123], v[128:129], off
	s_mov_b32 s98, 0x54000
	v_lshl_add_u64 v[128:129], v[4:5], 0, s[98:99]
	global_load_dwordx4 v[124:127], v[128:129], off
	global_load_dwordx4 v[4:7], v[4:5], off
	v_add3_u32 v12, v72, v176, v8
	s_waitcnt vmcnt(0)
; __device__ __forceinline__ void attn_unit(const bf16* __restrict__ P, unsigned short* __restrict__ Ob, int b, int h, int kvh, int qb, bool meta, int jt0, int ntl, float* part, unsigned* cnt, const float* __restrict__ qnw, const float2* __restrict__ rtab, char* lds) {
;     ...
;     for (int i = 0; i < 8; ++i) { const int cidx = lane + 64 * i, orow = cidx >> 4, c8 = (cidx & 15) * 8;
;       const u32x4 ov = *(const u32x4*)(stg + orow * 272 + c8 * 2);
;       const u32x4 gv = *(const u32x4*)(Pg + (grow0 + orow) * LD + 4096 + h * D + c8);
;       const unsigned ow[4] = {ov.x, ov.y, ov.z, ov.w}, gw[4] = {gv.x, gv.y, gv.z, gv.w}; unsigned res[4];
; #pragma unroll
;       for (int e = 0; e < 4; ++e) { const float o0 = __uint_as_float(ow[e] << 16), o1 = __uint_as_float(ow[e] & 0xffff0000u), g0 = __uint_as_float(gw[e] << 16), g1 = __uint_as_float(gw[e] & 0xffff0000u);
;         res[e] = cvtpk(o0 * (g0 / (1.f + __expf(-g0))), o1 * (g1 / (1.f + __expf(-g1)))); }
;       *(u32x4*)(Ob + (grow0 + orow) * 2048 + h * D + c8) = (u32x4){res[0], res[1], res[2], res[3]}; }
	v_lshlrev_b32_e32 v14, 16, v4
	v_mul_f32_e32 v9, 0xbfb8aa3b, v14
	v_exp_f32_e32 v15, v9
	v_and_b32_e32 v4, 0xffff0000, v4
	v_mul_f32_e32 v21, 0xbfb8aa3b, v4
	v_exp_f32_e32 v21, v21
	v_add_f32_e32 v15, 1.0, v15
	v_div_scale_f32 v16, s[0:1], v15, v15, v14
	v_rcp_f32_e32 v17, v16
	ds_read_b128 v[8:11], v12
	v_fma_f32 v19, -v16, v17, 1.0
	v_fmac_f32_e32 v17, v19, v17
	v_div_scale_f32 v19, vcc, v14, v15, v14
	v_mul_f32_e32 v20, v19, v17
	v_fma_f32 v22, -v16, v20, v19
	v_fmac_f32_e32 v20, v22, v17
	v_fma_f32 v16, -v16, v20, v19
	v_add_f32_e32 v19, 1.0, v21
	v_div_scale_f32 v21, s[0:1], v19, v19, v4
	v_rcp_f32_e32 v22, v21
	v_div_fmas_f32 v16, v16, v17, v20
	v_div_fixup_f32 v14, v16, v15, v14
	s_waitcnt lgkmcnt(0)
	v_lshlrev_b32_e32 v18, 16, v8
	v_fma_f32 v15, -v21, v22, 1.0
	v_fmac_f32_e32 v22, v15, v22
	v_div_scale_f32 v15, vcc, v4, v19, v4
	v_mul_f32_e32 v16, v15, v22
	v_fma_f32 v17, -v21, v16, v15
	v_fmac_f32_e32 v16, v17, v22
	v_fma_f32 v15, -v21, v16, v15
	v_div_fmas_f32 v15, v15, v22, v16
	v_lshlrev_b32_e32 v16, 16, v5
	v_mul_f32_e32 v17, 0xbfb8aa3b, v16
	v_exp_f32_e32 v17, v17
	v_and_b32_e32 v8, 0xffff0000, v8
	v_div_fixup_f32 v4, v15, v19, v4
	v_mul_f32_e32 v4, v4, v8
	v_mul_f32_e32 v14, v14, v18
	v_cvt_pk_bf16_f32 v8, v14, v4
	v_add_f32_e32 v4, 1.0, v17
	v_div_scale_f32 v14, s[0:1], v4, v4, v16
	v_rcp_f32_e32 v15, v14
	v_and_b32_e32 v5, 0xffff0000, v5
	v_mul_f32_e32 v20, 0xbfb8aa3b, v5
	v_exp_f32_e32 v20, v20
	v_fma_f32 v18, -v14, v15, 1.0
	v_fmac_f32_e32 v15, v18, v15
	v_div_scale_f32 v18, vcc, v16, v4, v16
	v_mul_f32_e32 v19, v18, v15
	v_fma_f32 v21, -v14, v19, v18
	v_fmac_f32_e32 v19, v21, v15
	v_fma_f32 v14, -v14, v19, v18
	v_add_f32_e32 v18, 1.0, v20
	v_div_scale_f32 v20, s[0:1], v18, v18, v5
	v_rcp_f32_e32 v21, v20
	v_div_fmas_f32 v14, v14, v15, v19
	v_div_fixup_f32 v4, v14, v4, v16
	v_lshlrev_b32_e32 v17, 16, v9
	v_fma_f32 v14, -v20, v21, 1.0
	v_fmac_f32_e32 v21, v14, v21
	v_div_scale_f32 v14, vcc, v5, v18, v5
	v_mul_f32_e32 v15, v14, v21
	v_fma_f32 v16, -v20, v15, v14
	v_fmac_f32_e32 v15, v16, v21
	v_fma_f32 v14, -v20, v15, v14
	v_div_fmas_f32 v14, v14, v21, v15
	v_lshlrev_b32_e32 v15, 16, v6
	v_mul_f32_e32 v16, 0xbfb8aa3b, v15
	v_exp_f32_e32 v16, v16
	v_and_b32_e32 v9, 0xffff0000, v9
	v_mul_f32_e32 v4, v4, v17
	v_div_fixup_f32 v5, v14, v18, v5
	v_mul_f32_e32 v5, v5, v9
	v_cvt_pk_bf16_f32 v9, v4, v5
	v_add_f32_e32 v4, 1.0, v16
	v_div_scale_f32 v5, s[0:1], v4, v4, v15
	v_rcp_f32_e32 v14, v5
	v_and_b32_e32 v6, 0xffff0000, v6
	v_mul_f32_e32 v19, 0xbfb8aa3b, v6
	v_exp_f32_e32 v19, v19
	v_fma_f32 v17, -v5, v14, 1.0
	v_fmac_f32_e32 v14, v17, v14
	v_div_scale_f32 v17, vcc, v15, v4, v15
	v_mul_f32_e32 v18, v17, v14
	v_fma_f32 v20, -v5, v18, v17
	v_fmac_f32_e32 v18, v20, v14
	v_fma_f32 v5, -v5, v18, v17
	v_add_f32_e32 v17, 1.0, v19
	v_div_scale_f32 v19, s[0:1], v17, v17, v6
	v_rcp_f32_e32 v20, v19
	v_div_fmas_f32 v5, v5, v14, v18
	v_div_fixup_f32 v4, v5, v4, v15
	v_lshlrev_b32_e32 v16, 16, v10
	v_fma_f32 v5, -v19, v20, 1.0
	v_fmac_f32_e32 v20, v5, v20
	v_div_scale_f32 v5, vcc, v6, v17, v6
	v_mul_f32_e32 v14, v5, v20
	v_fma_f32 v15, -v19, v14, v5
	v_fmac_f32_e32 v14, v15, v20
	v_fma_f32 v5, -v19, v14, v5
	v_div_fmas_f32 v5, v5, v20, v14
	v_lshlrev_b32_e32 v14, 16, v7
	v_mul_f32_e32 v15, 0xbfb8aa3b, v14
	v_exp_f32_e32 v15, v15
	v_and_b32_e32 v10, 0xffff0000, v10
	v_mul_f32_e32 v4, v4, v16
	v_div_fixup_f32 v5, v5, v17, v6
	v_mul_f32_e32 v5, v5, v10
	v_cvt_pk_bf16_f32 v10, v4, v5
	v_add_f32_e32 v4, 1.0, v15
	v_div_scale_f32 v5, s[0:1], v4, v4, v14
	v_rcp_f32_e32 v6, v5
	v_and_b32_e32 v7, 0xffff0000, v7
	v_mul_f32_e32 v18, 0xbfb8aa3b, v7
	v_exp_f32_e32 v18, v18
	v_fma_f32 v16, -v5, v6, 1.0
	v_fmac_f32_e32 v6, v16, v6
	v_div_scale_f32 v16, vcc, v14, v4, v14
	v_mul_f32_e32 v17, v16, v6
	v_fma_f32 v19, -v5, v17, v16
	v_fmac_f32_e32 v17, v19, v6
	v_fma_f32 v5, -v5, v17, v16
	v_add_f32_e32 v16, 1.0, v18
	v_div_scale_f32 v18, s[0:1], v16, v16, v7
	v_rcp_f32_e32 v19, v18
	v_div_fmas_f32 v5, v5, v6, v17
	v_div_fixup_f32 v4, v5, v4, v14
	v_lshlrev_b32_e32 v15, 16, v11
	v_fma_f32 v5, -v18, v19, 1.0
	v_fmac_f32_e32 v19, v5, v19
	v_div_scale_f32 v5, vcc, v7, v16, v7
	v_mul_f32_e32 v6, v5, v19
	v_fma_f32 v14, -v18, v6, v5
	v_fmac_f32_e32 v6, v14, v19
	v_fma_f32 v5, -v18, v6, v5
	v_div_fmas_f32 v5, v5, v19, v6
	v_and_b32_e32 v11, 0xffff0000, v11
	v_div_fixup_f32 v5, v5, v16, v7
	v_mul_f32_e32 v4, v4, v15
	v_mul_f32_e32 v5, v5, v11
	v_or_b32_e32 v6, 4, v0
	v_cvt_pk_bf16_f32 v11, v4, v5
	v_mad_u64_u32 v[4:5], s[0:1], v6, s46, v[2:3]
	v_add_u32_e32 v5, v13, v5
	v_lshl_add_u64 v[4:5], v[4:5], 0, s[64:65]
	v_lshl_add_u64 v[4:5], v[4:5], 0, v[176:177]
	v_add_co_u32_e32 v4, vcc, s52, v4
	s_add_u32 s0, s24, s64
	s_nop 0
	v_addc_co_u32_e32 v5, vcc, 0, v5, vcc
	s_nop 1
	v_mov_b64_e32 v[14:15], v[100:101]
	v_mov_b64_e32 v[16:17], v[102:103]
	s_addc_u32 s1, s25, 0
	v_lshl_add_u64 v[4:5], s[0:1], 0, v[176:177]
	v_lshlrev_b64 v[18:19], 12, v[0:1]
	v_lshl_add_u64 v[18:19], v[4:5], 0, v[18:19]
	global_store_dwordx4 v[18:19], v[8:11], off
	ds_read_b128 v[8:11], v12 offset:1088
	s_waitcnt lgkmcnt(0)
; __device__ __forceinline__ void attn_unit(const bf16* __restrict__ P, unsigned short* __restrict__ Ob, int b, int h, int kvh, int qb, bool meta, int jt0, int ntl, float* part, unsigned* cnt, const float* __restrict__ qnw, const float2* __restrict__ rtab, char* lds) {
;     ...
;     for (int i = 0; i < 8; ++i) { const int cidx = lane + 64 * i, orow = cidx >> 4, c8 = (cidx & 15) * 8;
;       const u32x4 ov = *(const u32x4*)(stg + orow * 272 + c8 * 2);
;       const u32x4 gv = *(const u32x4*)(Pg + (grow0 + orow) * LD + 4096 + h * D + c8);
;       const unsigned ow[4] = {ov.x, ov.y, ov.z, ov.w}, gw[4] = {gv.x, gv.y, gv.z, gv.w}; unsigned res[4];
; #pragma unroll
;       for (int e = 0; e < 4; ++e) { const float o0 = __uint_as_float(ow[e] << 16), o1 = __uint_as_float(ow[e] & 0xffff0000u), g0 = __uint_as_float(gw[e] << 16), g1 = __uint_as_float(gw[e] & 0xffff0000u);
;         res[e] = cvtpk(o0 * (g0 / (1.f + __expf(-g0))), o1 * (g1 / (1.f + __expf(-g1)))); }
;       *(u32x4*)(Ob + (grow0 + orow) * 2048 + h * D + c8) = (u32x4){res[0], res[1], res[2], res[3]}; }
	v_lshlrev_b32_e32 v21, 16, v8
	v_and_b32_e32 v8, 0xffff0000, v8
	s_nop 0
	v_lshlrev_b32_e32 v7, 16, v14
	v_mul_f32_e32 v20, 0xbfb8aa3b, v7
	v_exp_f32_e32 v20, v20
	v_and_b32_e32 v14, 0xffff0000, v14
	v_mul_f32_e32 v24, 0xbfb8aa3b, v14
	v_exp_f32_e32 v24, v24
	v_add_f32_e32 v18, 1.0, v20
	v_div_scale_f32 v19, s[0:1], v18, v18, v7
	v_rcp_f32_e32 v20, v19
	s_nop 0
	v_fma_f32 v22, -v19, v20, 1.0
	v_fmac_f32_e32 v20, v22, v20
	v_div_scale_f32 v22, vcc, v7, v18, v7
	v_mul_f32_e32 v23, v22, v20
	v_fma_f32 v25, -v19, v23, v22
	v_fmac_f32_e32 v23, v25, v20
	v_fma_f32 v19, -v19, v23, v22
	v_add_f32_e32 v22, 1.0, v24
	v_div_scale_f32 v24, s[0:1], v22, v22, v14
	v_rcp_f32_e32 v25, v24
	v_div_fmas_f32 v19, v19, v20, v23
	v_div_fixup_f32 v7, v19, v18, v7
	v_mul_f32_e32 v7, v7, v21
	v_fma_f32 v18, -v24, v25, 1.0
	v_fmac_f32_e32 v25, v18, v25
	v_div_scale_f32 v18, vcc, v14, v22, v14
	v_mul_f32_e32 v19, v18, v25
	v_fma_f32 v20, -v24, v19, v18
	v_fmac_f32_e32 v19, v20, v25
	v_fma_f32 v18, -v24, v19, v18
	v_div_fmas_f32 v18, v18, v25, v19
	v_lshlrev_b32_e32 v19, 16, v15
	v_mul_f32_e32 v20, 0xbfb8aa3b, v19
	v_exp_f32_e32 v20, v20
	v_div_fixup_f32 v14, v18, v22, v14
	v_mul_f32_e32 v8, v14, v8
	v_cvt_pk_bf16_f32 v14, v7, v8
	v_add_f32_e32 v7, 1.0, v20
	v_div_scale_f32 v8, s[0:1], v7, v7, v19
	v_rcp_f32_e32 v18, v8
	v_and_b32_e32 v15, 0xffff0000, v15
	v_mul_f32_e32 v23, 0xbfb8aa3b, v15
	v_exp_f32_e32 v23, v23
	v_fma_f32 v21, -v8, v18, 1.0
	v_fmac_f32_e32 v18, v21, v18
	v_div_scale_f32 v21, vcc, v19, v7, v19
	v_mul_f32_e32 v22, v21, v18
	v_fma_f32 v24, -v8, v22, v21
	v_fmac_f32_e32 v22, v24, v18
	v_fma_f32 v8, -v8, v22, v21
	v_add_f32_e32 v21, 1.0, v23
	v_div_scale_f32 v23, s[0:1], v21, v21, v15
	v_rcp_f32_e32 v24, v23
	v_div_fmas_f32 v8, v8, v18, v22
	v_div_fixup_f32 v7, v8, v7, v19
	v_lshlrev_b32_e32 v20, 16, v9
	v_fma_f32 v8, -v23, v24, 1.0
	v_fmac_f32_e32 v24, v8, v24
	v_div_scale_f32 v8, vcc, v15, v21, v15
	v_mul_f32_e32 v18, v8, v24
	v_fma_f32 v19, -v23, v18, v8
	v_fmac_f32_e32 v18, v19, v24
	v_fma_f32 v8, -v23, v18, v8
	v_div_fmas_f32 v8, v8, v24, v18
	v_lshlrev_b32_e32 v18, 16, v16
	v_mul_f32_e32 v19, 0xbfb8aa3b, v18
	v_exp_f32_e32 v19, v19
	v_and_b32_e32 v9, 0xffff0000, v9
	v_mul_f32_e32 v7, v7, v20
	v_div_fixup_f32 v8, v8, v21, v15
	v_mul_f32_e32 v8, v8, v9
	v_cvt_pk_bf16_f32 v15, v7, v8
	v_add_f32_e32 v7, 1.0, v19
	v_div_scale_f32 v8, s[0:1], v7, v7, v18
	v_rcp_f32_e32 v9, v8
	v_and_b32_e32 v16, 0xffff0000, v16
	v_mul_f32_e32 v22, 0xbfb8aa3b, v16
	v_exp_f32_e32 v22, v22
	v_fma_f32 v20, -v8, v9, 1.0
	v_fmac_f32_e32 v9, v20, v9
	v_div_scale_f32 v20, vcc, v18, v7, v18
	v_mul_f32_e32 v21, v20, v9
	v_fma_f32 v23, -v8, v21, v20
	v_fmac_f32_e32 v21, v23, v9
	v_fma_f32 v8, -v8, v21, v20
	v_add_f32_e32 v20, 1.0, v22
	v_div_scale_f32 v22, s[0:1], v20, v20, v16
	v_rcp_f32_e32 v23, v22
	v_div_fmas_f32 v8, v8, v9, v21
	v_div_fixup_f32 v7, v8, v7, v18
	v_lshlrev_b32_e32 v19, 16, v10
	v_fma_f32 v8, -v22, v23, 1.0
	v_fmac_f32_e32 v23, v8, v23
	v_div_scale_f32 v8, vcc, v16, v20, v16
	v_mul_f32_e32 v9, v8, v23
	v_fma_f32 v18, -v22, v9, v8
	v_fmac_f32_e32 v9, v18, v23
	v_fma_f32 v8, -v22, v9, v8
	v_div_fmas_f32 v8, v8, v23, v9
	v_lshlrev_b32_e32 v9, 16, v17
	v_mul_f32_e32 v18, 0xbfb8aa3b, v9
	v_exp_f32_e32 v18, v18
	v_and_b32_e32 v10, 0xffff0000, v10
	v_mul_f32_e32 v7, v7, v19
	v_div_fixup_f32 v8, v8, v20, v16
	v_mul_f32_e32 v8, v8, v10
	v_cvt_pk_bf16_f32 v16, v7, v8
	v_add_f32_e32 v7, 1.0, v18
	v_div_scale_f32 v8, s[0:1], v7, v7, v9
	v_rcp_f32_e32 v10, v8
	v_and_b32_e32 v17, 0xffff0000, v17
	v_mul_f32_e32 v21, 0xbfb8aa3b, v17
	v_exp_f32_e32 v21, v21
	v_fma_f32 v19, -v8, v10, 1.0
	v_fmac_f32_e32 v10, v19, v10
	v_div_scale_f32 v19, vcc, v9, v7, v9
	v_mul_f32_e32 v20, v19, v10
	v_fma_f32 v22, -v8, v20, v19
	v_fmac_f32_e32 v20, v22, v10
	v_fma_f32 v8, -v8, v20, v19
	v_add_f32_e32 v19, 1.0, v21
	v_div_scale_f32 v21, s[0:1], v19, v19, v17
	v_rcp_f32_e32 v22, v21
	v_div_fmas_f32 v8, v8, v10, v20
	v_div_fixup_f32 v7, v8, v7, v9
	v_lshlrev_b32_e32 v18, 16, v11
	v_fma_f32 v8, -v21, v22, 1.0
	v_fmac_f32_e32 v22, v8, v22
	v_div_scale_f32 v8, vcc, v17, v19, v17
	v_mul_f32_e32 v9, v8, v22
	v_fma_f32 v10, -v21, v9, v8
	v_fmac_f32_e32 v9, v10, v22
	v_fma_f32 v8, -v21, v9, v8
	v_div_fmas_f32 v8, v8, v22, v9
	v_and_b32_e32 v11, 0xffff0000, v11
	v_div_fixup_f32 v8, v8, v19, v17
	v_mul_f32_e32 v8, v8, v11
	v_or_b32_e32 v10, 8, v0
	v_mul_f32_e32 v7, v7, v18
	v_cvt_pk_bf16_f32 v17, v7, v8
	v_mad_u64_u32 v[8:9], s[0:1], v10, s46, v[2:3]
	v_add_u32_e32 v9, v13, v9
	v_lshl_add_u64 v[8:9], v[8:9], 0, s[64:65]
	v_lshl_add_u64 v[8:9], v[8:9], 0, v[176:177]
	v_add_co_u32_e32 v8, vcc, s52, v8
	v_mov_b32_e32 v7, v1
	s_nop 0
	v_addc_co_u32_e32 v9, vcc, 0, v9, vcc
	s_nop 1
	v_mov_b64_e32 v[18:19], v[104:105]
	v_mov_b64_e32 v[20:21], v[106:107]
	v_lshlrev_b64 v[6:7], 12, v[6:7]
	v_lshl_add_u64 v[6:7], v[4:5], 0, v[6:7]
	global_store_dwordx4 v[6:7], v[14:17], off
	s_nop 0
	v_lshlrev_b32_e32 v11, 16, v18
	v_mul_f32_e32 v8, 0xbfb8aa3b, v11
	v_exp_f32_e32 v22, v8
	v_and_b32_e32 v18, 0xffff0000, v18
	v_mul_f32_e32 v24, 0xbfb8aa3b, v18
	v_exp_f32_e32 v24, v24
	v_add_f32_e32 v14, 1.0, v22
	v_div_scale_f32 v15, s[0:1], v14, v14, v11
	v_rcp_f32_e32 v16, v15
	ds_read_b128 v[6:9], v12 offset:2176
	v_fma_f32 v22, -v15, v16, 1.0
	v_fmac_f32_e32 v16, v22, v16
	v_div_scale_f32 v22, vcc, v11, v14, v11
	v_mul_f32_e32 v23, v22, v16
	v_fma_f32 v25, -v15, v23, v22
	v_fmac_f32_e32 v23, v25, v16
	v_fma_f32 v15, -v15, v23, v22
	v_add_f32_e32 v22, 1.0, v24
	v_div_scale_f32 v24, s[0:1], v22, v22, v18
	v_rcp_f32_e32 v25, v24
	v_div_fmas_f32 v15, v15, v16, v23
	v_div_fixup_f32 v11, v15, v14, v11
	s_waitcnt lgkmcnt(0)
; __device__ __forceinline__ void attn_unit(const bf16* __restrict__ P, unsigned short* __restrict__ Ob, int b, int h, int kvh, int qb, bool meta, int jt0, int ntl, float* part, unsigned* cnt, const float* __restrict__ qnw, const float2* __restrict__ rtab, char* lds) {
;     ...
;     for (int i = 0; i < 8; ++i) { const int cidx = lane + 64 * i, orow = cidx >> 4, c8 = (cidx & 15) * 8;
;       const u32x4 ov = *(const u32x4*)(stg + orow * 272 + c8 * 2);
;       const u32x4 gv = *(const u32x4*)(Pg + (grow0 + orow) * LD + 4096 + h * D + c8);
;       const unsigned ow[4] = {ov.x, ov.y, ov.z, ov.w}, gw[4] = {gv.x, gv.y, gv.z, gv.w}; unsigned res[4];
; #pragma unroll
;       for (int e = 0; e < 4; ++e) { const float o0 = __uint_as_float(ow[e] << 16), o1 = __uint_as_float(ow[e] & 0xffff0000u), g0 = __uint_as_float(gw[e] << 16), g1 = __uint_as_float(gw[e] & 0xffff0000u);
;         res[e] = cvtpk(o0 * (g0 / (1.f + __expf(-g0))), o1 * (g1 / (1.f + __expf(-g1)))); }
;       *(u32x4*)(Ob + (grow0 + orow) * 2048 + h * D + c8) = (u32x4){res[0], res[1], res[2], res[3]}; }
	v_lshlrev_b32_e32 v17, 16, v6
	v_fma_f32 v14, -v24, v25, 1.0
	v_fmac_f32_e32 v25, v14, v25
	v_div_scale_f32 v14, vcc, v18, v22, v18
	v_mul_f32_e32 v15, v14, v25
	v_fma_f32 v16, -v24, v15, v14
	v_fmac_f32_e32 v15, v16, v25
	v_fma_f32 v14, -v24, v15, v14
	v_div_fmas_f32 v14, v14, v25, v15
	v_lshlrev_b32_e32 v15, 16, v19
	v_mul_f32_e32 v16, 0xbfb8aa3b, v15
	v_exp_f32_e32 v16, v16
	v_and_b32_e32 v6, 0xffff0000, v6
	v_div_fixup_f32 v14, v14, v22, v18
	v_mul_f32_e32 v6, v14, v6
	v_mul_f32_e32 v11, v11, v17
	v_cvt_pk_bf16_f32 v14, v11, v6
	v_add_f32_e32 v6, 1.0, v16
	v_div_scale_f32 v11, s[0:1], v6, v6, v15
	v_rcp_f32_e32 v16, v11
	v_and_b32_e32 v18, 0xffff0000, v19
	v_mul_f32_e32 v23, 0xbfb8aa3b, v18
	v_exp_f32_e32 v23, v23
	v_fma_f32 v19, -v11, v16, 1.0
	v_fmac_f32_e32 v16, v19, v16
	v_div_scale_f32 v19, vcc, v15, v6, v15
	v_mul_f32_e32 v22, v19, v16
	v_fma_f32 v24, -v11, v22, v19
	v_fmac_f32_e32 v22, v24, v16
	v_fma_f32 v11, -v11, v22, v19
	v_add_f32_e32 v19, 1.0, v23
	v_div_scale_f32 v23, s[0:1], v19, v19, v18
	v_rcp_f32_e32 v24, v23
	v_div_fmas_f32 v11, v11, v16, v22
	v_div_fixup_f32 v6, v11, v6, v15
	v_lshlrev_b32_e32 v17, 16, v7
	v_fma_f32 v11, -v23, v24, 1.0
	v_fmac_f32_e32 v24, v11, v24
	v_div_scale_f32 v11, vcc, v18, v19, v18
	v_mul_f32_e32 v15, v11, v24
	v_fma_f32 v16, -v23, v15, v11
	v_fmac_f32_e32 v15, v16, v24
	v_fma_f32 v11, -v23, v15, v11
	v_lshlrev_b32_e32 v16, 16, v20
	v_div_fmas_f32 v11, v11, v24, v15
	v_mul_f32_e32 v15, 0xbfb8aa3b, v16
	v_mul_f32_e32 v6, v6, v17
	v_exp_f32_e32 v17, v15
	v_and_b32_e32 v7, 0xffff0000, v7
	v_div_fixup_f32 v11, v11, v19, v18
	v_mul_f32_e32 v7, v11, v7
	v_cvt_pk_bf16_f32 v15, v6, v7
	v_add_f32_e32 v6, 1.0, v17
	v_div_scale_f32 v7, s[0:1], v6, v6, v16
	v_rcp_f32_e32 v11, v7
	v_and_b32_e32 v18, 0xffff0000, v20
	v_mul_f32_e32 v22, 0xbfb8aa3b, v18
	v_exp_f32_e32 v22, v22
	v_fma_f32 v19, -v7, v11, 1.0
	v_fmac_f32_e32 v11, v19, v11
	v_div_scale_f32 v19, vcc, v16, v6, v16
	v_mul_f32_e32 v20, v19, v11
	v_fma_f32 v23, -v7, v20, v19
	v_fmac_f32_e32 v20, v23, v11
	v_fma_f32 v7, -v7, v20, v19
	v_add_f32_e32 v19, 1.0, v22
	v_div_scale_f32 v22, s[0:1], v19, v19, v18
	v_rcp_f32_e32 v23, v22
	v_div_fmas_f32 v7, v7, v11, v20
	v_div_fixup_f32 v6, v7, v6, v16
	v_lshlrev_b32_e32 v17, 16, v8
	v_fma_f32 v7, -v22, v23, 1.0
	v_fmac_f32_e32 v23, v7, v23
	v_div_scale_f32 v7, vcc, v18, v19, v18
	v_mul_f32_e32 v11, v7, v23
	v_fma_f32 v16, -v22, v11, v7
	v_fmac_f32_e32 v11, v16, v23
	v_fma_f32 v7, -v22, v11, v7
	v_div_fmas_f32 v7, v7, v23, v11
	v_lshlrev_b32_e32 v11, 16, v21
	v_mul_f32_e32 v16, 0xbfb8aa3b, v11
	v_mul_f32_e32 v6, v6, v17
	v_exp_f32_e32 v17, v16
	v_and_b32_e32 v8, 0xffff0000, v8
	v_div_fixup_f32 v7, v7, v19, v18
	v_mul_f32_e32 v7, v7, v8
	v_cvt_pk_bf16_f32 v16, v6, v7
	v_add_f32_e32 v6, 1.0, v17
	v_div_scale_f32 v7, s[0:1], v6, v6, v11
	v_rcp_f32_e32 v8, v7
	v_and_b32_e32 v18, 0xffff0000, v21
	v_mul_f32_e32 v21, 0xbfb8aa3b, v18
	v_exp_f32_e32 v21, v21
	v_fma_f32 v19, -v7, v8, 1.0
	v_fmac_f32_e32 v8, v19, v8
	v_div_scale_f32 v19, vcc, v11, v6, v11
	v_mul_f32_e32 v20, v19, v8
	v_fma_f32 v22, -v7, v20, v19
	v_fmac_f32_e32 v20, v22, v8
	v_fma_f32 v7, -v7, v20, v19
	v_add_f32_e32 v19, 1.0, v21
	v_div_scale_f32 v21, s[0:1], v19, v19, v18
	v_rcp_f32_e32 v22, v21
	v_div_fmas_f32 v7, v7, v8, v20
	v_div_fixup_f32 v6, v7, v6, v11
	v_lshlrev_b32_e32 v17, 16, v9
	v_fma_f32 v7, -v21, v22, 1.0
	v_fmac_f32_e32 v22, v7, v22
	v_div_scale_f32 v7, vcc, v18, v19, v18
	v_mul_f32_e32 v8, v7, v22
	v_fma_f32 v11, -v21, v8, v7
	v_fmac_f32_e32 v8, v11, v22
	v_fma_f32 v7, -v21, v8, v7
	v_div_fmas_f32 v7, v7, v22, v8
	v_and_b32_e32 v9, 0xffff0000, v9
	v_div_fixup_f32 v7, v7, v19, v18
	v_mul_f32_e32 v6, v6, v17
	v_mul_f32_e32 v7, v7, v9
	v_or_b32_e32 v8, 12, v0
	v_cvt_pk_bf16_f32 v17, v6, v7
	v_mad_u64_u32 v[6:7], s[0:1], v8, s46, v[2:3]
	v_add_u32_e32 v7, v13, v7
	v_lshl_add_u64 v[6:7], v[6:7], 0, s[64:65]
	v_lshl_add_u64 v[6:7], v[6:7], 0, v[176:177]
	v_add_co_u32_e32 v6, vcc, s52, v6
	v_mov_b32_e32 v11, v1
	s_nop 0
	v_addc_co_u32_e32 v7, vcc, 0, v7, vcc
	s_nop 1
	v_mov_b64_e32 v[18:19], v[108:109]
	v_mov_b64_e32 v[20:21], v[110:111]
	v_lshlrev_b64 v[6:7], 12, v[10:11]
	v_lshl_add_u64 v[6:7], v[4:5], 0, v[6:7]
	global_store_dwordx4 v[6:7], v[14:17], off
	ds_read_b128 v[14:17], v12 offset:3264
	s_waitcnt lgkmcnt(0)
; __device__ __forceinline__ void attn_unit(const bf16* __restrict__ P, unsigned short* __restrict__ Ob, int b, int h, int kvh, int qb, bool meta, int jt0, int ntl, float* part, unsigned* cnt, const float* __restrict__ qnw, const float2* __restrict__ rtab, char* lds) {
;     ...
;     for (int i = 0; i < 8; ++i) { const int cidx = lane + 64 * i, orow = cidx >> 4, c8 = (cidx & 15) * 8;
;       const u32x4 ov = *(const u32x4*)(stg + orow * 272 + c8 * 2);
;       const u32x4 gv = *(const u32x4*)(Pg + (grow0 + orow) * LD + 4096 + h * D + c8);
;       const unsigned ow[4] = {ov.x, ov.y, ov.z, ov.w}, gw[4] = {gv.x, gv.y, gv.z, gv.w}; unsigned res[4];
; #pragma unroll
;       for (int e = 0; e < 4; ++e) { const float o0 = __uint_as_float(ow[e] << 16), o1 = __uint_as_float(ow[e] & 0xffff0000u), g0 = __uint_as_float(gw[e] << 16), g1 = __uint_as_float(gw[e] & 0xffff0000u);
;         res[e] = cvtpk(o0 * (g0 / (1.f + __expf(-g0))), o1 * (g1 / (1.f + __expf(-g1)))); }
;       *(u32x4*)(Ob + (grow0 + orow) * 2048 + h * D + c8) = (u32x4){res[0], res[1], res[2], res[3]}; }
	v_lshlrev_b32_e32 v11, 16, v14
	v_and_b32_e32 v14, 0xffff0000, v14
	s_nop 0
	v_lshlrev_b32_e32 v9, 16, v18
	v_mul_f32_e32 v10, 0xbfb8aa3b, v9
	v_exp_f32_e32 v10, v10
	v_and_b32_e32 v18, 0xffff0000, v18
	v_mul_f32_e32 v24, 0xbfb8aa3b, v18
	v_exp_f32_e32 v24, v24
	v_add_f32_e32 v6, 1.0, v10
	v_div_scale_f32 v7, s[0:1], v6, v6, v9
	v_rcp_f32_e32 v10, v7
	s_nop 0
	v_fma_f32 v22, -v7, v10, 1.0
	v_fmac_f32_e32 v10, v22, v10
	v_div_scale_f32 v22, vcc, v9, v6, v9
	v_mul_f32_e32 v23, v22, v10
	v_fma_f32 v25, -v7, v23, v22
	v_fmac_f32_e32 v23, v25, v10
	v_fma_f32 v7, -v7, v23, v22
	v_add_f32_e32 v22, 1.0, v24
	v_div_scale_f32 v24, s[0:1], v22, v22, v18
	v_rcp_f32_e32 v25, v24
	v_div_fmas_f32 v7, v7, v10, v23
	v_div_fixup_f32 v6, v7, v6, v9
	v_mul_f32_e32 v6, v6, v11
	v_fma_f32 v7, -v24, v25, 1.0
	v_fmac_f32_e32 v25, v7, v25
	v_div_scale_f32 v7, vcc, v18, v22, v18
	v_mul_f32_e32 v9, v7, v25
	v_fma_f32 v10, -v24, v9, v7
	v_fmac_f32_e32 v9, v10, v25
	v_fma_f32 v7, -v24, v9, v7
	v_div_fmas_f32 v7, v7, v25, v9
	v_lshlrev_b32_e32 v9, 16, v19
	v_mul_f32_e32 v10, 0xbfb8aa3b, v9
	v_exp_f32_e32 v10, v10
	v_div_fixup_f32 v7, v7, v22, v18
	v_mul_f32_e32 v7, v7, v14
	v_cvt_pk_bf16_f32 v14, v6, v7
	v_add_f32_e32 v6, 1.0, v10
	v_div_scale_f32 v7, s[0:1], v6, v6, v9
	v_rcp_f32_e32 v10, v7
	v_and_b32_e32 v18, 0xffff0000, v19
	v_mul_f32_e32 v23, 0xbfb8aa3b, v18
	v_exp_f32_e32 v23, v23
	v_fma_f32 v19, -v7, v10, 1.0
	v_fmac_f32_e32 v10, v19, v10
	v_div_scale_f32 v19, vcc, v9, v6, v9
	v_mul_f32_e32 v22, v19, v10
	v_fma_f32 v24, -v7, v22, v19
	v_fmac_f32_e32 v22, v24, v10
	v_fma_f32 v7, -v7, v22, v19
	v_add_f32_e32 v19, 1.0, v23
	v_div_scale_f32 v23, s[0:1], v19, v19, v18
	v_rcp_f32_e32 v24, v23
	v_div_fmas_f32 v7, v7, v10, v22
	v_div_fixup_f32 v6, v7, v6, v9
	v_lshlrev_b32_e32 v11, 16, v15
	v_fma_f32 v7, -v23, v24, 1.0
	v_fmac_f32_e32 v24, v7, v24
	v_div_scale_f32 v7, vcc, v18, v19, v18
	v_mul_f32_e32 v9, v7, v24
	v_fma_f32 v10, -v23, v9, v7
	v_fmac_f32_e32 v9, v10, v24
	v_fma_f32 v7, -v23, v9, v7
	v_div_fmas_f32 v7, v7, v24, v9
	v_lshlrev_b32_e32 v9, 16, v20
	v_mul_f32_e32 v10, 0xbfb8aa3b, v9
	v_exp_f32_e32 v10, v10
	v_and_b32_e32 v15, 0xffff0000, v15
	v_mul_f32_e32 v6, v6, v11
	v_div_fixup_f32 v7, v7, v19, v18
	v_mul_f32_e32 v7, v7, v15
	v_cvt_pk_bf16_f32 v15, v6, v7
	v_add_f32_e32 v6, 1.0, v10
	v_div_scale_f32 v7, s[0:1], v6, v6, v9
	v_rcp_f32_e32 v10, v7
	v_and_b32_e32 v18, 0xffff0000, v20
	v_mul_f32_e32 v22, 0xbfb8aa3b, v18
	v_exp_f32_e32 v22, v22
	v_fma_f32 v19, -v7, v10, 1.0
	v_fmac_f32_e32 v10, v19, v10
	v_div_scale_f32 v19, vcc, v9, v6, v9
	v_mul_f32_e32 v20, v19, v10
	v_fma_f32 v23, -v7, v20, v19
	v_fmac_f32_e32 v20, v23, v10
	v_fma_f32 v7, -v7, v20, v19
	v_add_f32_e32 v19, 1.0, v22
	v_div_scale_f32 v22, s[0:1], v19, v19, v18
	v_rcp_f32_e32 v23, v22
	v_div_fmas_f32 v7, v7, v10, v20
	v_div_fixup_f32 v6, v7, v6, v9
	v_lshlrev_b32_e32 v11, 16, v16
	v_fma_f32 v7, -v22, v23, 1.0
	v_fmac_f32_e32 v23, v7, v23
	v_div_scale_f32 v7, vcc, v18, v19, v18
	v_mul_f32_e32 v9, v7, v23
	v_fma_f32 v10, -v22, v9, v7
	v_fmac_f32_e32 v9, v10, v23
	v_fma_f32 v7, -v22, v9, v7
	v_div_fmas_f32 v7, v7, v23, v9
	v_lshlrev_b32_e32 v9, 16, v21
	v_mul_f32_e32 v10, 0xbfb8aa3b, v9
	v_exp_f32_e32 v10, v10
	v_and_b32_e32 v16, 0xffff0000, v16
	v_mul_f32_e32 v6, v6, v11
	v_div_fixup_f32 v7, v7, v19, v18
	v_mul_f32_e32 v7, v7, v16
	v_cvt_pk_bf16_f32 v16, v6, v7
	v_add_f32_e32 v6, 1.0, v10
	v_div_scale_f32 v7, s[0:1], v6, v6, v9
	v_rcp_f32_e32 v10, v7
	v_and_b32_e32 v18, 0xffff0000, v21
	v_mul_f32_e32 v21, 0xbfb8aa3b, v18
	v_exp_f32_e32 v21, v21
	v_fma_f32 v19, -v7, v10, 1.0
	v_fmac_f32_e32 v10, v19, v10
	v_div_scale_f32 v19, vcc, v9, v6, v9
	v_mul_f32_e32 v20, v19, v10
	v_fma_f32 v22, -v7, v20, v19
	v_fmac_f32_e32 v20, v22, v10
	v_fma_f32 v7, -v7, v20, v19
	v_add_f32_e32 v19, 1.0, v21
	v_div_scale_f32 v21, s[0:1], v19, v19, v18
	v_rcp_f32_e32 v22, v21
	v_div_fmas_f32 v7, v7, v10, v20
	v_div_fixup_f32 v6, v7, v6, v9
	v_lshlrev_b32_e32 v11, 16, v17
	v_fma_f32 v7, -v21, v22, 1.0
	v_fmac_f32_e32 v22, v7, v22
	v_div_scale_f32 v7, vcc, v18, v19, v18
	v_mul_f32_e32 v9, v7, v22
	v_fma_f32 v10, -v21, v9, v7
	v_fmac_f32_e32 v9, v10, v22
	v_fma_f32 v7, -v21, v9, v7
	v_div_fmas_f32 v7, v7, v22, v9
	v_and_b32_e32 v17, 0xffff0000, v17
	v_mul_f32_e32 v6, v6, v11
	v_div_fixup_f32 v7, v7, v19, v18
	v_mul_f32_e32 v7, v7, v17
	v_cvt_pk_bf16_f32 v17, v6, v7
	v_or_b32_e32 v6, 16, v0
	v_mad_u64_u32 v[10:11], s[0:1], v6, s46, v[2:3]
	v_add_u32_e32 v11, v13, v11
	v_lshl_add_u64 v[10:11], v[10:11], 0, s[64:65]
	v_lshl_add_u64 v[10:11], v[10:11], 0, v[176:177]
	v_add_co_u32_e32 v10, vcc, s52, v10
	v_mov_b32_e32 v9, v1
	s_nop 0
	v_addc_co_u32_e32 v11, vcc, 0, v11, vcc
	s_nop 1
	v_mov_b64_e32 v[18:19], v[112:113]
	v_mov_b64_e32 v[20:21], v[114:115]
	v_lshlrev_b64 v[8:9], 12, v[8:9]
	v_lshl_add_u64 v[8:9], v[4:5], 0, v[8:9]
	global_store_dwordx4 v[8:9], v[14:17], off
	s_nop 0
	v_lshlrev_b32_e32 v7, 16, v18
	v_mul_f32_e32 v10, 0xbfb8aa3b, v7
	v_exp_f32_e32 v22, v10
	v_and_b32_e32 v18, 0xffff0000, v18
	v_mul_f32_e32 v24, 0xbfb8aa3b, v18
	v_exp_f32_e32 v24, v24
	v_add_f32_e32 v14, 1.0, v22
	v_div_scale_f32 v15, s[0:1], v14, v14, v7
	v_rcp_f32_e32 v16, v15
	ds_read_b128 v[8:11], v12 offset:4352
	v_fma_f32 v22, -v15, v16, 1.0
	v_fmac_f32_e32 v16, v22, v16
	v_div_scale_f32 v22, vcc, v7, v14, v7
	v_mul_f32_e32 v23, v22, v16
	v_fma_f32 v25, -v15, v23, v22
	v_fmac_f32_e32 v23, v25, v16
	v_fma_f32 v15, -v15, v23, v22
	v_add_f32_e32 v22, 1.0, v24
	v_div_scale_f32 v24, s[0:1], v22, v22, v18
	v_rcp_f32_e32 v25, v24
	v_div_fmas_f32 v15, v15, v16, v23
	v_div_fixup_f32 v7, v15, v14, v7
	s_waitcnt lgkmcnt(0)
; __device__ __forceinline__ void attn_unit(const bf16* __restrict__ P, unsigned short* __restrict__ Ob, int b, int h, int kvh, int qb, bool meta, int jt0, int ntl, float* part, unsigned* cnt, const float* __restrict__ qnw, const float2* __restrict__ rtab, char* lds) {
;     ...
;     for (int i = 0; i < 8; ++i) { const int cidx = lane + 64 * i, orow = cidx >> 4, c8 = (cidx & 15) * 8;
;       const u32x4 ov = *(const u32x4*)(stg + orow * 272 + c8 * 2);
;       const u32x4 gv = *(const u32x4*)(Pg + (grow0 + orow) * LD + 4096 + h * D + c8);
;       const unsigned ow[4] = {ov.x, ov.y, ov.z, ov.w}, gw[4] = {gv.x, gv.y, gv.z, gv.w}; unsigned res[4];
; #pragma unroll
;       for (int e = 0; e < 4; ++e) { const float o0 = __uint_as_float(ow[e] << 16), o1 = __uint_as_float(ow[e] & 0xffff0000u), g0 = __uint_as_float(gw[e] << 16), g1 = __uint_as_float(gw[e] & 0xffff0000u);
;         res[e] = cvtpk(o0 * (g0 / (1.f + __expf(-g0))), o1 * (g1 / (1.f + __expf(-g1)))); }
;       *(u32x4*)(Ob + (grow0 + orow) * 2048 + h * D + c8) = (u32x4){res[0], res[1], res[2], res[3]}; }
	v_lshlrev_b32_e32 v17, 16, v8
	v_fma_f32 v14, -v24, v25, 1.0
	v_fmac_f32_e32 v25, v14, v25
	v_div_scale_f32 v14, vcc, v18, v22, v18
	v_mul_f32_e32 v15, v14, v25
	v_fma_f32 v16, -v24, v15, v14
	v_fmac_f32_e32 v15, v16, v25
	v_fma_f32 v14, -v24, v15, v14
	v_div_fmas_f32 v14, v14, v25, v15
	v_lshlrev_b32_e32 v15, 16, v19
	v_mul_f32_e32 v16, 0xbfb8aa3b, v15
	v_exp_f32_e32 v16, v16
	v_and_b32_e32 v8, 0xffff0000, v8
	v_mul_f32_e32 v7, v7, v17
	v_div_fixup_f32 v14, v14, v22, v18
	v_mul_f32_e32 v8, v14, v8
	v_cvt_pk_bf16_f32 v14, v7, v8
	v_add_f32_e32 v7, 1.0, v16
	v_div_scale_f32 v8, s[0:1], v7, v7, v15
	v_rcp_f32_e32 v16, v8
	v_and_b32_e32 v18, 0xffff0000, v19
	v_mul_f32_e32 v23, 0xbfb8aa3b, v18
	v_exp_f32_e32 v23, v23
	v_fma_f32 v19, -v8, v16, 1.0
	v_fmac_f32_e32 v16, v19, v16
	v_div_scale_f32 v19, vcc, v15, v7, v15
	v_mul_f32_e32 v22, v19, v16
	v_fma_f32 v24, -v8, v22, v19
	v_fmac_f32_e32 v22, v24, v16
	v_fma_f32 v8, -v8, v22, v19
	v_add_f32_e32 v19, 1.0, v23
	v_div_scale_f32 v23, s[0:1], v19, v19, v18
	v_rcp_f32_e32 v24, v23
	v_div_fmas_f32 v8, v8, v16, v22
	v_div_fixup_f32 v7, v8, v7, v15
	v_lshlrev_b32_e32 v17, 16, v9
	v_fma_f32 v8, -v23, v24, 1.0
	v_fmac_f32_e32 v24, v8, v24
	v_div_scale_f32 v8, vcc, v18, v19, v18
	v_mul_f32_e32 v15, v8, v24
	v_fma_f32 v16, -v23, v15, v8
	v_fmac_f32_e32 v15, v16, v24
	v_fma_f32 v8, -v23, v15, v8
	v_lshlrev_b32_e32 v16, 16, v20
	v_div_fmas_f32 v8, v8, v24, v15
	v_mul_f32_e32 v15, 0xbfb8aa3b, v16
	v_mul_f32_e32 v7, v7, v17
	v_exp_f32_e32 v17, v15
	v_and_b32_e32 v9, 0xffff0000, v9
	v_div_fixup_f32 v8, v8, v19, v18
	v_mul_f32_e32 v8, v8, v9
	v_cvt_pk_bf16_f32 v15, v7, v8
	v_add_f32_e32 v7, 1.0, v17
	v_div_scale_f32 v8, s[0:1], v7, v7, v16
	v_rcp_f32_e32 v9, v8
	v_and_b32_e32 v18, 0xffff0000, v20
	v_mul_f32_e32 v22, 0xbfb8aa3b, v18
	v_exp_f32_e32 v22, v22
	v_fma_f32 v19, -v8, v9, 1.0
	v_fmac_f32_e32 v9, v19, v9
	v_div_scale_f32 v19, vcc, v16, v7, v16
	v_mul_f32_e32 v20, v19, v9
	v_fma_f32 v23, -v8, v20, v19
	v_fmac_f32_e32 v20, v23, v9
	v_fma_f32 v8, -v8, v20, v19
	v_add_f32_e32 v19, 1.0, v22
	v_div_scale_f32 v22, s[0:1], v19, v19, v18
	v_rcp_f32_e32 v23, v22
	v_div_fmas_f32 v8, v8, v9, v20
	v_div_fixup_f32 v7, v8, v7, v16
	v_lshlrev_b32_e32 v17, 16, v10
	v_fma_f32 v8, -v22, v23, 1.0
	v_fmac_f32_e32 v23, v8, v23
	v_div_scale_f32 v8, vcc, v18, v19, v18
	v_mul_f32_e32 v9, v8, v23
	v_fma_f32 v16, -v22, v9, v8
	v_fmac_f32_e32 v9, v16, v23
	v_fma_f32 v8, -v22, v9, v8
	v_div_fmas_f32 v8, v8, v23, v9
	v_lshlrev_b32_e32 v9, 16, v21
	v_mul_f32_e32 v16, 0xbfb8aa3b, v9
	v_mul_f32_e32 v7, v7, v17
	v_exp_f32_e32 v17, v16
	v_and_b32_e32 v10, 0xffff0000, v10
	v_div_fixup_f32 v8, v8, v19, v18
	v_mul_f32_e32 v8, v8, v10
	v_cvt_pk_bf16_f32 v16, v7, v8
	v_add_f32_e32 v7, 1.0, v17
	v_div_scale_f32 v8, s[0:1], v7, v7, v9
	v_rcp_f32_e32 v10, v8
	v_and_b32_e32 v18, 0xffff0000, v21
	v_mul_f32_e32 v21, 0xbfb8aa3b, v18
	v_exp_f32_e32 v21, v21
	v_fma_f32 v19, -v8, v10, 1.0
	v_fmac_f32_e32 v10, v19, v10
	v_div_scale_f32 v19, vcc, v9, v7, v9
	v_mul_f32_e32 v20, v19, v10
	v_fma_f32 v22, -v8, v20, v19
	v_fmac_f32_e32 v20, v22, v10
	v_fma_f32 v8, -v8, v20, v19
	v_add_f32_e32 v19, 1.0, v21
	v_div_scale_f32 v21, s[0:1], v19, v19, v18
	v_rcp_f32_e32 v22, v21
	v_div_fmas_f32 v8, v8, v10, v20
	v_div_fixup_f32 v7, v8, v7, v9
	v_lshlrev_b32_e32 v17, 16, v11
	v_fma_f32 v8, -v21, v22, 1.0
	v_fmac_f32_e32 v22, v8, v22
	v_div_scale_f32 v8, vcc, v18, v19, v18
	v_mul_f32_e32 v9, v8, v22
	v_fma_f32 v10, -v21, v9, v8
	v_fmac_f32_e32 v9, v10, v22
	v_fma_f32 v8, -v21, v9, v8
	v_div_fmas_f32 v8, v8, v22, v9
	v_and_b32_e32 v11, 0xffff0000, v11
	v_div_fixup_f32 v8, v8, v19, v18
	v_mul_f32_e32 v8, v8, v11
	v_mul_f32_e32 v7, v7, v17
	v_cvt_pk_bf16_f32 v17, v7, v8
	v_or_b32_e32 v8, 20, v0
	v_mad_u64_u32 v[10:11], s[0:1], v8, s46, v[2:3]
	v_add_u32_e32 v11, v13, v11
	v_lshl_add_u64 v[10:11], v[10:11], 0, s[64:65]
	v_lshl_add_u64 v[10:11], v[10:11], 0, v[176:177]
	v_add_co_u32_e32 v10, vcc, s52, v10
	v_mov_b32_e32 v7, v1
	s_nop 0
	v_addc_co_u32_e32 v11, vcc, 0, v11, vcc
	s_nop 1
	v_mov_b64_e32 v[18:19], v[116:117]
	v_mov_b64_e32 v[20:21], v[118:119]
	v_lshlrev_b64 v[6:7], 12, v[6:7]
	v_lshl_add_u64 v[6:7], v[4:5], 0, v[6:7]
	global_store_dwordx4 v[6:7], v[14:17], off
	ds_read_b128 v[14:17], v12 offset:5440
	s_waitcnt lgkmcnt(0)
; __device__ __forceinline__ void attn_unit(const bf16* __restrict__ P, unsigned short* __restrict__ Ob, int b, int h, int kvh, int qb, bool meta, int jt0, int ntl, float* part, unsigned* cnt, const float* __restrict__ qnw, const float2* __restrict__ rtab, char* lds) {
;     ...
;     for (int i = 0; i < 8; ++i) { const int cidx = lane + 64 * i, orow = cidx >> 4, c8 = (cidx & 15) * 8;
;       const u32x4 ov = *(const u32x4*)(stg + orow * 272 + c8 * 2);
;       const u32x4 gv = *(const u32x4*)(Pg + (grow0 + orow) * LD + 4096 + h * D + c8);
;       const unsigned ow[4] = {ov.x, ov.y, ov.z, ov.w}, gw[4] = {gv.x, gv.y, gv.z, gv.w}; unsigned res[4];
; #pragma unroll
;       for (int e = 0; e < 4; ++e) { const float o0 = __uint_as_float(ow[e] << 16), o1 = __uint_as_float(ow[e] & 0xffff0000u), g0 = __uint_as_float(gw[e] << 16), g1 = __uint_as_float(gw[e] & 0xffff0000u);
;         res[e] = cvtpk(o0 * (g0 / (1.f + __expf(-g0))), o1 * (g1 / (1.f + __expf(-g1)))); }
;       *(u32x4*)(Ob + (grow0 + orow) * 2048 + h * D + c8) = (u32x4){res[0], res[1], res[2], res[3]}; }
	v_lshlrev_b32_e32 v11, 16, v14
	v_and_b32_e32 v14, 0xffff0000, v14
	s_nop 0
	v_lshlrev_b32_e32 v9, 16, v18
	v_mul_f32_e32 v10, 0xbfb8aa3b, v9
	v_exp_f32_e32 v10, v10
	v_and_b32_e32 v18, 0xffff0000, v18
	v_mul_f32_e32 v24, 0xbfb8aa3b, v18
	v_exp_f32_e32 v24, v24
	v_add_f32_e32 v6, 1.0, v10
	v_div_scale_f32 v7, s[0:1], v6, v6, v9
	v_rcp_f32_e32 v10, v7
	s_nop 0
	v_fma_f32 v22, -v7, v10, 1.0
	v_fmac_f32_e32 v10, v22, v10
	v_div_scale_f32 v22, vcc, v9, v6, v9
	v_mul_f32_e32 v23, v22, v10
	v_fma_f32 v25, -v7, v23, v22
	v_fmac_f32_e32 v23, v25, v10
	v_fma_f32 v7, -v7, v23, v22
	v_add_f32_e32 v22, 1.0, v24
	v_div_scale_f32 v24, s[0:1], v22, v22, v18
	v_rcp_f32_e32 v25, v24
	v_div_fmas_f32 v7, v7, v10, v23
	v_div_fixup_f32 v6, v7, v6, v9
	v_mul_f32_e32 v6, v6, v11
	v_fma_f32 v7, -v24, v25, 1.0
	v_fmac_f32_e32 v25, v7, v25
	v_div_scale_f32 v7, vcc, v18, v22, v18
	v_mul_f32_e32 v9, v7, v25
	v_fma_f32 v10, -v24, v9, v7
	v_fmac_f32_e32 v9, v10, v25
	v_fma_f32 v7, -v24, v9, v7
	v_div_fmas_f32 v7, v7, v25, v9
	v_lshlrev_b32_e32 v9, 16, v19
	v_mul_f32_e32 v10, 0xbfb8aa3b, v9
	v_exp_f32_e32 v10, v10
	v_div_fixup_f32 v7, v7, v22, v18
	v_mul_f32_e32 v7, v7, v14
	v_cvt_pk_bf16_f32 v14, v6, v7
	v_add_f32_e32 v6, 1.0, v10
	v_div_scale_f32 v7, s[0:1], v6, v6, v9
	v_rcp_f32_e32 v10, v7
	v_and_b32_e32 v18, 0xffff0000, v19
	v_mul_f32_e32 v23, 0xbfb8aa3b, v18
	v_exp_f32_e32 v23, v23
	v_fma_f32 v19, -v7, v10, 1.0
	v_fmac_f32_e32 v10, v19, v10
	v_div_scale_f32 v19, vcc, v9, v6, v9
	v_mul_f32_e32 v22, v19, v10
	v_fma_f32 v24, -v7, v22, v19
	v_fmac_f32_e32 v22, v24, v10
	v_fma_f32 v7, -v7, v22, v19
	v_add_f32_e32 v19, 1.0, v23
	v_div_scale_f32 v23, s[0:1], v19, v19, v18
	v_rcp_f32_e32 v24, v23
	v_div_fmas_f32 v7, v7, v10, v22
	v_div_fixup_f32 v6, v7, v6, v9
	v_lshlrev_b32_e32 v11, 16, v15
	v_fma_f32 v7, -v23, v24, 1.0
	v_fmac_f32_e32 v24, v7, v24
	v_div_scale_f32 v7, vcc, v18, v19, v18
	v_mul_f32_e32 v9, v7, v24
	v_fma_f32 v10, -v23, v9, v7
	v_fmac_f32_e32 v9, v10, v24
	v_fma_f32 v7, -v23, v9, v7
	v_div_fmas_f32 v7, v7, v24, v9
	v_lshlrev_b32_e32 v9, 16, v20
	v_mul_f32_e32 v10, 0xbfb8aa3b, v9
	v_exp_f32_e32 v10, v10
	v_and_b32_e32 v15, 0xffff0000, v15
	v_mul_f32_e32 v6, v6, v11
	v_div_fixup_f32 v7, v7, v19, v18
	v_mul_f32_e32 v7, v7, v15
	v_cvt_pk_bf16_f32 v15, v6, v7
	v_add_f32_e32 v6, 1.0, v10
	v_div_scale_f32 v7, s[0:1], v6, v6, v9
	v_rcp_f32_e32 v10, v7
	v_and_b32_e32 v18, 0xffff0000, v20
	v_mul_f32_e32 v22, 0xbfb8aa3b, v18
	v_exp_f32_e32 v22, v22
	v_fma_f32 v19, -v7, v10, 1.0
	v_fmac_f32_e32 v10, v19, v10
	v_div_scale_f32 v19, vcc, v9, v6, v9
	v_mul_f32_e32 v20, v19, v10
	v_fma_f32 v23, -v7, v20, v19
	v_fmac_f32_e32 v20, v23, v10
	v_fma_f32 v7, -v7, v20, v19
	v_add_f32_e32 v19, 1.0, v22
	v_div_scale_f32 v22, s[0:1], v19, v19, v18
	v_rcp_f32_e32 v23, v22
	v_div_fmas_f32 v7, v7, v10, v20
	v_div_fixup_f32 v6, v7, v6, v9
	v_lshlrev_b32_e32 v11, 16, v16
	v_fma_f32 v7, -v22, v23, 1.0
	v_fmac_f32_e32 v23, v7, v23
	v_div_scale_f32 v7, vcc, v18, v19, v18
	v_mul_f32_e32 v9, v7, v23
	v_fma_f32 v10, -v22, v9, v7
	v_fmac_f32_e32 v9, v10, v23
	v_fma_f32 v7, -v22, v9, v7
	v_div_fmas_f32 v7, v7, v23, v9
	v_lshlrev_b32_e32 v9, 16, v21
	v_mul_f32_e32 v10, 0xbfb8aa3b, v9
	v_exp_f32_e32 v10, v10
	v_and_b32_e32 v16, 0xffff0000, v16
	v_mul_f32_e32 v6, v6, v11
	v_div_fixup_f32 v7, v7, v19, v18
	v_mul_f32_e32 v7, v7, v16
	v_cvt_pk_bf16_f32 v16, v6, v7
	v_add_f32_e32 v6, 1.0, v10
	v_div_scale_f32 v7, s[0:1], v6, v6, v9
	v_rcp_f32_e32 v10, v7
	v_and_b32_e32 v18, 0xffff0000, v21
	v_mul_f32_e32 v21, 0xbfb8aa3b, v18
	v_exp_f32_e32 v21, v21
	v_fma_f32 v19, -v7, v10, 1.0
	v_fmac_f32_e32 v10, v19, v10
	v_div_scale_f32 v19, vcc, v9, v6, v9
	v_mul_f32_e32 v20, v19, v10
	v_fma_f32 v22, -v7, v20, v19
	v_fmac_f32_e32 v20, v22, v10
	v_fma_f32 v7, -v7, v20, v19
	v_add_f32_e32 v19, 1.0, v21
	v_div_scale_f32 v21, s[0:1], v19, v19, v18
	v_rcp_f32_e32 v22, v21
	v_div_fmas_f32 v7, v7, v10, v20
	v_div_fixup_f32 v6, v7, v6, v9
	v_lshlrev_b32_e32 v11, 16, v17
	v_fma_f32 v7, -v21, v22, 1.0
	v_fmac_f32_e32 v22, v7, v22
	v_div_scale_f32 v7, vcc, v18, v19, v18
	v_mul_f32_e32 v9, v7, v22
	v_fma_f32 v10, -v21, v9, v7
	v_fmac_f32_e32 v9, v10, v22
	v_fma_f32 v7, -v21, v9, v7
	v_div_fmas_f32 v7, v7, v22, v9
	v_and_b32_e32 v17, 0xffff0000, v17
	v_mul_f32_e32 v6, v6, v11
	v_div_fixup_f32 v7, v7, v19, v18
	v_mul_f32_e32 v7, v7, v17
	v_cvt_pk_bf16_f32 v17, v6, v7
	v_or_b32_e32 v6, 24, v0
	v_mad_u64_u32 v[10:11], s[0:1], v6, s46, v[2:3]
	v_add_u32_e32 v11, v13, v11
	v_lshl_add_u64 v[10:11], v[10:11], 0, s[64:65]
	v_lshl_add_u64 v[10:11], v[10:11], 0, v[176:177]
	v_add_co_u32_e32 v10, vcc, s52, v10
	v_mov_b32_e32 v9, v1
	s_nop 0
	v_addc_co_u32_e32 v11, vcc, 0, v11, vcc
	s_nop 1
	v_mov_b64_e32 v[18:19], v[120:121]
	v_mov_b64_e32 v[20:21], v[122:123]
	v_lshlrev_b64 v[8:9], 12, v[8:9]
	v_lshl_add_u64 v[8:9], v[4:5], 0, v[8:9]
	global_store_dwordx4 v[8:9], v[14:17], off
	v_or_b32_e32 v0, 28, v0
	v_mad_u64_u32 v[2:3], s[0:1], v0, s46, v[2:3]
	v_add_u32_e32 v3, v13, v3
	v_lshl_add_u64 v[2:3], v[2:3], 0, s[64:65]
	v_lshl_add_u64 v[2:3], v[2:3], 0, v[176:177]
	s_nop 0
	v_lshlrev_b32_e32 v7, 16, v18
	v_mul_f32_e32 v10, 0xbfb8aa3b, v7
	v_exp_f32_e32 v22, v10
	v_and_b32_e32 v18, 0xffff0000, v18
	v_mul_f32_e32 v24, 0xbfb8aa3b, v18
	v_exp_f32_e32 v24, v24
	v_add_f32_e32 v14, 1.0, v22
	v_div_scale_f32 v15, s[0:1], v14, v14, v7
	v_rcp_f32_e32 v16, v15
	ds_read_b128 v[8:11], v12 offset:6528
	v_fma_f32 v22, -v15, v16, 1.0
	v_fmac_f32_e32 v16, v22, v16
	v_div_scale_f32 v22, vcc, v7, v14, v7
	v_mul_f32_e32 v23, v22, v16
	v_fma_f32 v25, -v15, v23, v22
	v_fmac_f32_e32 v23, v25, v16
	v_fma_f32 v15, -v15, v23, v22
	v_add_f32_e32 v22, 1.0, v24
	v_div_scale_f32 v24, s[0:1], v22, v22, v18
	v_rcp_f32_e32 v25, v24
	v_div_fmas_f32 v15, v15, v16, v23
	v_div_fixup_f32 v7, v15, v14, v7
	s_waitcnt lgkmcnt(0)
; __device__ __forceinline__ void attn_unit(const bf16* __restrict__ P, unsigned short* __restrict__ Ob, int b, int h, int kvh, int qb, bool meta, int jt0, int ntl, float* part, unsigned* cnt, const float* __restrict__ qnw, const float2* __restrict__ rtab, char* lds) {
;     ...
;     for (int i = 0; i < 8; ++i) { const int cidx = lane + 64 * i, orow = cidx >> 4, c8 = (cidx & 15) * 8;
;       const u32x4 ov = *(const u32x4*)(stg + orow * 272 + c8 * 2);
;       const u32x4 gv = *(const u32x4*)(Pg + (grow0 + orow) * LD + 4096 + h * D + c8);
;       const unsigned ow[4] = {ov.x, ov.y, ov.z, ov.w}, gw[4] = {gv.x, gv.y, gv.z, gv.w}; unsigned res[4];
; #pragma unroll
;       for (int e = 0; e < 4; ++e) { const float o0 = __uint_as_float(ow[e] << 16), o1 = __uint_as_float(ow[e] & 0xffff0000u), g0 = __uint_as_float(gw[e] << 16), g1 = __uint_as_float(gw[e] & 0xffff0000u);
;         res[e] = cvtpk(o0 * (g0 / (1.f + __expf(-g0))), o1 * (g1 / (1.f + __expf(-g1)))); }
;       *(u32x4*)(Ob + (grow0 + orow) * 2048 + h * D + c8) = (u32x4){res[0], res[1], res[2], res[3]}; }
	v_lshlrev_b32_e32 v17, 16, v8
	v_fma_f32 v14, -v24, v25, 1.0
	v_fmac_f32_e32 v25, v14, v25
	v_div_scale_f32 v14, vcc, v18, v22, v18
	v_mul_f32_e32 v15, v14, v25
	v_fma_f32 v16, -v24, v15, v14
	v_fmac_f32_e32 v15, v16, v25
	v_fma_f32 v14, -v24, v15, v14
	v_div_fmas_f32 v14, v14, v25, v15
	v_lshlrev_b32_e32 v15, 16, v19
	v_mul_f32_e32 v16, 0xbfb8aa3b, v15
	v_exp_f32_e32 v16, v16
	v_and_b32_e32 v8, 0xffff0000, v8
	v_div_fixup_f32 v14, v14, v22, v18
	v_mul_f32_e32 v7, v7, v17
	v_mul_f32_e32 v8, v14, v8
	v_cvt_pk_bf16_f32 v8, v7, v8
	v_add_f32_e32 v7, 1.0, v16
	v_div_scale_f32 v14, s[0:1], v7, v7, v15
	v_rcp_f32_e32 v16, v14
	v_and_b32_e32 v18, 0xffff0000, v19
	v_mul_f32_e32 v23, 0xbfb8aa3b, v18
	v_exp_f32_e32 v23, v23
	v_fma_f32 v19, -v14, v16, 1.0
	v_fmac_f32_e32 v16, v19, v16
	v_div_scale_f32 v19, vcc, v15, v7, v15
	v_mul_f32_e32 v22, v19, v16
	v_fma_f32 v24, -v14, v22, v19
	v_fmac_f32_e32 v22, v24, v16
	v_fma_f32 v14, -v14, v22, v19
	v_add_f32_e32 v19, 1.0, v23
	v_div_scale_f32 v23, s[0:1], v19, v19, v18
	v_rcp_f32_e32 v24, v23
	v_div_fmas_f32 v14, v14, v16, v22
	v_div_fixup_f32 v7, v14, v7, v15
	v_lshlrev_b32_e32 v17, 16, v9
	v_fma_f32 v14, -v23, v24, 1.0
	v_fmac_f32_e32 v24, v14, v24
	v_div_scale_f32 v14, vcc, v18, v19, v18
	v_mul_f32_e32 v15, v14, v24
	v_fma_f32 v16, -v23, v15, v14
	v_fmac_f32_e32 v15, v16, v24
	v_fma_f32 v14, -v23, v15, v14
	v_div_fmas_f32 v14, v14, v24, v15
	v_lshlrev_b32_e32 v15, 16, v20
	v_mul_f32_e32 v16, 0xbfb8aa3b, v15
	v_exp_f32_e32 v16, v16
	v_and_b32_e32 v9, 0xffff0000, v9
	v_div_fixup_f32 v14, v14, v19, v18
	v_mul_f32_e32 v7, v7, v17
	v_mul_f32_e32 v9, v14, v9
	v_cvt_pk_bf16_f32 v9, v7, v9
	v_add_f32_e32 v7, 1.0, v16
	v_div_scale_f32 v14, s[0:1], v7, v7, v15
	v_rcp_f32_e32 v16, v14
	v_and_b32_e32 v18, 0xffff0000, v20
	v_mul_f32_e32 v22, 0xbfb8aa3b, v18
	v_exp_f32_e32 v22, v22
	v_fma_f32 v19, -v14, v16, 1.0
	v_fmac_f32_e32 v16, v19, v16
	v_div_scale_f32 v19, vcc, v15, v7, v15
	v_mul_f32_e32 v20, v19, v16
	v_fma_f32 v23, -v14, v20, v19
	v_fmac_f32_e32 v20, v23, v16
	v_fma_f32 v14, -v14, v20, v19
	v_add_f32_e32 v19, 1.0, v22
	v_div_scale_f32 v22, s[0:1], v19, v19, v18
	v_rcp_f32_e32 v23, v22
	v_div_fmas_f32 v14, v14, v16, v20
	v_div_fixup_f32 v7, v14, v7, v15
	v_lshlrev_b32_e32 v17, 16, v10
	v_fma_f32 v14, -v22, v23, 1.0
	v_fmac_f32_e32 v23, v14, v23
	v_div_scale_f32 v14, vcc, v18, v19, v18
	v_mul_f32_e32 v15, v14, v23
	v_fma_f32 v16, -v22, v15, v14
	v_fmac_f32_e32 v15, v16, v23
	v_fma_f32 v14, -v22, v15, v14
	v_div_fmas_f32 v14, v14, v23, v15
	v_lshlrev_b32_e32 v15, 16, v21
	v_mul_f32_e32 v16, 0xbfb8aa3b, v15
	v_exp_f32_e32 v16, v16
	v_and_b32_e32 v10, 0xffff0000, v10
	v_div_fixup_f32 v14, v14, v19, v18
	v_mul_f32_e32 v7, v7, v17
	v_mul_f32_e32 v10, v14, v10
	v_cvt_pk_bf16_f32 v10, v7, v10
	v_add_f32_e32 v7, 1.0, v16
	v_div_scale_f32 v14, s[0:1], v7, v7, v15
	v_rcp_f32_e32 v16, v14
	v_and_b32_e32 v18, 0xffff0000, v21
	v_mul_f32_e32 v21, 0xbfb8aa3b, v18
	v_exp_f32_e32 v21, v21
	v_fma_f32 v19, -v14, v16, 1.0
	v_fmac_f32_e32 v16, v19, v16
	v_div_scale_f32 v19, vcc, v15, v7, v15
	v_mul_f32_e32 v20, v19, v16
	v_fma_f32 v22, -v14, v20, v19
	v_fmac_f32_e32 v20, v22, v16
	v_fma_f32 v14, -v14, v20, v19
	v_add_f32_e32 v19, 1.0, v21
	v_div_scale_f32 v21, s[0:1], v19, v19, v18
	v_rcp_f32_e32 v22, v21
	v_div_fmas_f32 v14, v14, v16, v20
	v_div_fixup_f32 v7, v14, v7, v15
	v_lshlrev_b32_e32 v17, 16, v11
	v_fma_f32 v14, -v21, v22, 1.0
	v_fmac_f32_e32 v22, v14, v22
	v_div_scale_f32 v14, vcc, v18, v19, v18
	v_mul_f32_e32 v15, v14, v22
	v_fma_f32 v16, -v21, v15, v14
	v_fmac_f32_e32 v15, v16, v22
	v_fma_f32 v14, -v21, v15, v14
	v_div_fmas_f32 v14, v14, v22, v15
	v_and_b32_e32 v11, 0xffff0000, v11
	v_div_fixup_f32 v14, v14, v19, v18
	v_add_co_u32_e32 v2, vcc, s52, v2
	v_mul_f32_e32 v11, v14, v11
	s_nop 0
	v_addc_co_u32_e32 v3, vcc, 0, v3, vcc
	v_mul_f32_e32 v7, v7, v17
	v_cvt_pk_bf16_f32 v11, v7, v11
	s_nop 1
	v_mov_b64_e32 v[14:15], v[124:125]
	v_mov_b64_e32 v[16:17], v[126:127]
	v_mov_b32_e32 v7, v1
	v_lshlrev_b64 v[2:3], 12, v[6:7]
	v_lshl_add_u64 v[2:3], v[4:5], 0, v[2:3]
	global_store_dwordx4 v[2:3], v[8:11], off
	v_lshlrev_b64 v[0:1], 12, v[0:1]
	v_lshl_add_u64 v[0:1], v[4:5], 0, v[0:1]
	s_nop 0
	v_lshlrev_b32_e32 v13, 16, v14
	v_mul_f32_e32 v6, 0xbfb8aa3b, v13
	v_exp_f32_e32 v18, v6
	ds_read_b128 v[6:9], v12 offset:7616
	v_and_b32_e32 v12, 0xffff0000, v14
	v_mul_f32_e32 v19, 0xbfb8aa3b, v12
	v_add_f32_e32 v2, 1.0, v18
	v_div_scale_f32 v3, s[0:1], v2, v2, v13
	v_rcp_f32_e32 v10, v3
	v_exp_f32_e32 v19, v19
	s_waitcnt lgkmcnt(0)
; __device__ __forceinline__ void attn_unit(const bf16* __restrict__ P, unsigned short* __restrict__ Ob, int b, int h, int kvh, int qb, bool meta, int jt0, int ntl, float* part, unsigned* cnt, const float* __restrict__ qnw, const float2* __restrict__ rtab, char* lds) {
;     ...
;     for (int i = 0; i < 8; ++i) { const int cidx = lane + 64 * i, orow = cidx >> 4, c8 = (cidx & 15) * 8;
;       const u32x4 ov = *(const u32x4*)(stg + orow * 272 + c8 * 2);
;       const u32x4 gv = *(const u32x4*)(Pg + (grow0 + orow) * LD + 4096 + h * D + c8);
;       const unsigned ow[4] = {ov.x, ov.y, ov.z, ov.w}, gw[4] = {gv.x, gv.y, gv.z, gv.w}; unsigned res[4];
; #pragma unroll
;       for (int e = 0; e < 4; ++e) { const float o0 = __uint_as_float(ow[e] << 16), o1 = __uint_as_float(ow[e] & 0xffff0000u), g0 = __uint_as_float(gw[e] << 16), g1 = __uint_as_float(gw[e] & 0xffff0000u);
;         res[e] = cvtpk(o0 * (g0 / (1.f + __expf(-g0))), o1 * (g1 / (1.f + __expf(-g1)))); }
;       *(u32x4*)(Ob + (grow0 + orow) * 2048 + h * D + c8) = (u32x4){res[0], res[1], res[2], res[3]}; }
;     ...
;   __syncthreads();
	v_lshlrev_b32_e32 v11, 16, v6
	v_and_b32_e32 v6, 0xffff0000, v6
	v_fma_f32 v14, -v3, v10, 1.0
	v_fmac_f32_e32 v10, v14, v10
	v_div_scale_f32 v14, vcc, v13, v2, v13
	v_mul_f32_e32 v18, v14, v10
	v_fma_f32 v20, -v3, v18, v14
	v_fmac_f32_e32 v18, v20, v10
	v_fma_f32 v3, -v3, v18, v14
	v_add_f32_e32 v14, 1.0, v19
	v_div_scale_f32 v19, s[0:1], v14, v14, v12
	v_rcp_f32_e32 v20, v19
	v_div_fmas_f32 v3, v3, v10, v18
	v_div_fixup_f32 v2, v3, v2, v13
	v_mul_f32_e32 v2, v2, v11
	v_fma_f32 v3, -v19, v20, 1.0
	v_fmac_f32_e32 v20, v3, v20
	v_div_scale_f32 v3, vcc, v12, v14, v12
	v_mul_f32_e32 v10, v3, v20
	v_fma_f32 v11, -v19, v10, v3
	v_fmac_f32_e32 v10, v11, v20
	v_fma_f32 v3, -v19, v10, v3
	v_div_fmas_f32 v3, v3, v20, v10
	v_lshlrev_b32_e32 v10, 16, v15
	v_mul_f32_e32 v11, 0xbfb8aa3b, v10
	v_exp_f32_e32 v11, v11
	v_div_fixup_f32 v3, v3, v14, v12
	v_mul_f32_e32 v3, v3, v6
	v_cvt_pk_bf16_f32 v6, v2, v3
	v_add_f32_e32 v2, 1.0, v11
	v_div_scale_f32 v3, s[0:1], v2, v2, v10
	v_rcp_f32_e32 v11, v3
	v_and_b32_e32 v13, 0xffff0000, v15
	v_mul_f32_e32 v18, 0xbfb8aa3b, v13
	v_exp_f32_e32 v18, v18
	v_fma_f32 v14, -v3, v11, 1.0
	v_fmac_f32_e32 v11, v14, v11
	v_div_scale_f32 v14, vcc, v10, v2, v10
	v_mul_f32_e32 v15, v14, v11
	v_fma_f32 v19, -v3, v15, v14
	v_fmac_f32_e32 v15, v19, v11
	v_fma_f32 v3, -v3, v15, v14
	v_add_f32_e32 v14, 1.0, v18
	v_div_scale_f32 v18, s[0:1], v14, v14, v13
	v_rcp_f32_e32 v19, v18
	v_div_fmas_f32 v3, v3, v11, v15
	v_div_fixup_f32 v2, v3, v2, v10
	v_lshlrev_b32_e32 v12, 16, v7
	v_fma_f32 v3, -v18, v19, 1.0
	v_fmac_f32_e32 v19, v3, v19
	v_div_scale_f32 v3, vcc, v13, v14, v13
	v_mul_f32_e32 v10, v3, v19
	v_fma_f32 v11, -v18, v10, v3
	v_fmac_f32_e32 v10, v11, v19
	v_fma_f32 v3, -v18, v10, v3
	v_div_fmas_f32 v3, v3, v19, v10
	v_lshlrev_b32_e32 v10, 16, v16
	v_mul_f32_e32 v11, 0xbfb8aa3b, v10
	v_exp_f32_e32 v11, v11
	v_and_b32_e32 v7, 0xffff0000, v7
	v_mul_f32_e32 v2, v2, v12
	v_div_fixup_f32 v3, v3, v14, v13
	v_mul_f32_e32 v3, v3, v7
	v_cvt_pk_bf16_f32 v7, v2, v3
	v_add_f32_e32 v2, 1.0, v11
	v_div_scale_f32 v3, s[0:1], v2, v2, v10
	v_rcp_f32_e32 v11, v3
	v_and_b32_e32 v13, 0xffff0000, v16
	v_mul_f32_e32 v16, 0xbfb8aa3b, v13
	v_exp_f32_e32 v16, v16
	v_fma_f32 v14, -v3, v11, 1.0
	v_fmac_f32_e32 v11, v14, v11
	v_div_scale_f32 v14, vcc, v10, v2, v10
	v_mul_f32_e32 v15, v14, v11
	v_fma_f32 v18, -v3, v15, v14
	v_fmac_f32_e32 v15, v18, v11
	v_fma_f32 v3, -v3, v15, v14
	v_add_f32_e32 v14, 1.0, v16
	v_div_scale_f32 v16, s[0:1], v14, v14, v13
	v_rcp_f32_e32 v18, v16
	v_div_fmas_f32 v3, v3, v11, v15
	v_div_fixup_f32 v2, v3, v2, v10
	v_lshlrev_b32_e32 v12, 16, v8
	v_fma_f32 v3, -v16, v18, 1.0
	v_fmac_f32_e32 v18, v3, v18
	v_div_scale_f32 v3, vcc, v13, v14, v13
	v_mul_f32_e32 v10, v3, v18
	v_fma_f32 v11, -v16, v10, v3
	v_fmac_f32_e32 v10, v11, v18
	v_fma_f32 v3, -v16, v10, v3
	v_div_fmas_f32 v3, v3, v18, v10
	v_lshlrev_b32_e32 v10, 16, v17
	v_mul_f32_e32 v11, 0xbfb8aa3b, v10
	v_exp_f32_e32 v11, v11
	v_and_b32_e32 v8, 0xffff0000, v8
	v_mul_f32_e32 v2, v2, v12
	v_div_fixup_f32 v3, v3, v14, v13
	v_mul_f32_e32 v3, v3, v8
	v_cvt_pk_bf16_f32 v8, v2, v3
	v_add_f32_e32 v2, 1.0, v11
	v_div_scale_f32 v3, s[0:1], v2, v2, v10
	v_rcp_f32_e32 v11, v3
	v_and_b32_e32 v13, 0xffff0000, v17
	v_mul_f32_e32 v16, 0xbfb8aa3b, v13
	v_exp_f32_e32 v16, v16
	v_fma_f32 v14, -v3, v11, 1.0
	v_fmac_f32_e32 v11, v14, v11
	v_div_scale_f32 v14, vcc, v10, v2, v10
	v_mul_f32_e32 v15, v14, v11
	v_fma_f32 v17, -v3, v15, v14
	v_fmac_f32_e32 v15, v17, v11
	v_fma_f32 v3, -v3, v15, v14
	v_add_f32_e32 v14, 1.0, v16
	v_div_scale_f32 v16, s[0:1], v14, v14, v13
	v_rcp_f32_e32 v17, v16
	v_div_fmas_f32 v3, v3, v11, v15
	v_div_fixup_f32 v2, v3, v2, v10
	v_lshlrev_b32_e32 v12, 16, v9
	v_fma_f32 v3, -v16, v17, 1.0
	v_fmac_f32_e32 v17, v3, v17
	v_div_scale_f32 v3, vcc, v13, v14, v13
	v_mul_f32_e32 v10, v3, v17
	v_fma_f32 v11, -v16, v10, v3
	v_fmac_f32_e32 v10, v11, v17
	v_fma_f32 v3, -v16, v10, v3
	v_div_fmas_f32 v3, v3, v17, v10
	v_and_b32_e32 v9, 0xffff0000, v9
	v_div_fixup_f32 v3, v3, v14, v13
	v_mul_f32_e32 v2, v2, v12
	v_mul_f32_e32 v3, v3, v9
	v_cvt_pk_bf16_f32 v9, v2, v3
	global_store_dwordx4 v[0:1], v[6:9], off
	s_barrier
